# epilogue quad_sum shuffles: ds_bpermute LDS round trips replaced by v_mov + v_permlane16/32_swap (101 of 160 sites)
# baseline (speedup 1.0000x reference)
.LBB0_234:
	s_cmp_gt_i32 s14, 3
	s_cselect_b64 s[30:31], -1, 0
	s_and_b64 s[46:47], s[30:31], exec
	s_cselect_b32 s46, s44, s40
	s_cselect_b32 s47, s45, s41
	s_lshl_b32 s9, s6, 8
	v_add_u32_e32 v152, s9, v166
	v_or_b32_e32 v144, 16, v152
	v_ashrrev_i32_e32 v153, 31, v152
	v_ashrrev_i32_e32 v145, 31, v144
	v_lshlrev_b64 v[142:143], 6, v[152:153]
	v_lshlrev_b64 v[144:145], 6, v[144:145]
	v_or_b32_e32 v150, 32, v152
	v_lshl_add_u64 v[142:143], v[134:135], 0, v[142:143]
	v_lshl_add_u64 v[146:147], v[134:135], 0, v[144:145]
	v_ashrrev_i32_e32 v151, 31, v150
	global_load_dwordx4 v[142:145], v[142:143], off
	s_nop 0
	global_load_dwordx4 v[146:149], v[146:147], off
	v_lshlrev_b64 v[150:151], 6, v[150:151]
	v_lshl_add_u64 v[150:151], v[134:135], 0, v[150:151]
	global_load_dwordx4 v[154:157], v[150:151], off
	v_or_b32_e32 v150, 48, v152
	v_ashrrev_i32_e32 v151, 31, v150
	v_lshlrev_b64 v[150:151], 6, v[150:151]
	v_lshl_add_u64 v[150:151], v[134:135], 0, v[150:151]
	global_load_dwordx4 v[158:161], v[150:151], off
	s_lshl_b32 s6, s14, 8
	s_and_b32 s6, s6, 0x300
	s_cmp_lt_i32 s14, 4
	s_waitcnt vmcnt(0)
	v_mov_b32_e32 v150, v143
	v_mov_b32_e32 v151, v144
	v_mov_b32_e32 v143, v145
	v_pk_add_f32 v[142:143], v[150:151], v[142:143]
	v_add_f32_e32 v132, v146, v147
	v_add_f32_e32 v144, v148, v149
	v_add_f32_e32 v142, v142, v143
	v_add_f32_e32 v145, v154, v155
	v_add_f32_e32 v146, v156, v157
	v_add_f32_e32 v132, v132, v144
	v_mov_b32_e32 v144, v142
	v_add_f32_e32 v143, v145, v146
	v_mov_b32_e32 v145, v132
	v_add_f32_e32 v147, v158, v159
	v_add_f32_e32 v148, v160, v161
	v_add_f32_e32 v146, v147, v148
	s_waitcnt lgkmcnt(1)
	s_nop 1
	v_permlane16_swap_b32_e32 v144, v142
	v_add_f32_e32 v142, v142, v144
	v_mov_b32_e32 v147, v143
	v_mov_b32_e32 v148, v146
	s_waitcnt lgkmcnt(2)
	s_nop 1
	v_permlane16_swap_b32_e32 v145, v132
	v_add_f32_e32 v188, v132, v145
	v_mov_b32_e32 v132, v142
	ds_bpermute_b32 v189, v165, v188
	s_waitcnt lgkmcnt(3)
	s_nop 1
	v_permlane16_swap_b32_e32 v147, v143
	v_add_f32_e32 v186, v143, v147
	s_waitcnt lgkmcnt(2)
	s_nop 1
	v_permlane16_swap_b32_e32 v148, v146
	v_add_f32_e32 v184, v146, v148
	ds_bpermute_b32 v187, v165, v186
	s_waitcnt lgkmcnt(2)
	s_nop 1
	v_permlane32_swap_b32_e32 v132, v142
	v_add_f32_e32 v132, v142, v132
	v_fmamk_f32 v132, v132, 0x3a800000, v175
	ds_bpermute_b32 v185, v165, v184
	v_rsq_f32_e32 v154, v132
	v_or_b32_e32 v132, s6, v171
	v_add_u32_e32 v150, 0x80, v152
	v_add_u32_e32 v148, 0x90, v152
	v_ashrrev_i32_e32 v151, 31, v150
	v_ashrrev_i32_e32 v149, 31, v148
	v_lshlrev_b64 v[142:143], 6, v[150:151]
	v_lshlrev_b64 v[144:145], 6, v[148:149]
	v_lshl_add_u64 v[142:143], v[134:135], 0, v[142:143]
	v_lshl_add_u64 v[144:145], v[134:135], 0, v[144:145]
	global_load_dwordx4 v[156:159], v[142:143], off
	global_load_dwordx4 v[160:163], v[144:145], off
	v_add_u32_e32 v144, 0xa0, v152
	v_ashrrev_i32_e32 v145, 31, v144
	v_lshlrev_b64 v[142:143], 6, v[144:145]
	v_lshl_add_u64 v[142:143], v[134:135], 0, v[142:143]
	global_load_dwordx4 v[176:179], v[142:143], off
	v_add_u32_e32 v142, 0xb0, v152
	v_ashrrev_i32_e32 v143, 31, v142
	v_lshlrev_b64 v[146:147], 6, v[142:143]
	v_lshl_add_u64 v[146:147], v[134:135], 0, v[146:147]
	global_load_dwordx4 v[180:183], v[146:147], off
	s_waitcnt vmcnt(3)
	v_add_f32_e32 v146, v156, v157
	v_add_f32_e32 v147, v158, v159
	s_waitcnt vmcnt(2)
	v_add_f32_e32 v155, v160, v161
	v_add_f32_e32 v156, v162, v163
	v_add_f32_e32 v146, v146, v147
	v_add_f32_e32 v147, v155, v156
	s_waitcnt vmcnt(1)
	v_add_f32_e32 v157, v176, v177
	v_add_f32_e32 v158, v178, v179
	v_add_f32_e32 v155, v157, v158
	v_mov_b32_e32 v157, v146
	v_mov_b32_e32 v158, v147
	s_waitcnt vmcnt(0)
	v_add_f32_e32 v159, v180, v181
	v_add_f32_e32 v160, v182, v183
	v_add_f32_e32 v156, v159, v160
	ds_bpermute_b32 v159, v164, v155
	v_mov_b32_e32 v160, v156
	s_waitcnt lgkmcnt(3)
	s_nop 1
	v_permlane16_swap_b32_e32 v157, v146
	v_add_f32_e32 v182, v146, v157
	s_waitcnt lgkmcnt(2)
	s_nop 1
	v_permlane16_swap_b32_e32 v158, v147
	v_add_f32_e32 v180, v147, v158
	ds_bpermute_b32 v183, v165, v182
	s_waitcnt lgkmcnt(2)
	v_add_f32_e32 v178, v155, v159
	s_waitcnt lgkmcnt(1)
	s_nop 1
	v_permlane16_swap_b32_e32 v160, v156
	v_add_f32_e32 v176, v156, v160
	ds_bpermute_b32 v181, v165, v180
	ds_bpermute_b32 v179, v165, v178
	ds_bpermute_b32 v177, v165, v176
	v_lshlrev_b32_e32 v132, 1, v132
	v_pk_mul_f32 v[124:125], v[124:125], v[154:155] op_sel_hi:[1,0]
	v_lshl_add_u64 v[146:147], s[46:47], 0, v[132:133]
	v_mul_f32_e32 v132, 0x3d372713, v124
	v_mul_f32_e32 v155, 0x3d372713, v125
	v_mul_f32_e32 v132, v124, v132
	v_mul_f32_e32 v155, v125, v155
	v_fma_f32 v132, v124, v132, v124
	v_fma_f32 v155, v125, v155, v125
	v_mul_f32_e32 v132, 0x3f4c422a, v132
	v_mul_f32_e32 v155, 0x3f4c422a, v155
	v_mul_f32_e32 v132, 0xc038aa3b, v132
	v_mul_f32_e32 v155, 0xc038aa3b, v155
	v_exp_f32_e32 v132, v132
	v_exp_f32_e32 v155, v155
	v_lshlrev_b64 v[156:157], 11, v[152:153]
	v_lshl_add_u64 v[190:191], v[146:147], 0, v[156:157]
	v_add_f32_e32 v132, 1.0, v132
	v_pk_mul_f32 v[126:127], v[126:127], v[154:155] op_sel_hi:[1,0]
	v_rcp_f32_e32 v156, v132
	v_add_f32_e32 v132, 1.0, v155
	v_mul_f32_e32 v155, 0x3d372713, v126
	v_mul_f32_e32 v155, v126, v155
	v_fma_f32 v155, v126, v155, v126
	v_mul_f32_e32 v155, 0x3f4c422a, v155
	v_mul_f32_e32 v155, 0xc038aa3b, v155
	v_exp_f32_e32 v155, v155
	v_mul_f32_e32 v157, 0x3d372713, v127
	v_mul_f32_e32 v157, v127, v157
	v_fma_f32 v157, v127, v157, v127
	v_pk_mul_f32 v[192:193], v[120:121], v[154:155] op_sel_hi:[1,0]
	v_mul_f32_e32 v157, 0x3f4c422a, v157
	v_mul_f32_e32 v120, 0x3d372713, v192
	v_mul_f32_e32 v120, v192, v120
	v_mul_f32_e32 v121, 0x3d372713, v193
	v_fma_f32 v120, v192, v120, v192
	v_mul_f32_e32 v121, v193, v121
	v_mul_f32_e32 v120, 0x3f4c422a, v120
	v_fma_f32 v121, v193, v121, v193
	v_mul_f32_e32 v120, 0xc038aa3b, v120
	v_mul_f32_e32 v121, 0x3f4c422a, v121
	v_mul_f32_e32 v157, 0xc038aa3b, v157
	v_exp_f32_e32 v120, v120
	v_mul_f32_e32 v121, 0xc038aa3b, v121
	v_exp_f32_e32 v157, v157
	v_exp_f32_e32 v121, v121
	v_rcp_f32_e32 v158, v132
	v_add_f32_e32 v132, 1.0, v155
	v_add_f32_e32 v120, 1.0, v120
	v_rcp_f32_e32 v160, v132
	v_add_f32_e32 v132, 1.0, v157
	v_rcp_f32_e32 v157, v120
	v_add_f32_e32 v120, 1.0, v121
	v_rcp_f32_e32 v161, v120
	v_pk_mul_f32 v[194:195], v[122:123], v[154:155] op_sel_hi:[1,0]
	v_mov_b32_e32 v121, v192
	v_pk_mov_b32 v[122:123], v[124:125], v[192:193] op_sel:[1,0]
	v_mov_b32_e32 v159, v157
	v_mov_b32_e32 v192, v126
	v_mov_b32_e32 v120, v124
	v_pk_mul_f32 v[124:125], v[122:123], v[158:159]
	v_pk_mul_f32 v[122:123], v[192:193], v[160:161]
	v_mov_b32_e32 v192, v127
	v_mul_f32_e32 v126, 0x3d372713, v194
	v_mul_f32_e32 v127, 0x3d372713, v195
	v_mul_f32_e32 v126, v194, v126
	v_mul_f32_e32 v127, v195, v127
	v_fma_f32 v126, v194, v126, v194
	v_fma_f32 v127, v195, v127, v195
	v_mul_f32_e32 v126, 0x3f4c422a, v126
	v_mul_f32_e32 v127, 0x3f4c422a, v127
	v_pk_mul_f32 v[116:117], v[116:117], v[154:155] op_sel_hi:[1,0]
	v_mul_f32_e32 v126, 0xc038aa3b, v126
	v_mul_f32_e32 v127, 0xc038aa3b, v127
	v_mul_f32_e32 v155, 0x3d372713, v117
	v_exp_f32_e32 v126, v126
	v_exp_f32_e32 v127, v127
	v_mul_f32_e32 v155, v117, v155
	v_fma_f32 v155, v117, v155, v117
	v_mul_f32_e32 v155, 0x3f4c422a, v155
	v_mul_f32_e32 v155, 0xc038aa3b, v155
	v_rcp_f32_e32 v162, v132
	v_add_f32_e32 v126, 1.0, v126
	v_add_f32_e32 v127, 1.0, v127
	v_exp_f32_e32 v155, v155
	v_rcp_f32_e32 v126, v126
	v_rcp_f32_e32 v127, v127
	v_pk_mul_f32 v[120:121], v[120:121], v[156:157]
	v_mov_b32_e32 v163, v161
	v_cvt_pk_bf16_f32 v232, v120, v124
	v_pk_mul_f32 v[156:157], v[192:193], v[162:163]
	v_pk_mul_f32 v[118:119], v[118:119], v[154:155] op_sel_hi:[1,0]
	v_cvt_pk_bf16_f32 v233, v122, v156
	v_cvt_pk_bf16_f32 v234, v121, v123
	v_pk_mul_f32 v[126:127], v[194:195], v[126:127]
	v_mul_f32_e32 v132, 0x3d372713, v116
	v_cvt_pk_bf16_f32 v235, v126, v127
	s_nop 1
	v_permlane16_swap_b32_e32 v232, v234
	v_permlane16_swap_b32_e32 v233, v235
	v_lshl_add_u64 v[236:237], v[190:191], 0, v[238:239]
	global_store_dwordx4 v[236:237], v[232:235], off
	s_nop 1
	v_mul_f32_e32 v158, 0x3d372713, v118
	v_mul_f32_e32 v158, v118, v158
	v_mul_f32_e32 v159, 0x3d372713, v119
	v_mul_f32_e32 v132, v116, v132
	v_fma_f32 v158, v118, v158, v118
	v_mul_f32_e32 v159, v119, v159
	v_fma_f32 v132, v116, v132, v116
	v_mul_f32_e32 v158, 0x3f4c422a, v158
	v_fma_f32 v159, v119, v159, v119
	v_mul_f32_e32 v132, 0x3f4c422a, v132
	v_mul_f32_e32 v158, 0xc038aa3b, v158
	v_mul_f32_e32 v159, 0x3f4c422a, v159
	v_mul_f32_e32 v132, 0xc038aa3b, v132
	v_exp_f32_e32 v158, v158
	v_mul_f32_e32 v159, 0xc038aa3b, v159
	v_exp_f32_e32 v132, v132
	v_exp_f32_e32 v159, v159
	v_add_f32_e32 v155, 1.0, v155
	v_add_f32_e32 v158, 1.0, v158
	v_add_f32_e32 v132, 1.0, v132
	v_rcp_f32_e32 v155, v155
	v_rcp_f32_e32 v161, v158
	v_add_f32_e32 v158, 1.0, v159
	v_rcp_f32_e32 v132, v132
	v_rcp_f32_e32 v159, v158
	v_pk_mul_f32 v[112:113], v[112:113], v[154:155] op_sel_hi:[1,0]
	v_pk_mul_f32 v[114:115], v[114:115], v[154:155] op_sel_hi:[1,0]
	v_mul_f32_e32 v158, v116, v132
	v_mul_f32_e32 v160, v117, v155
	v_mul_f32_e32 v116, v118, v161
	v_mul_f32_e32 v118, v119, v159
	v_mul_f32_e32 v117, 0x3d372713, v112
	v_mul_f32_e32 v119, 0x3d372713, v113
	v_mul_f32_e32 v132, 0x3d372713, v114
	v_mul_f32_e32 v154, 0x3d372713, v115
	v_mul_f32_e32 v117, v112, v117
	v_mul_f32_e32 v119, v113, v119
	v_mul_f32_e32 v132, v114, v132
	v_mul_f32_e32 v154, v115, v154
	v_fma_f32 v117, v112, v117, v112
	v_fma_f32 v119, v113, v119, v113
	v_fma_f32 v132, v114, v132, v114
	v_fma_f32 v154, v115, v154, v115
	v_mul_f32_e32 v117, 0x3f4c422a, v117
	v_mul_f32_e32 v119, 0x3f4c422a, v119
	v_mul_f32_e32 v132, 0x3f4c422a, v132
	v_mul_f32_e32 v154, 0x3f4c422a, v154
	v_mul_f32_e32 v117, 0xc038aa3b, v117
	v_mul_f32_e32 v119, 0xc038aa3b, v119
	v_mul_f32_e32 v132, 0xc038aa3b, v132
	v_mul_f32_e32 v154, 0xc038aa3b, v154
	v_exp_f32_e32 v117, v117
	v_exp_f32_e32 v119, v119
	v_exp_f32_e32 v132, v132
	v_exp_f32_e32 v154, v154
	v_add_f32_e32 v117, 1.0, v117
	v_add_f32_e32 v119, 1.0, v119
	v_add_f32_e32 v132, 1.0, v132
	v_add_f32_e32 v154, 1.0, v154
	v_rcp_f32_e32 v117, v117
	v_rcp_f32_e32 v119, v119
	v_rcp_f32_e32 v132, v132
	v_rcp_f32_e32 v155, v154
	v_cvt_pk_bf16_f32 v232, v158, v160
	v_cvt_pk_bf16_f32 v233, v116, v118
	v_mul_f32_e32 v154, v112, v117
	v_mul_f32_e32 v162, v113, v119
	v_mul_f32_e32 v112, v114, v132
	v_mul_f32_e32 v114, v115, v155
	v_cvt_pk_bf16_f32 v234, v154, v162
	v_cvt_pk_bf16_f32 v235, v112, v114
	s_nop 1
	v_permlane16_swap_b32_e32 v232, v234
	v_permlane16_swap_b32_e32 v233, v235
	v_lshl_add_u64 v[236:237], v[190:191], 0, v[238:239]
	global_store_dwordx4 v[236:237], v[232:235], off offset:256
	s_nop 1
	s_cbranch_scc1 .LBB0_238
	v_pk_mul_f32 v[190:191], v[120:121], v[120:121]
	v_pk_mul_f32 v[192:193], v[124:125], v[124:125]
	v_pk_add_f32 v[198:199], v[120:121], v[124:125]
	v_pk_mul_f32 v[124:125], v[120:121], v[124:125]
	v_pk_mul_f32 v[194:195], v[122:123], v[122:123]
	v_pk_mul_f32 v[196:197], v[156:157], v[156:157]
	v_mov_b32_e32 v199, v125
	v_pk_add_f32 v[124:125], v[122:123], v[156:157]
	v_pk_mul_f32 v[156:157], v[122:123], v[156:157]
	v_mul_f32_e32 v132, v126, v126
	v_pk_mov_b32 v[120:121], v[120:121], v[190:191] op_sel:[1,0]
	v_pk_mov_b32 v[122:123], v[122:123], v[192:193] op_sel:[1,0]
	v_mov_b32_e32 v125, v157
	v_pk_fma_f32 v[156:157], v[126:127], v[126:127], v[132:133] op_sel_hi:[1,1,0]
	v_pk_add_f32 v[120:121], v[120:121], v[122:123]
	v_mov_b32_e32 v122, v126
	v_mov_b32_e32 v123, v194
	v_pk_mov_b32 v[126:127], v[126:127], v[196:197] op_sel:[1,0]
	v_mul_f32_e32 v159, v158, v158
	v_mul_f32_e32 v161, v160, v160
	v_mul_f32_e32 v117, v116, v116
	v_mul_f32_e32 v119, v118, v118
	v_pk_add_f32 v[124:125], v[198:199], v[124:125]
	v_mov_b32_e32 v156, v133
	v_pk_add_f32 v[122:123], v[122:123], v[126:127]
	v_mul_f32_e32 v155, v154, v154
	v_mul_f32_e32 v163, v162, v162
	v_mul_f32_e32 v113, v112, v112
	v_mul_f32_e32 v115, v114, v114
	v_pk_add_f32 v[124:125], v[124:125], v[156:157]
	v_pk_add_f32 v[120:121], v[120:121], v[122:123]
	v_pk_add_f32 v[122:123], v[158:159], v[160:161]
	v_pk_add_f32 v[116:117], v[116:117], v[118:119]
	v_pk_add_f32 v[120:121], v[120:121], v[124:125]
	v_pk_add_f32 v[116:117], v[122:123], v[116:117]
	v_pk_add_f32 v[118:119], v[154:155], v[162:163]
	v_pk_add_f32 v[112:113], v[112:113], v[114:115]
	v_pk_add_f32 v[116:117], v[116:117], v[120:121]
	v_pk_add_f32 v[112:113], v[118:119], v[112:113]
	s_nop 0
	v_pk_add_f32 v[112:113], v[112:113], v[116:117]
	v_mov_b32_e32 v114, v112
	v_mov_b32_e32 v115, v113
	s_waitcnt lgkmcnt(0)
	s_nop 1
	v_permlane16_swap_b32_e32 v114, v112
	v_permlane16_swap_b32_e32 v115, v113
	v_pk_add_f32 v[112:113], v[112:113], v[114:115]
	ds_bpermute_b32 v114, v165, v112
	ds_bpermute_b32 v115, v165, v113
	s_and_saveexec_b64 s[6:7], s[2:3]
	s_cbranch_execz .LBB0_237
	s_lshl_b32 s25, s14, 2
	s_add_i32 s25, s25, -16
	v_mov_b32_e32 v132, s25
	v_lshl_add_u64 v[116:117], v[152:153], 4, v[132:133]
	v_or_b32_e32 v116, s59, v116
	v_lshl_add_u64 v[116:117], v[116:117], 3, s[18:19]
	s_waitcnt lgkmcnt(0)
	v_pk_add_f32 v[112:113], v[112:113], v[114:115]
	global_store_dwordx2 v[116:117], v[112:113], off

.LBB0_238:
	v_add_f32_e32 v112, v188, v189
	v_fmamk_f32 v112, v112, 0x3a800000, v175
	v_rsq_f32_e32 v120, v112
	v_add_u32_e32 v112, s9, v168
	v_ashrrev_i32_e32 v113, 31, v112
	s_waitcnt lgkmcnt(0)
	v_lshlrev_b64 v[114:115], 11, v[112:113]
	v_pk_mul_f32 v[110:111], v[110:111], v[120:121] op_sel_hi:[1,0]
	v_pk_mul_f32 v[108:109], v[108:109], v[120:121] op_sel_hi:[1,0]
	v_mul_f32_e32 v116, 0x3d372713, v110
	v_mul_f32_e32 v116, v110, v116
	v_fma_f32 v116, v110, v116, v110
	v_lshl_add_u64 v[124:125], v[146:147], 0, v[114:115]
	v_mul_f32_e32 v115, 0x3d372713, v109
	v_mul_f32_e32 v116, 0x3f4c422a, v116
	v_mul_f32_e32 v115, v109, v115
	v_mul_f32_e32 v116, 0xc038aa3b, v116
	v_pk_mul_f32 v[126:127], v[104:105], v[120:121] op_sel_hi:[1,0]
	v_fma_f32 v115, v109, v115, v109
	v_exp_f32_e32 v117, v116
	v_mul_f32_e32 v116, 0x3d372713, v111
	v_mul_f32_e32 v104, 0x3d372713, v126
	v_mul_f32_e32 v115, 0x3f4c422a, v115
	v_mul_f32_e32 v116, v111, v116
	v_mul_f32_e32 v104, v126, v104
	v_mul_f32_e32 v105, 0x3d372713, v127
	v_mul_f32_e32 v115, 0xc038aa3b, v115
	v_fma_f32 v116, v111, v116, v111
	v_fma_f32 v104, v126, v104, v126
	v_mul_f32_e32 v105, v127, v105
	v_exp_f32_e32 v115, v115
	v_mul_f32_e32 v116, 0x3f4c422a, v116
	v_mul_f32_e32 v104, 0x3f4c422a, v104
	v_fma_f32 v105, v127, v105, v127
	v_mul_f32_e32 v116, 0xc038aa3b, v116
	v_mul_f32_e32 v104, 0xc038aa3b, v104
	v_mul_f32_e32 v105, 0x3f4c422a, v105
	v_exp_f32_e32 v119, v116
	v_exp_f32_e32 v104, v104
	v_mul_f32_e32 v105, 0xc038aa3b, v105
	v_exp_f32_e32 v105, v105
	v_add_f32_e32 v115, 1.0, v115
	v_rcp_f32_e32 v116, v115
	v_add_f32_e32 v115, 1.0, v117
	v_rcp_f32_e32 v118, v115
	v_add_f32_e32 v115, 1.0, v119
	v_add_f32_e32 v104, 1.0, v104
	v_rcp_f32_e32 v122, v115
	v_rcp_f32_e32 v115, v104
	v_add_f32_e32 v104, 1.0, v105
	v_rcp_f32_e32 v119, v104
	v_mul_f32_e32 v114, 0x3d372713, v108
	v_mul_f32_e32 v114, v108, v114
	v_pk_mul_f32 v[152:153], v[106:107], v[120:121] op_sel_hi:[1,0]
	v_mov_b32_e32 v105, v126
	v_pk_mov_b32 v[106:107], v[108:109], v[126:127] op_sel:[1,0]
	v_mov_b32_e32 v117, v115
	v_mov_b32_e32 v126, v110
	v_fma_f32 v114, v108, v114, v108
	v_mov_b32_e32 v104, v108
	v_pk_mul_f32 v[108:109], v[106:107], v[116:117]
	v_pk_mul_f32 v[106:107], v[126:127], v[118:119]
	v_mov_b32_e32 v126, v111
	v_mul_f32_e32 v110, 0x3d372713, v152
	v_mul_f32_e32 v111, 0x3d372713, v153
	v_mul_f32_e32 v114, 0x3f4c422a, v114
	v_mul_f32_e32 v110, v152, v110
	v_mul_f32_e32 v111, v153, v111
	v_mul_f32_e32 v114, 0xc038aa3b, v114
	v_fma_f32 v110, v152, v110, v152
	v_fma_f32 v111, v153, v111, v153
	v_exp_f32_e32 v114, v114
	v_mul_f32_e32 v110, 0x3f4c422a, v110
	v_mul_f32_e32 v111, 0x3f4c422a, v111
	v_mul_f32_e32 v110, 0xc038aa3b, v110
	v_mul_f32_e32 v111, 0xc038aa3b, v111
	v_exp_f32_e32 v110, v110
	v_exp_f32_e32 v111, v111
	v_add_f32_e32 v114, 1.0, v114
	v_rcp_f32_e32 v114, v114
	v_add_f32_e32 v110, 1.0, v110
	v_add_f32_e32 v111, 1.0, v111
	v_rcp_f32_e32 v110, v110
	v_rcp_f32_e32 v111, v111
	v_pk_mul_f32 v[104:105], v[104:105], v[114:115]
	v_mov_b32_e32 v123, v119
	v_cvt_pk_bf16_f32 v232, v104, v108
	v_pk_mul_f32 v[102:103], v[102:103], v[120:121] op_sel_hi:[1,0]
	v_pk_mul_f32 v[114:115], v[126:127], v[122:123]
	v_pk_mul_f32 v[100:101], v[100:101], v[120:121] op_sel_hi:[1,0]
	v_cvt_pk_bf16_f32 v233, v106, v114
	v_cvt_pk_bf16_f32 v234, v105, v107
	v_mul_f32_e32 v118, 0x3d372713, v102
	v_pk_mul_f32 v[110:111], v[152:153], v[110:111]
	v_mul_f32_e32 v118, v102, v118
	v_cvt_pk_bf16_f32 v235, v110, v111
	s_nop 1
	v_permlane16_swap_b32_e32 v232, v234
	v_permlane16_swap_b32_e32 v233, v235
	v_lshl_add_u64 v[236:237], v[124:125], 0, v[238:239]
	global_store_dwordx4 v[236:237], v[232:235], off
	s_nop 1
	v_mul_f32_e32 v116, 0x3d372713, v100
	v_mul_f32_e32 v119, 0x3d372713, v103
	v_mul_f32_e32 v116, v100, v116
	v_mul_f32_e32 v117, 0x3d372713, v101
	v_fma_f32 v118, v102, v118, v102
	v_mul_f32_e32 v119, v103, v119
	v_fma_f32 v116, v100, v116, v100
	v_mul_f32_e32 v117, v101, v117
	v_mul_f32_e32 v118, 0x3f4c422a, v118
	v_fma_f32 v119, v103, v119, v103
	v_mul_f32_e32 v116, 0x3f4c422a, v116
	v_fma_f32 v117, v101, v117, v101
	v_mul_f32_e32 v118, 0xc038aa3b, v118
	v_mul_f32_e32 v119, 0x3f4c422a, v119
	v_mul_f32_e32 v116, 0xc038aa3b, v116
	v_mul_f32_e32 v117, 0x3f4c422a, v117
	v_exp_f32_e32 v118, v118
	v_mul_f32_e32 v119, 0xc038aa3b, v119
	v_exp_f32_e32 v116, v116
	v_mul_f32_e32 v117, 0xc038aa3b, v117
	v_exp_f32_e32 v119, v119
	v_exp_f32_e32 v117, v117
	v_add_f32_e32 v118, 1.0, v118
	v_add_f32_e32 v116, 1.0, v116
	v_rcp_f32_e32 v121, v118
	v_add_f32_e32 v118, 1.0, v119
	v_rcp_f32_e32 v116, v116
	v_add_f32_e32 v117, 1.0, v117
	v_rcp_f32_e32 v119, v118
	v_rcp_f32_e32 v117, v117
	v_pk_mul_f32 v[96:97], v[96:97], v[120:121] op_sel_hi:[1,0]
	v_mul_f32_e32 v116, v100, v116
	v_mul_f32_e32 v100, v102, v121
	v_mul_f32_e32 v102, v103, v119
	v_mul_f32_e32 v103, 0x3d372713, v97
	v_pk_mul_f32 v[98:99], v[98:99], v[120:121] op_sel_hi:[1,0]
	v_mul_f32_e32 v118, v101, v117
	v_mul_f32_e32 v101, 0x3d372713, v96
	v_mul_f32_e32 v103, v97, v103
	v_mul_f32_e32 v117, 0x3d372713, v98
	v_mul_f32_e32 v119, 0x3d372713, v99
	v_mul_f32_e32 v101, v96, v101
	v_fma_f32 v103, v97, v103, v97
	v_mul_f32_e32 v117, v98, v117
	v_mul_f32_e32 v119, v99, v119
	v_fma_f32 v101, v96, v101, v96
	v_mul_f32_e32 v103, 0x3f4c422a, v103
	v_fma_f32 v117, v98, v117, v98
	v_fma_f32 v119, v99, v119, v99
	v_mul_f32_e32 v101, 0x3f4c422a, v101
	v_mul_f32_e32 v103, 0xc038aa3b, v103
	v_mul_f32_e32 v117, 0x3f4c422a, v117
	v_mul_f32_e32 v119, 0x3f4c422a, v119
	v_mul_f32_e32 v101, 0xc038aa3b, v101
	v_exp_f32_e32 v103, v103
	v_mul_f32_e32 v117, 0xc038aa3b, v117
	v_mul_f32_e32 v119, 0xc038aa3b, v119
	v_exp_f32_e32 v101, v101
	v_exp_f32_e32 v117, v117
	v_exp_f32_e32 v119, v119
	v_add_f32_e32 v103, 1.0, v103
	v_add_f32_e32 v101, 1.0, v101
	v_rcp_f32_e32 v103, v103
	v_add_f32_e32 v117, 1.0, v117
	v_add_f32_e32 v119, 1.0, v119
	v_rcp_f32_e32 v101, v101
	v_rcp_f32_e32 v117, v117
	v_rcp_f32_e32 v119, v119
	v_cvt_pk_bf16_f32 v232, v116, v118
	v_cvt_pk_bf16_f32 v233, v100, v102
	v_mul_f32_e32 v122, v97, v103
	v_cndmask_b32_e64 v97, 0, 1, s[30:31]
	v_mul_f32_e32 v120, v96, v101
	v_mul_f32_e32 v96, v98, v117
	v_mul_f32_e32 v98, v99, v119
	v_cmp_ne_u32_e64 s[6:7], 1, v97
	s_andn2_b64 vcc, exec, s[30:31]
	v_cvt_pk_bf16_f32 v234, v120, v122
	v_cvt_pk_bf16_f32 v235, v96, v98
	s_nop 1
	v_permlane16_swap_b32_e32 v232, v234
	v_permlane16_swap_b32_e32 v233, v235
	v_lshl_add_u64 v[236:237], v[124:125], 0, v[238:239]
	global_store_dwordx4 v[236:237], v[232:235], off offset:256
	s_nop 1
	s_cbranch_vccnz .LBB0_242
	v_pk_mul_f32 v[126:127], v[108:109], v[108:109]
	v_pk_add_f32 v[156:157], v[104:105], v[108:109]
	v_pk_mul_f32 v[108:109], v[104:105], v[108:109]
	v_pk_mul_f32 v[124:125], v[104:105], v[104:105]
	v_pk_mul_f32 v[154:155], v[114:115], v[114:115]
	v_mov_b32_e32 v157, v109
	v_pk_add_f32 v[108:109], v[106:107], v[114:115]
	v_pk_mul_f32 v[114:115], v[106:107], v[114:115]
	v_pk_mul_f32 v[152:153], v[106:107], v[106:107]
	v_mul_f32_e32 v114, v110, v110
	v_pk_mov_b32 v[104:105], v[104:105], v[124:125] op_sel:[1,0]
	v_pk_mov_b32 v[106:107], v[106:107], v[126:127] op_sel:[1,0]
	v_mov_b32_e32 v109, v115
	v_pk_fma_f32 v[114:115], v[110:111], v[110:111], v[114:115] op_sel_hi:[1,1,0]
	v_pk_add_f32 v[104:105], v[104:105], v[106:107]
	v_mov_b32_e32 v106, v110
	v_mov_b32_e32 v107, v152
	v_pk_mov_b32 v[110:111], v[110:111], v[154:155] op_sel:[1,0]
	v_mul_f32_e32 v117, v116, v116
	v_mul_f32_e32 v119, v118, v118
	v_mul_f32_e32 v101, v100, v100
	v_mul_f32_e32 v103, v102, v102
	v_pk_add_f32 v[108:109], v[156:157], v[108:109]
	v_mov_b32_e32 v114, v133
	v_pk_add_f32 v[106:107], v[106:107], v[110:111]
	v_mul_f32_e32 v121, v120, v120
	v_mul_f32_e32 v123, v122, v122
	v_mul_f32_e32 v97, v96, v96
	v_mul_f32_e32 v99, v98, v98
	v_pk_add_f32 v[108:109], v[108:109], v[114:115]
	v_pk_add_f32 v[104:105], v[104:105], v[106:107]
	v_pk_add_f32 v[106:107], v[116:117], v[118:119]
	v_pk_add_f32 v[100:101], v[100:101], v[102:103]
	v_pk_add_f32 v[104:105], v[104:105], v[108:109]
	v_pk_add_f32 v[100:101], v[106:107], v[100:101]
	v_pk_add_f32 v[102:103], v[120:121], v[122:123]
	v_pk_add_f32 v[96:97], v[96:97], v[98:99]
	v_pk_add_f32 v[100:101], v[100:101], v[104:105]
	v_pk_add_f32 v[96:97], v[102:103], v[96:97]
	s_nop 0
	v_pk_add_f32 v[96:97], v[96:97], v[100:101]
	v_mov_b32_e32 v98, v96
	v_mov_b32_e32 v99, v97
	s_waitcnt lgkmcnt(0)
	s_nop 1
	v_permlane16_swap_b32_e32 v98, v96
	v_permlane16_swap_b32_e32 v99, v97
	v_pk_add_f32 v[96:97], v[96:97], v[98:99]
	ds_bpermute_b32 v98, v165, v96
	ds_bpermute_b32 v99, v165, v97
	s_and_saveexec_b64 s[30:31], s[2:3]
	s_cbranch_execz .LBB0_241
	s_lshl_b32 s25, s14, 2
	s_add_i32 s25, s25, -16
	v_mov_b32_e32 v132, s25
	v_lshl_add_u64 v[100:101], v[112:113], 4, v[132:133]
	v_or_b32_e32 v100, s59, v100
	v_lshl_add_u64 v[100:101], v[100:101], 3, s[18:19]
	s_waitcnt lgkmcnt(0)
	v_pk_add_f32 v[96:97], v[96:97], v[98:99]
	global_store_dwordx2 v[100:101], v[96:97], off

.LBB0_242:
	v_add_f32_e32 v96, v186, v187
	v_fmamk_f32 v96, v96, 0x3a800000, v175
	v_rsq_f32_e32 v104, v96
	v_add_u32_e32 v96, s9, v169
	v_ashrrev_i32_e32 v97, 31, v96
	s_waitcnt lgkmcnt(0)
	v_lshlrev_b64 v[98:99], 11, v[96:97]
	v_pk_mul_f32 v[94:95], v[94:95], v[104:105] op_sel_hi:[1,0]
	v_pk_mul_f32 v[92:93], v[92:93], v[104:105] op_sel_hi:[1,0]
	v_mul_f32_e32 v100, 0x3d372713, v94
	v_mul_f32_e32 v100, v94, v100
	v_fma_f32 v100, v94, v100, v94
	v_lshl_add_u64 v[108:109], v[146:147], 0, v[98:99]
	v_mul_f32_e32 v99, 0x3d372713, v93
	v_mul_f32_e32 v100, 0x3f4c422a, v100
	v_mul_f32_e32 v99, v93, v99
	v_mul_f32_e32 v100, 0xc038aa3b, v100
	v_pk_mul_f32 v[110:111], v[88:89], v[104:105] op_sel_hi:[1,0]
	v_fma_f32 v99, v93, v99, v93
	v_exp_f32_e32 v101, v100
	v_mul_f32_e32 v100, 0x3d372713, v95
	v_mul_f32_e32 v88, 0x3d372713, v110
	v_mul_f32_e32 v99, 0x3f4c422a, v99
	v_mul_f32_e32 v100, v95, v100
	v_mul_f32_e32 v88, v110, v88
	v_mul_f32_e32 v89, 0x3d372713, v111
	v_mul_f32_e32 v99, 0xc038aa3b, v99
	v_fma_f32 v100, v95, v100, v95
	v_fma_f32 v88, v110, v88, v110
	v_mul_f32_e32 v89, v111, v89
	v_exp_f32_e32 v99, v99
	v_mul_f32_e32 v100, 0x3f4c422a, v100
	v_mul_f32_e32 v88, 0x3f4c422a, v88
	v_fma_f32 v89, v111, v89, v111
	v_mul_f32_e32 v100, 0xc038aa3b, v100
	v_mul_f32_e32 v88, 0xc038aa3b, v88
	v_mul_f32_e32 v89, 0x3f4c422a, v89
	v_exp_f32_e32 v103, v100
	v_exp_f32_e32 v88, v88
	v_mul_f32_e32 v89, 0xc038aa3b, v89
	v_exp_f32_e32 v89, v89
	v_add_f32_e32 v99, 1.0, v99
	v_rcp_f32_e32 v100, v99
	v_add_f32_e32 v99, 1.0, v101
	v_rcp_f32_e32 v102, v99
	v_add_f32_e32 v99, 1.0, v103
	v_add_f32_e32 v88, 1.0, v88
	v_rcp_f32_e32 v106, v99
	v_rcp_f32_e32 v99, v88
	v_add_f32_e32 v88, 1.0, v89
	v_rcp_f32_e32 v103, v88
	v_mul_f32_e32 v98, 0x3d372713, v92
	v_mul_f32_e32 v98, v92, v98
	v_pk_mul_f32 v[112:113], v[90:91], v[104:105] op_sel_hi:[1,0]
	v_mov_b32_e32 v89, v110
	v_pk_mov_b32 v[90:91], v[92:93], v[110:111] op_sel:[1,0]
	v_mov_b32_e32 v101, v99
	v_mov_b32_e32 v110, v94
	v_fma_f32 v98, v92, v98, v92
	v_mov_b32_e32 v88, v92
	v_pk_mul_f32 v[92:93], v[90:91], v[100:101]
	v_pk_mul_f32 v[90:91], v[110:111], v[102:103]
	v_mov_b32_e32 v110, v95
	v_mul_f32_e32 v94, 0x3d372713, v112
	v_mul_f32_e32 v95, 0x3d372713, v113
	v_mul_f32_e32 v94, v112, v94
	v_mul_f32_e32 v95, v113, v95
	v_mul_f32_e32 v98, 0x3f4c422a, v98
	v_fma_f32 v94, v112, v94, v112
	v_fma_f32 v95, v113, v95, v113
	v_mul_f32_e32 v98, 0xc038aa3b, v98
	v_mul_f32_e32 v94, 0x3f4c422a, v94
	v_mul_f32_e32 v95, 0x3f4c422a, v95
	v_exp_f32_e32 v98, v98
	v_mul_f32_e32 v94, 0xc038aa3b, v94
	v_mul_f32_e32 v95, 0xc038aa3b, v95
	v_exp_f32_e32 v94, v94
	v_exp_f32_e32 v95, v95
	v_add_f32_e32 v98, 1.0, v98
	v_rcp_f32_e32 v98, v98
	v_add_f32_e32 v94, 1.0, v94
	v_add_f32_e32 v95, 1.0, v95
	v_rcp_f32_e32 v94, v94
	v_rcp_f32_e32 v95, v95
	v_mov_b32_e32 v107, v103
	v_pk_mul_f32 v[88:89], v[88:89], v[98:99]
	v_pk_mul_f32 v[98:99], v[110:111], v[106:107]
	v_cvt_pk_bf16_f32 v232, v88, v92
	v_pk_mul_f32 v[86:87], v[86:87], v[104:105] op_sel_hi:[1,0]
	v_cvt_pk_bf16_f32 v233, v90, v98
	v_pk_mul_f32 v[94:95], v[112:113], v[94:95]
	v_cvt_pk_bf16_f32 v234, v89, v91
	v_pk_mul_f32 v[84:85], v[84:85], v[104:105] op_sel_hi:[1,0]
	v_cvt_pk_bf16_f32 v235, v94, v95
	v_mul_f32_e32 v102, 0x3d372713, v86
	s_nop 1
	v_permlane16_swap_b32_e32 v232, v234
	v_permlane16_swap_b32_e32 v233, v235
	v_lshl_add_u64 v[236:237], v[108:109], 0, v[238:239]
	global_store_dwordx4 v[236:237], v[232:235], off
	s_nop 1
	v_mul_f32_e32 v100, 0x3d372713, v84
	v_mul_f32_e32 v101, 0x3d372713, v85
	v_mul_f32_e32 v102, v86, v102
	v_mul_f32_e32 v103, 0x3d372713, v87
	v_mul_f32_e32 v100, v84, v100
	v_mul_f32_e32 v101, v85, v101
	v_fma_f32 v102, v86, v102, v86
	v_mul_f32_e32 v103, v87, v103
	v_fma_f32 v100, v84, v100, v84
	v_fma_f32 v101, v85, v101, v85
	v_mul_f32_e32 v102, 0x3f4c422a, v102
	v_fma_f32 v103, v87, v103, v87
	v_mul_f32_e32 v100, 0x3f4c422a, v100
	v_mul_f32_e32 v101, 0x3f4c422a, v101
	v_mul_f32_e32 v102, 0xc038aa3b, v102
	v_mul_f32_e32 v103, 0x3f4c422a, v103
	v_mul_f32_e32 v100, 0xc038aa3b, v100
	v_mul_f32_e32 v101, 0xc038aa3b, v101
	v_exp_f32_e32 v102, v102
	v_mul_f32_e32 v103, 0xc038aa3b, v103
	v_exp_f32_e32 v100, v100
	v_exp_f32_e32 v101, v101
	v_exp_f32_e32 v103, v103
	v_add_f32_e32 v102, 1.0, v102
	v_add_f32_e32 v100, 1.0, v100
	v_add_f32_e32 v101, 1.0, v101
	v_rcp_f32_e32 v105, v102
	v_add_f32_e32 v102, 1.0, v103
	v_rcp_f32_e32 v100, v100
	v_rcp_f32_e32 v101, v101
	v_rcp_f32_e32 v103, v102
	v_pk_mul_f32 v[80:81], v[80:81], v[104:105] op_sel_hi:[1,0]
	v_pk_mul_f32 v[82:83], v[82:83], v[104:105] op_sel_hi:[1,0]
	v_mul_f32_e32 v100, v84, v100
	v_mul_f32_e32 v102, v85, v101
	v_mul_f32_e32 v84, v86, v105
	v_mul_f32_e32 v86, v87, v103
	v_mul_f32_e32 v85, 0x3d372713, v80
	v_mul_f32_e32 v87, 0x3d372713, v81
	v_mul_f32_e32 v101, 0x3d372713, v82
	v_mul_f32_e32 v103, 0x3d372713, v83
	v_mul_f32_e32 v85, v80, v85
	v_mul_f32_e32 v87, v81, v87
	v_mul_f32_e32 v101, v82, v101
	v_mul_f32_e32 v103, v83, v103
	v_fma_f32 v85, v80, v85, v80
	v_fma_f32 v87, v81, v87, v81
	v_fma_f32 v101, v82, v101, v82
	v_fma_f32 v103, v83, v103, v83
	v_mul_f32_e32 v85, 0x3f4c422a, v85
	v_mul_f32_e32 v87, 0x3f4c422a, v87
	v_mul_f32_e32 v101, 0x3f4c422a, v101
	v_mul_f32_e32 v103, 0x3f4c422a, v103
	v_mul_f32_e32 v85, 0xc038aa3b, v85
	v_mul_f32_e32 v87, 0xc038aa3b, v87
	v_mul_f32_e32 v101, 0xc038aa3b, v101
	v_mul_f32_e32 v103, 0xc038aa3b, v103
	v_exp_f32_e32 v85, v85
	v_exp_f32_e32 v87, v87
	v_exp_f32_e32 v101, v101
	v_exp_f32_e32 v103, v103
	v_add_f32_e32 v85, 1.0, v85
	v_add_f32_e32 v87, 1.0, v87
	v_add_f32_e32 v101, 1.0, v101
	v_add_f32_e32 v103, 1.0, v103
	v_rcp_f32_e32 v85, v85
	v_rcp_f32_e32 v87, v87
	v_rcp_f32_e32 v101, v101
	v_rcp_f32_e32 v103, v103
	v_cvt_pk_bf16_f32 v232, v100, v102
	v_cvt_pk_bf16_f32 v233, v84, v86
	v_mul_f32_e32 v104, v80, v85
	v_mul_f32_e32 v106, v81, v87
	v_mul_f32_e32 v80, v82, v101
	v_mul_f32_e32 v82, v83, v103
	s_and_b64 vcc, exec, s[6:7]
	v_cvt_pk_bf16_f32 v234, v104, v106
	v_cvt_pk_bf16_f32 v235, v80, v82
	s_nop 1
	v_permlane16_swap_b32_e32 v232, v234
	v_permlane16_swap_b32_e32 v233, v235
	v_lshl_add_u64 v[236:237], v[108:109], 0, v[238:239]
	global_store_dwordx4 v[236:237], v[232:235], off offset:256
	s_nop 1
	s_cbranch_vccnz .LBB0_246
	v_pk_mul_f32 v[110:111], v[92:93], v[92:93]
	v_pk_add_f32 v[116:117], v[88:89], v[92:93]
	v_pk_mul_f32 v[92:93], v[88:89], v[92:93]
	v_pk_mul_f32 v[108:109], v[88:89], v[88:89]
	v_pk_mul_f32 v[114:115], v[98:99], v[98:99]
	v_mov_b32_e32 v117, v93
	v_pk_add_f32 v[92:93], v[90:91], v[98:99]
	v_pk_mul_f32 v[98:99], v[90:91], v[98:99]
	v_pk_mul_f32 v[112:113], v[90:91], v[90:91]
	v_mul_f32_e32 v98, v94, v94
	v_pk_mov_b32 v[88:89], v[88:89], v[108:109] op_sel:[1,0]
	v_pk_mov_b32 v[90:91], v[90:91], v[110:111] op_sel:[1,0]
	v_mov_b32_e32 v93, v99
	v_pk_fma_f32 v[98:99], v[94:95], v[94:95], v[98:99] op_sel_hi:[1,1,0]
	v_pk_add_f32 v[88:89], v[88:89], v[90:91]
	v_mov_b32_e32 v90, v94
	v_mov_b32_e32 v91, v112
	v_pk_mov_b32 v[94:95], v[94:95], v[114:115] op_sel:[1,0]
	v_mul_f32_e32 v101, v100, v100
	v_mul_f32_e32 v103, v102, v102
	v_mul_f32_e32 v85, v84, v84
	v_mul_f32_e32 v87, v86, v86
	v_pk_add_f32 v[92:93], v[116:117], v[92:93]
	v_mov_b32_e32 v98, v133
	v_pk_add_f32 v[90:91], v[90:91], v[94:95]
	v_mul_f32_e32 v105, v104, v104
	v_mul_f32_e32 v107, v106, v106
	v_mul_f32_e32 v81, v80, v80
	v_mul_f32_e32 v83, v82, v82
	v_pk_add_f32 v[92:93], v[92:93], v[98:99]
	v_pk_add_f32 v[88:89], v[88:89], v[90:91]
	v_pk_add_f32 v[90:91], v[100:101], v[102:103]
	v_pk_add_f32 v[84:85], v[84:85], v[86:87]
	v_pk_add_f32 v[88:89], v[88:89], v[92:93]
	v_pk_add_f32 v[84:85], v[90:91], v[84:85]
	v_pk_add_f32 v[86:87], v[104:105], v[106:107]
	v_pk_add_f32 v[80:81], v[80:81], v[82:83]
	v_pk_add_f32 v[84:85], v[84:85], v[88:89]
	v_pk_add_f32 v[80:81], v[86:87], v[80:81]
	s_nop 0
	v_pk_add_f32 v[80:81], v[80:81], v[84:85]
	v_mov_b32_e32 v82, v80
	v_mov_b32_e32 v83, v81
	s_waitcnt lgkmcnt(0)
	s_nop 1
	v_permlane16_swap_b32_e32 v82, v80
	v_permlane16_swap_b32_e32 v83, v81
	v_pk_add_f32 v[80:81], v[80:81], v[82:83]
	ds_bpermute_b32 v82, v165, v80
	ds_bpermute_b32 v83, v165, v81
	s_and_saveexec_b64 s[30:31], s[2:3]
	s_cbranch_execz .LBB0_245
	s_lshl_b32 s25, s14, 2
	s_add_i32 s25, s25, -16
	v_mov_b32_e32 v132, s25
	v_lshl_add_u64 v[84:85], v[96:97], 4, v[132:133]
	v_or_b32_e32 v84, s59, v84
	v_lshl_add_u64 v[84:85], v[84:85], 3, s[18:19]
	s_waitcnt lgkmcnt(0)
	v_pk_add_f32 v[80:81], v[80:81], v[82:83]
	global_store_dwordx2 v[84:85], v[80:81], off

.LBB0_246:
	v_add_f32_e32 v80, v184, v185
	v_fmamk_f32 v80, v80, 0x3a800000, v175
	v_rsq_f32_e32 v88, v80
	v_add_u32_e32 v80, s9, v170
	v_ashrrev_i32_e32 v81, 31, v80
	s_waitcnt lgkmcnt(0)
	v_lshlrev_b64 v[82:83], 11, v[80:81]
	v_pk_mul_f32 v[78:79], v[78:79], v[88:89] op_sel_hi:[1,0]
	v_pk_mul_f32 v[76:77], v[76:77], v[88:89] op_sel_hi:[1,0]
	v_mul_f32_e32 v84, 0x3d372713, v78
	v_mul_f32_e32 v84, v78, v84
	v_fma_f32 v84, v78, v84, v78
	v_lshl_add_u64 v[92:93], v[146:147], 0, v[82:83]
	v_mul_f32_e32 v83, 0x3d372713, v77
	v_mul_f32_e32 v84, 0x3f4c422a, v84
	v_mul_f32_e32 v83, v77, v83
	v_mul_f32_e32 v84, 0xc038aa3b, v84
	v_pk_mul_f32 v[94:95], v[72:73], v[88:89] op_sel_hi:[1,0]
	v_fma_f32 v83, v77, v83, v77
	v_exp_f32_e32 v85, v84
	v_mul_f32_e32 v84, 0x3d372713, v79
	v_mul_f32_e32 v72, 0x3d372713, v94
	v_mul_f32_e32 v83, 0x3f4c422a, v83
	v_mul_f32_e32 v84, v79, v84
	v_mul_f32_e32 v72, v94, v72
	v_mul_f32_e32 v73, 0x3d372713, v95
	v_mul_f32_e32 v83, 0xc038aa3b, v83
	v_fma_f32 v84, v79, v84, v79
	v_fma_f32 v72, v94, v72, v94
	v_mul_f32_e32 v73, v95, v73
	v_exp_f32_e32 v83, v83
	v_mul_f32_e32 v84, 0x3f4c422a, v84
	v_mul_f32_e32 v72, 0x3f4c422a, v72
	v_fma_f32 v73, v95, v73, v95
	v_mul_f32_e32 v84, 0xc038aa3b, v84
	v_mul_f32_e32 v72, 0xc038aa3b, v72
	v_mul_f32_e32 v73, 0x3f4c422a, v73
	v_exp_f32_e32 v87, v84
	v_exp_f32_e32 v72, v72
	v_mul_f32_e32 v73, 0xc038aa3b, v73
	v_exp_f32_e32 v73, v73
	v_add_f32_e32 v83, 1.0, v83
	v_rcp_f32_e32 v84, v83
	v_add_f32_e32 v83, 1.0, v85
	v_rcp_f32_e32 v86, v83
	v_add_f32_e32 v83, 1.0, v87
	v_add_f32_e32 v72, 1.0, v72
	v_rcp_f32_e32 v90, v83
	v_rcp_f32_e32 v83, v72
	v_add_f32_e32 v72, 1.0, v73
	v_rcp_f32_e32 v87, v72
	v_mul_f32_e32 v82, 0x3d372713, v76
	v_mul_f32_e32 v82, v76, v82
	v_pk_mul_f32 v[96:97], v[74:75], v[88:89] op_sel_hi:[1,0]
	v_mov_b32_e32 v73, v94
	v_pk_mov_b32 v[74:75], v[76:77], v[94:95] op_sel:[1,0]
	v_mov_b32_e32 v85, v83
	v_mov_b32_e32 v94, v78
	v_fma_f32 v82, v76, v82, v76
	v_mov_b32_e32 v72, v76
	v_pk_mul_f32 v[76:77], v[74:75], v[84:85]
	v_pk_mul_f32 v[74:75], v[94:95], v[86:87]
	v_mov_b32_e32 v94, v79
	v_mul_f32_e32 v78, 0x3d372713, v96
	v_mul_f32_e32 v79, 0x3d372713, v97
	v_mul_f32_e32 v78, v96, v78
	v_mul_f32_e32 v79, v97, v79
	v_mul_f32_e32 v82, 0x3f4c422a, v82
	v_fma_f32 v78, v96, v78, v96
	v_fma_f32 v79, v97, v79, v97
	v_mul_f32_e32 v82, 0xc038aa3b, v82
	v_mul_f32_e32 v78, 0x3f4c422a, v78
	v_mul_f32_e32 v79, 0x3f4c422a, v79
	v_exp_f32_e32 v82, v82
	v_mul_f32_e32 v78, 0xc038aa3b, v78
	v_mul_f32_e32 v79, 0xc038aa3b, v79
	v_exp_f32_e32 v78, v78
	v_exp_f32_e32 v79, v79
	v_add_f32_e32 v82, 1.0, v82
	v_rcp_f32_e32 v82, v82
	v_add_f32_e32 v78, 1.0, v78
	v_add_f32_e32 v79, 1.0, v79
	v_rcp_f32_e32 v78, v78
	v_rcp_f32_e32 v79, v79
	v_mov_b32_e32 v91, v87
	v_pk_mul_f32 v[72:73], v[72:73], v[82:83]
	v_pk_mul_f32 v[82:83], v[94:95], v[90:91]
	v_cvt_pk_bf16_f32 v232, v72, v76
	v_pk_mul_f32 v[70:71], v[70:71], v[88:89] op_sel_hi:[1,0]
	v_cvt_pk_bf16_f32 v233, v74, v82
	v_pk_mul_f32 v[78:79], v[96:97], v[78:79]
	v_cvt_pk_bf16_f32 v234, v73, v75
	v_pk_mul_f32 v[68:69], v[68:69], v[88:89] op_sel_hi:[1,0]
	v_cvt_pk_bf16_f32 v235, v78, v79
	v_mul_f32_e32 v86, 0x3d372713, v70
	s_nop 1
	v_permlane16_swap_b32_e32 v232, v234
	v_permlane16_swap_b32_e32 v233, v235
	v_lshl_add_u64 v[236:237], v[92:93], 0, v[238:239]
	global_store_dwordx4 v[236:237], v[232:235], off
	s_nop 1
	v_mul_f32_e32 v84, 0x3d372713, v68
	v_mul_f32_e32 v85, 0x3d372713, v69
	v_mul_f32_e32 v86, v70, v86
	v_mul_f32_e32 v87, 0x3d372713, v71
	v_mul_f32_e32 v84, v68, v84
	v_mul_f32_e32 v85, v69, v85
	v_fma_f32 v86, v70, v86, v70
	v_mul_f32_e32 v87, v71, v87
	v_fma_f32 v84, v68, v84, v68
	v_fma_f32 v85, v69, v85, v69
	v_mul_f32_e32 v86, 0x3f4c422a, v86
	v_fma_f32 v87, v71, v87, v71
	v_mul_f32_e32 v84, 0x3f4c422a, v84
	v_mul_f32_e32 v85, 0x3f4c422a, v85
	v_mul_f32_e32 v86, 0xc038aa3b, v86
	v_mul_f32_e32 v87, 0x3f4c422a, v87
	v_mul_f32_e32 v84, 0xc038aa3b, v84
	v_mul_f32_e32 v85, 0xc038aa3b, v85
	v_exp_f32_e32 v86, v86
	v_mul_f32_e32 v87, 0xc038aa3b, v87
	v_exp_f32_e32 v84, v84
	v_exp_f32_e32 v85, v85
	v_exp_f32_e32 v87, v87
	v_add_f32_e32 v86, 1.0, v86
	v_add_f32_e32 v84, 1.0, v84
	v_add_f32_e32 v85, 1.0, v85
	v_rcp_f32_e32 v89, v86
	v_add_f32_e32 v86, 1.0, v87
	v_rcp_f32_e32 v84, v84
	v_rcp_f32_e32 v85, v85
	v_rcp_f32_e32 v87, v86
	v_pk_mul_f32 v[64:65], v[64:65], v[88:89] op_sel_hi:[1,0]
	v_pk_mul_f32 v[66:67], v[66:67], v[88:89] op_sel_hi:[1,0]
	v_mul_f32_e32 v84, v68, v84
	v_mul_f32_e32 v86, v69, v85
	v_mul_f32_e32 v68, v70, v89
	v_mul_f32_e32 v70, v71, v87
	v_mul_f32_e32 v69, 0x3d372713, v64
	v_mul_f32_e32 v71, 0x3d372713, v65
	v_mul_f32_e32 v85, 0x3d372713, v66
	v_mul_f32_e32 v87, 0x3d372713, v67
	v_mul_f32_e32 v69, v64, v69
	v_mul_f32_e32 v71, v65, v71
	v_mul_f32_e32 v85, v66, v85
	v_mul_f32_e32 v87, v67, v87
	v_fma_f32 v69, v64, v69, v64
	v_fma_f32 v71, v65, v71, v65
	v_fma_f32 v85, v66, v85, v66
	v_fma_f32 v87, v67, v87, v67
	v_mul_f32_e32 v69, 0x3f4c422a, v69
	v_mul_f32_e32 v71, 0x3f4c422a, v71
	v_mul_f32_e32 v85, 0x3f4c422a, v85
	v_mul_f32_e32 v87, 0x3f4c422a, v87
	v_mul_f32_e32 v69, 0xc038aa3b, v69
	v_mul_f32_e32 v71, 0xc038aa3b, v71
	v_mul_f32_e32 v85, 0xc038aa3b, v85
	v_mul_f32_e32 v87, 0xc038aa3b, v87
	v_exp_f32_e32 v69, v69
	v_exp_f32_e32 v71, v71
	v_exp_f32_e32 v85, v85
	v_exp_f32_e32 v87, v87
	v_add_f32_e32 v69, 1.0, v69
	v_add_f32_e32 v71, 1.0, v71
	v_add_f32_e32 v85, 1.0, v85
	v_add_f32_e32 v87, 1.0, v87
	v_rcp_f32_e32 v69, v69
	v_rcp_f32_e32 v71, v71
	v_rcp_f32_e32 v85, v85
	v_rcp_f32_e32 v87, v87
	v_cvt_pk_bf16_f32 v232, v84, v86
	v_cvt_pk_bf16_f32 v233, v68, v70
	v_mul_f32_e32 v88, v64, v69
	v_mul_f32_e32 v90, v65, v71
	v_mul_f32_e32 v64, v66, v85
	v_mul_f32_e32 v66, v67, v87
	s_and_b64 vcc, exec, s[6:7]
	v_cvt_pk_bf16_f32 v234, v88, v90
	v_cvt_pk_bf16_f32 v235, v64, v66
	s_nop 1
	v_permlane16_swap_b32_e32 v232, v234
	v_permlane16_swap_b32_e32 v233, v235
	v_lshl_add_u64 v[236:237], v[92:93], 0, v[238:239]
	global_store_dwordx4 v[236:237], v[232:235], off offset:256
	s_nop 1
	s_cbranch_vccnz .LBB0_250
	v_pk_mul_f32 v[94:95], v[76:77], v[76:77]
	v_pk_add_f32 v[100:101], v[72:73], v[76:77]
	v_pk_mul_f32 v[76:77], v[72:73], v[76:77]
	v_pk_mul_f32 v[92:93], v[72:73], v[72:73]
	v_pk_mul_f32 v[98:99], v[82:83], v[82:83]
	v_mov_b32_e32 v101, v77
	v_pk_add_f32 v[76:77], v[74:75], v[82:83]
	v_pk_mul_f32 v[82:83], v[74:75], v[82:83]
	v_pk_mul_f32 v[96:97], v[74:75], v[74:75]
	v_mul_f32_e32 v82, v78, v78
	v_pk_mov_b32 v[72:73], v[72:73], v[92:93] op_sel:[1,0]
	v_pk_mov_b32 v[74:75], v[74:75], v[94:95] op_sel:[1,0]
	v_mov_b32_e32 v77, v83
	v_pk_fma_f32 v[82:83], v[78:79], v[78:79], v[82:83] op_sel_hi:[1,1,0]
	v_pk_add_f32 v[72:73], v[72:73], v[74:75]
	v_mov_b32_e32 v74, v78
	v_mov_b32_e32 v75, v96
	v_pk_mov_b32 v[78:79], v[78:79], v[98:99] op_sel:[1,0]
	v_mul_f32_e32 v85, v84, v84
	v_mul_f32_e32 v87, v86, v86
	v_mul_f32_e32 v69, v68, v68
	v_mul_f32_e32 v71, v70, v70
	v_pk_add_f32 v[76:77], v[100:101], v[76:77]
	v_mov_b32_e32 v82, v133
	v_pk_add_f32 v[74:75], v[74:75], v[78:79]
	v_mul_f32_e32 v89, v88, v88
	v_mul_f32_e32 v91, v90, v90
	v_mul_f32_e32 v65, v64, v64
	v_mul_f32_e32 v67, v66, v66
	v_pk_add_f32 v[76:77], v[76:77], v[82:83]
	v_pk_add_f32 v[72:73], v[72:73], v[74:75]
	v_pk_add_f32 v[74:75], v[84:85], v[86:87]
	v_pk_add_f32 v[68:69], v[68:69], v[70:71]
	v_pk_add_f32 v[72:73], v[72:73], v[76:77]
	v_pk_add_f32 v[68:69], v[74:75], v[68:69]
	v_pk_add_f32 v[70:71], v[88:89], v[90:91]
	v_pk_add_f32 v[64:65], v[64:65], v[66:67]
	v_pk_add_f32 v[68:69], v[68:69], v[72:73]
	v_pk_add_f32 v[64:65], v[70:71], v[64:65]
	s_nop 0
	v_pk_add_f32 v[64:65], v[64:65], v[68:69]
	v_mov_b32_e32 v66, v64
	v_mov_b32_e32 v67, v65
	s_waitcnt lgkmcnt(0)
	s_nop 1
	v_permlane16_swap_b32_e32 v66, v64
	v_permlane16_swap_b32_e32 v67, v65
	v_pk_add_f32 v[64:65], v[64:65], v[66:67]
	ds_bpermute_b32 v66, v165, v64
	ds_bpermute_b32 v67, v165, v65
	s_and_saveexec_b64 s[30:31], s[2:3]
	s_cbranch_execz .LBB0_249
	s_lshl_b32 s9, s14, 2
	s_add_i32 s9, s9, -16
	v_mov_b32_e32 v132, s9
	v_lshl_add_u64 v[68:69], v[80:81], 4, v[132:133]
	v_or_b32_e32 v68, s59, v68
	v_lshl_add_u64 v[68:69], v[68:69], 3, s[18:19]
	s_waitcnt lgkmcnt(0)
	v_pk_add_f32 v[64:65], v[64:65], v[66:67]
	global_store_dwordx2 v[68:69], v[64:65], off

.LBB0_250:
	v_add_f32_e32 v64, v182, v183
	v_fmamk_f32 v64, v64, 0x3a800000, v175
	v_rsq_f32_e32 v70, v64
	v_lshlrev_b64 v[64:65], 11, v[150:151]
	v_lshl_add_u64 v[74:75], v[146:147], 0, v[64:65]
	s_and_b64 vcc, exec, s[6:7]
	v_pk_mul_f32 v[62:63], v[62:63], v[70:71] op_sel_hi:[1,0]
	v_pk_mul_f32 v[60:61], v[60:61], v[70:71] op_sel_hi:[1,0]
	s_waitcnt lgkmcnt(1)
	v_mul_f32_e32 v66, 0x3d372713, v62
	v_mul_f32_e32 v66, v62, v66
	v_fma_f32 v66, v62, v66, v62
	v_mul_f32_e32 v65, 0x3d372713, v61
	v_mul_f32_e32 v66, 0x3f4c422a, v66
	v_mul_f32_e32 v65, v61, v65
	v_mul_f32_e32 v66, 0xc038aa3b, v66
	v_pk_mul_f32 v[76:77], v[56:57], v[70:71] op_sel_hi:[1,0]
	v_fma_f32 v65, v61, v65, v61
	s_waitcnt lgkmcnt(0)
	v_exp_f32_e32 v67, v66
	v_mul_f32_e32 v66, 0x3d372713, v63
	v_mul_f32_e32 v56, 0x3d372713, v76
	v_mul_f32_e32 v65, 0x3f4c422a, v65
	v_mul_f32_e32 v66, v63, v66
	v_mul_f32_e32 v56, v76, v56
	v_mul_f32_e32 v57, 0x3d372713, v77
	v_mul_f32_e32 v65, 0xc038aa3b, v65
	v_fma_f32 v66, v63, v66, v63
	v_fma_f32 v56, v76, v56, v76
	v_mul_f32_e32 v57, v77, v57
	v_exp_f32_e32 v65, v65
	v_mul_f32_e32 v66, 0x3f4c422a, v66
	v_mul_f32_e32 v56, 0x3f4c422a, v56
	v_fma_f32 v57, v77, v57, v77
	v_mul_f32_e32 v66, 0xc038aa3b, v66
	v_mul_f32_e32 v56, 0xc038aa3b, v56
	v_mul_f32_e32 v57, 0x3f4c422a, v57
	v_exp_f32_e32 v69, v66
	v_exp_f32_e32 v56, v56
	v_mul_f32_e32 v57, 0xc038aa3b, v57
	v_exp_f32_e32 v57, v57
	v_add_f32_e32 v65, 1.0, v65
	v_rcp_f32_e32 v66, v65
	v_add_f32_e32 v65, 1.0, v67
	v_rcp_f32_e32 v68, v65
	v_add_f32_e32 v65, 1.0, v69
	v_add_f32_e32 v56, 1.0, v56
	v_rcp_f32_e32 v72, v65
	v_rcp_f32_e32 v65, v56
	v_add_f32_e32 v56, 1.0, v57
	v_rcp_f32_e32 v69, v56
	v_mul_f32_e32 v64, 0x3d372713, v60
	v_mul_f32_e32 v64, v60, v64
	v_pk_mul_f32 v[78:79], v[58:59], v[70:71] op_sel_hi:[1,0]
	v_mov_b32_e32 v57, v76
	v_pk_mov_b32 v[58:59], v[60:61], v[76:77] op_sel:[1,0]
	v_mov_b32_e32 v67, v65
	v_mov_b32_e32 v76, v62
	v_fma_f32 v64, v60, v64, v60
	v_mov_b32_e32 v56, v60
	v_pk_mul_f32 v[60:61], v[58:59], v[66:67]
	v_pk_mul_f32 v[58:59], v[76:77], v[68:69]
	v_mov_b32_e32 v76, v63
	v_mul_f32_e32 v62, 0x3d372713, v78
	v_mul_f32_e32 v63, 0x3d372713, v79
	v_mul_f32_e32 v62, v78, v62
	v_mul_f32_e32 v63, v79, v63
	v_mul_f32_e32 v64, 0x3f4c422a, v64
	v_fma_f32 v62, v78, v62, v78
	v_fma_f32 v63, v79, v63, v79
	v_mul_f32_e32 v64, 0xc038aa3b, v64
	v_mul_f32_e32 v62, 0x3f4c422a, v62
	v_mul_f32_e32 v63, 0x3f4c422a, v63
	v_exp_f32_e32 v64, v64
	v_mul_f32_e32 v62, 0xc038aa3b, v62
	v_mul_f32_e32 v63, 0xc038aa3b, v63
	v_exp_f32_e32 v62, v62
	v_exp_f32_e32 v63, v63
	v_add_f32_e32 v64, 1.0, v64
	v_rcp_f32_e32 v64, v64
	v_add_f32_e32 v62, 1.0, v62
	v_add_f32_e32 v63, 1.0, v63
	v_rcp_f32_e32 v62, v62
	v_rcp_f32_e32 v63, v63
	v_mov_b32_e32 v73, v69
	v_pk_mul_f32 v[56:57], v[56:57], v[64:65]
	v_pk_mul_f32 v[64:65], v[76:77], v[72:73]
	v_cvt_pk_bf16_f32 v232, v56, v60
	v_pk_mul_f32 v[54:55], v[54:55], v[70:71] op_sel_hi:[1,0]
	v_cvt_pk_bf16_f32 v233, v58, v64
	v_pk_mul_f32 v[62:63], v[78:79], v[62:63]
	v_cvt_pk_bf16_f32 v234, v57, v59
	v_pk_mul_f32 v[52:53], v[52:53], v[70:71] op_sel_hi:[1,0]
	v_cvt_pk_bf16_f32 v235, v62, v63
	v_mul_f32_e32 v68, 0x3d372713, v54
	s_nop 1
	v_permlane16_swap_b32_e32 v232, v234
	v_permlane16_swap_b32_e32 v233, v235
	v_lshl_add_u64 v[236:237], v[74:75], 0, v[238:239]
	global_store_dwordx4 v[236:237], v[232:235], off
	s_nop 1
	v_mul_f32_e32 v66, 0x3d372713, v52
	v_mul_f32_e32 v67, 0x3d372713, v53
	v_mul_f32_e32 v68, v54, v68
	v_mul_f32_e32 v69, 0x3d372713, v55
	v_mul_f32_e32 v66, v52, v66
	v_mul_f32_e32 v67, v53, v67
	v_fma_f32 v68, v54, v68, v54
	v_mul_f32_e32 v69, v55, v69
	v_fma_f32 v66, v52, v66, v52
	v_fma_f32 v67, v53, v67, v53
	v_mul_f32_e32 v68, 0x3f4c422a, v68
	v_fma_f32 v69, v55, v69, v55
	v_mul_f32_e32 v66, 0x3f4c422a, v66
	v_mul_f32_e32 v67, 0x3f4c422a, v67
	v_mul_f32_e32 v68, 0xc038aa3b, v68
	v_mul_f32_e32 v69, 0x3f4c422a, v69
	v_mul_f32_e32 v66, 0xc038aa3b, v66
	v_mul_f32_e32 v67, 0xc038aa3b, v67
	v_exp_f32_e32 v68, v68
	v_mul_f32_e32 v69, 0xc038aa3b, v69
	v_exp_f32_e32 v66, v66
	v_exp_f32_e32 v67, v67
	v_exp_f32_e32 v69, v69
	v_add_f32_e32 v68, 1.0, v68
	v_add_f32_e32 v66, 1.0, v66
	v_add_f32_e32 v67, 1.0, v67
	v_rcp_f32_e32 v71, v68
	v_add_f32_e32 v68, 1.0, v69
	v_rcp_f32_e32 v66, v66
	v_rcp_f32_e32 v67, v67
	v_rcp_f32_e32 v69, v68
	v_pk_mul_f32 v[48:49], v[48:49], v[70:71] op_sel_hi:[1,0]
	v_pk_mul_f32 v[50:51], v[50:51], v[70:71] op_sel_hi:[1,0]
	v_mul_f32_e32 v66, v52, v66
	v_mul_f32_e32 v68, v53, v67
	v_mul_f32_e32 v52, v54, v71
	v_mul_f32_e32 v54, v55, v69
	v_mul_f32_e32 v53, 0x3d372713, v48
	v_mul_f32_e32 v55, 0x3d372713, v49
	v_mul_f32_e32 v67, 0x3d372713, v50
	v_mul_f32_e32 v69, 0x3d372713, v51
	v_mul_f32_e32 v53, v48, v53
	v_mul_f32_e32 v55, v49, v55
	v_mul_f32_e32 v67, v50, v67
	v_mul_f32_e32 v69, v51, v69
	v_fma_f32 v53, v48, v53, v48
	v_fma_f32 v55, v49, v55, v49
	v_fma_f32 v67, v50, v67, v50
	v_fma_f32 v69, v51, v69, v51
	v_mul_f32_e32 v53, 0x3f4c422a, v53
	v_mul_f32_e32 v55, 0x3f4c422a, v55
	v_mul_f32_e32 v67, 0x3f4c422a, v67
	v_mul_f32_e32 v69, 0x3f4c422a, v69
	v_mul_f32_e32 v53, 0xc038aa3b, v53
	v_mul_f32_e32 v55, 0xc038aa3b, v55
	v_mul_f32_e32 v67, 0xc038aa3b, v67
	v_mul_f32_e32 v69, 0xc038aa3b, v69
	v_exp_f32_e32 v53, v53
	v_exp_f32_e32 v55, v55
	v_exp_f32_e32 v67, v67
	v_exp_f32_e32 v69, v69
	v_add_f32_e32 v53, 1.0, v53
	v_add_f32_e32 v55, 1.0, v55
	v_add_f32_e32 v67, 1.0, v67
	v_add_f32_e32 v69, 1.0, v69
	v_rcp_f32_e32 v53, v53
	v_rcp_f32_e32 v55, v55
	v_rcp_f32_e32 v67, v67
	v_rcp_f32_e32 v69, v69
	v_cvt_pk_bf16_f32 v232, v66, v68
	v_cvt_pk_bf16_f32 v233, v52, v54
	v_mul_f32_e32 v70, v48, v53
	v_mul_f32_e32 v72, v49, v55
	v_mul_f32_e32 v48, v50, v67
	v_mul_f32_e32 v50, v51, v69
	v_cvt_pk_bf16_f32 v234, v70, v72
	v_cvt_pk_bf16_f32 v235, v48, v50
	s_nop 1
	v_permlane16_swap_b32_e32 v232, v234
	v_permlane16_swap_b32_e32 v233, v235
	v_lshl_add_u64 v[236:237], v[74:75], 0, v[238:239]
	global_store_dwordx4 v[236:237], v[232:235], off offset:256
	s_nop 1
	s_cbranch_vccnz .LBB0_254
	v_pk_mul_f32 v[76:77], v[60:61], v[60:61]
	v_pk_add_f32 v[82:83], v[56:57], v[60:61]
	v_pk_mul_f32 v[60:61], v[56:57], v[60:61]
	v_pk_mul_f32 v[74:75], v[56:57], v[56:57]
	v_pk_mul_f32 v[80:81], v[64:65], v[64:65]
	v_mov_b32_e32 v83, v61
	v_pk_add_f32 v[60:61], v[58:59], v[64:65]
	v_pk_mul_f32 v[64:65], v[58:59], v[64:65]
	v_pk_mul_f32 v[78:79], v[58:59], v[58:59]
	v_mul_f32_e32 v64, v62, v62
	v_pk_mov_b32 v[56:57], v[56:57], v[74:75] op_sel:[1,0]
	v_pk_mov_b32 v[58:59], v[58:59], v[76:77] op_sel:[1,0]
	v_mov_b32_e32 v61, v65
	v_pk_fma_f32 v[64:65], v[62:63], v[62:63], v[64:65] op_sel_hi:[1,1,0]
	v_pk_add_f32 v[56:57], v[56:57], v[58:59]
	v_mov_b32_e32 v58, v62
	v_mov_b32_e32 v59, v78
	v_pk_mov_b32 v[62:63], v[62:63], v[80:81] op_sel:[1,0]
	v_mul_f32_e32 v67, v66, v66
	v_mul_f32_e32 v69, v68, v68
	v_mul_f32_e32 v53, v52, v52
	v_mul_f32_e32 v55, v54, v54
	v_pk_add_f32 v[60:61], v[82:83], v[60:61]
	v_mov_b32_e32 v64, v133
	v_pk_add_f32 v[58:59], v[58:59], v[62:63]
	v_mul_f32_e32 v71, v70, v70
	v_mul_f32_e32 v73, v72, v72
	v_mul_f32_e32 v49, v48, v48
	v_mul_f32_e32 v51, v50, v50
	v_pk_add_f32 v[60:61], v[60:61], v[64:65]
	v_pk_add_f32 v[56:57], v[56:57], v[58:59]
	v_pk_add_f32 v[58:59], v[66:67], v[68:69]
	v_pk_add_f32 v[52:53], v[52:53], v[54:55]
	v_pk_add_f32 v[56:57], v[56:57], v[60:61]
	v_pk_add_f32 v[52:53], v[58:59], v[52:53]
	v_pk_add_f32 v[54:55], v[70:71], v[72:73]
	v_pk_add_f32 v[48:49], v[48:49], v[50:51]
	v_pk_add_f32 v[52:53], v[52:53], v[56:57]
	v_pk_add_f32 v[48:49], v[54:55], v[48:49]
	s_nop 0
	v_pk_add_f32 v[48:49], v[48:49], v[52:53]
	v_mov_b32_e32 v50, v48
	v_mov_b32_e32 v51, v49
	s_waitcnt lgkmcnt(0)
	s_nop 1
	v_permlane16_swap_b32_e32 v50, v48
	v_permlane16_swap_b32_e32 v51, v49
	v_pk_add_f32 v[48:49], v[48:49], v[50:51]
	ds_bpermute_b32 v50, v165, v48
	ds_bpermute_b32 v51, v165, v49
	s_and_saveexec_b64 s[30:31], s[2:3]
	s_cbranch_execz .LBB0_253
	s_lshl_b32 s9, s14, 2
	s_add_i32 s9, s9, -16
	v_mov_b32_e32 v132, s9
	v_lshl_add_u64 v[52:53], v[150:151], 4, v[132:133]
	v_or_b32_e32 v52, s59, v52
	v_lshl_add_u64 v[52:53], v[52:53], 3, s[18:19]
	s_waitcnt lgkmcnt(0)
	v_pk_add_f32 v[48:49], v[48:49], v[50:51]
	global_store_dwordx2 v[52:53], v[48:49], off

.LBB0_254:
	v_add_f32_e32 v48, v180, v181
	v_fmamk_f32 v48, v48, 0x3a800000, v175
	v_rsq_f32_e32 v54, v48
	v_lshlrev_b64 v[48:49], 11, v[148:149]
	v_lshl_add_u64 v[58:59], v[146:147], 0, v[48:49]
	s_and_b64 vcc, exec, s[6:7]
	v_pk_mul_f32 v[46:47], v[46:47], v[54:55] op_sel_hi:[1,0]
	v_pk_mul_f32 v[44:45], v[44:45], v[54:55] op_sel_hi:[1,0]
	s_waitcnt lgkmcnt(1)
	v_mul_f32_e32 v50, 0x3d372713, v46
	v_mul_f32_e32 v50, v46, v50
	v_fma_f32 v50, v46, v50, v46
	v_mul_f32_e32 v49, 0x3d372713, v45
	v_mul_f32_e32 v50, 0x3f4c422a, v50
	v_mul_f32_e32 v49, v45, v49
	v_mul_f32_e32 v50, 0xc038aa3b, v50
	v_pk_mul_f32 v[60:61], v[40:41], v[54:55] op_sel_hi:[1,0]
	v_fma_f32 v49, v45, v49, v45
	s_waitcnt lgkmcnt(0)
	v_exp_f32_e32 v51, v50
	v_mul_f32_e32 v50, 0x3d372713, v47
	v_mul_f32_e32 v40, 0x3d372713, v60
	v_mul_f32_e32 v49, 0x3f4c422a, v49
	v_mul_f32_e32 v50, v47, v50
	v_mul_f32_e32 v40, v60, v40
	v_mul_f32_e32 v41, 0x3d372713, v61
	v_mul_f32_e32 v49, 0xc038aa3b, v49
	v_fma_f32 v50, v47, v50, v47
	v_fma_f32 v40, v60, v40, v60
	v_mul_f32_e32 v41, v61, v41
	v_exp_f32_e32 v49, v49
	v_mul_f32_e32 v50, 0x3f4c422a, v50
	v_mul_f32_e32 v40, 0x3f4c422a, v40
	v_fma_f32 v41, v61, v41, v61
	v_mul_f32_e32 v50, 0xc038aa3b, v50
	v_mul_f32_e32 v40, 0xc038aa3b, v40
	v_mul_f32_e32 v41, 0x3f4c422a, v41
	v_exp_f32_e32 v53, v50
	v_exp_f32_e32 v40, v40
	v_mul_f32_e32 v41, 0xc038aa3b, v41
	v_exp_f32_e32 v41, v41
	v_add_f32_e32 v49, 1.0, v49
	v_rcp_f32_e32 v50, v49
	v_add_f32_e32 v49, 1.0, v51
	v_rcp_f32_e32 v52, v49
	v_add_f32_e32 v49, 1.0, v53
	v_add_f32_e32 v40, 1.0, v40
	v_rcp_f32_e32 v56, v49
	v_rcp_f32_e32 v49, v40
	v_add_f32_e32 v40, 1.0, v41
	v_rcp_f32_e32 v53, v40
	v_mul_f32_e32 v48, 0x3d372713, v44
	v_mul_f32_e32 v48, v44, v48
	v_pk_mul_f32 v[62:63], v[42:43], v[54:55] op_sel_hi:[1,0]
	v_mov_b32_e32 v41, v60
	v_pk_mov_b32 v[42:43], v[44:45], v[60:61] op_sel:[1,0]
	v_mov_b32_e32 v51, v49
	v_mov_b32_e32 v60, v46
	v_fma_f32 v48, v44, v48, v44
	v_mov_b32_e32 v40, v44
	v_pk_mul_f32 v[44:45], v[42:43], v[50:51]
	v_pk_mul_f32 v[42:43], v[60:61], v[52:53]
	v_mov_b32_e32 v60, v47
	v_mul_f32_e32 v46, 0x3d372713, v62
	v_mul_f32_e32 v47, 0x3d372713, v63
	v_mul_f32_e32 v46, v62, v46
	v_mul_f32_e32 v47, v63, v47
	v_mul_f32_e32 v48, 0x3f4c422a, v48
	v_fma_f32 v46, v62, v46, v62
	v_fma_f32 v47, v63, v47, v63
	v_mul_f32_e32 v48, 0xc038aa3b, v48
	v_mul_f32_e32 v46, 0x3f4c422a, v46
	v_mul_f32_e32 v47, 0x3f4c422a, v47
	v_exp_f32_e32 v48, v48
	v_mul_f32_e32 v46, 0xc038aa3b, v46
	v_mul_f32_e32 v47, 0xc038aa3b, v47
	v_exp_f32_e32 v46, v46
	v_exp_f32_e32 v47, v47
	v_add_f32_e32 v48, 1.0, v48
	v_rcp_f32_e32 v48, v48
	v_add_f32_e32 v46, 1.0, v46
	v_add_f32_e32 v47, 1.0, v47
	v_rcp_f32_e32 v46, v46
	v_rcp_f32_e32 v47, v47
	v_mov_b32_e32 v57, v53
	v_pk_mul_f32 v[40:41], v[40:41], v[48:49]
	v_pk_mul_f32 v[48:49], v[60:61], v[56:57]
	v_cvt_pk_bf16_f32 v232, v40, v44
	v_pk_mul_f32 v[38:39], v[38:39], v[54:55] op_sel_hi:[1,0]
	v_cvt_pk_bf16_f32 v233, v42, v48
	v_pk_mul_f32 v[46:47], v[62:63], v[46:47]
	v_cvt_pk_bf16_f32 v234, v41, v43
	v_pk_mul_f32 v[36:37], v[36:37], v[54:55] op_sel_hi:[1,0]
	v_cvt_pk_bf16_f32 v235, v46, v47
	v_mul_f32_e32 v52, 0x3d372713, v38
	s_nop 1
	v_permlane16_swap_b32_e32 v232, v234
	v_permlane16_swap_b32_e32 v233, v235
	v_lshl_add_u64 v[236:237], v[58:59], 0, v[238:239]
	global_store_dwordx4 v[236:237], v[232:235], off
	s_nop 1
	v_mul_f32_e32 v50, 0x3d372713, v36
	v_mul_f32_e32 v51, 0x3d372713, v37
	v_mul_f32_e32 v52, v38, v52
	v_mul_f32_e32 v53, 0x3d372713, v39
	v_mul_f32_e32 v50, v36, v50
	v_mul_f32_e32 v51, v37, v51
	v_fma_f32 v52, v38, v52, v38
	v_mul_f32_e32 v53, v39, v53
	v_fma_f32 v50, v36, v50, v36
	v_fma_f32 v51, v37, v51, v37
	v_mul_f32_e32 v52, 0x3f4c422a, v52
	v_fma_f32 v53, v39, v53, v39
	v_mul_f32_e32 v50, 0x3f4c422a, v50
	v_mul_f32_e32 v51, 0x3f4c422a, v51
	v_mul_f32_e32 v52, 0xc038aa3b, v52
	v_mul_f32_e32 v53, 0x3f4c422a, v53
	v_mul_f32_e32 v50, 0xc038aa3b, v50
	v_mul_f32_e32 v51, 0xc038aa3b, v51
	v_exp_f32_e32 v52, v52
	v_mul_f32_e32 v53, 0xc038aa3b, v53
	v_exp_f32_e32 v50, v50
	v_exp_f32_e32 v51, v51
	v_exp_f32_e32 v53, v53
	v_add_f32_e32 v52, 1.0, v52
	v_add_f32_e32 v50, 1.0, v50
	v_add_f32_e32 v51, 1.0, v51
	v_rcp_f32_e32 v55, v52
	v_add_f32_e32 v52, 1.0, v53
	v_rcp_f32_e32 v50, v50
	v_rcp_f32_e32 v51, v51
	v_rcp_f32_e32 v53, v52
	v_pk_mul_f32 v[32:33], v[32:33], v[54:55] op_sel_hi:[1,0]
	v_pk_mul_f32 v[34:35], v[34:35], v[54:55] op_sel_hi:[1,0]
	v_mul_f32_e32 v50, v36, v50
	v_mul_f32_e32 v52, v37, v51
	v_mul_f32_e32 v36, v38, v55
	v_mul_f32_e32 v38, v39, v53
	v_mul_f32_e32 v37, 0x3d372713, v32
	v_mul_f32_e32 v39, 0x3d372713, v33
	v_mul_f32_e32 v51, 0x3d372713, v34
	v_mul_f32_e32 v53, 0x3d372713, v35
	v_mul_f32_e32 v37, v32, v37
	v_mul_f32_e32 v39, v33, v39
	v_mul_f32_e32 v51, v34, v51
	v_mul_f32_e32 v53, v35, v53
	v_fma_f32 v37, v32, v37, v32
	v_fma_f32 v39, v33, v39, v33
	v_fma_f32 v51, v34, v51, v34
	v_fma_f32 v53, v35, v53, v35
	v_mul_f32_e32 v37, 0x3f4c422a, v37
	v_mul_f32_e32 v39, 0x3f4c422a, v39
	v_mul_f32_e32 v51, 0x3f4c422a, v51
	v_mul_f32_e32 v53, 0x3f4c422a, v53
	v_mul_f32_e32 v37, 0xc038aa3b, v37
	v_mul_f32_e32 v39, 0xc038aa3b, v39
	v_mul_f32_e32 v51, 0xc038aa3b, v51
	v_mul_f32_e32 v53, 0xc038aa3b, v53
	v_exp_f32_e32 v37, v37
	v_exp_f32_e32 v39, v39
	v_exp_f32_e32 v51, v51
	v_exp_f32_e32 v53, v53
	v_add_f32_e32 v37, 1.0, v37
	v_add_f32_e32 v39, 1.0, v39
	v_add_f32_e32 v51, 1.0, v51
	v_add_f32_e32 v53, 1.0, v53
	v_rcp_f32_e32 v37, v37
	v_rcp_f32_e32 v39, v39
	v_rcp_f32_e32 v51, v51
	v_rcp_f32_e32 v53, v53
	v_cvt_pk_bf16_f32 v232, v50, v52
	v_cvt_pk_bf16_f32 v233, v36, v38
	v_mul_f32_e32 v54, v32, v37
	v_mul_f32_e32 v56, v33, v39
	v_mul_f32_e32 v32, v34, v51
	v_mul_f32_e32 v34, v35, v53
	v_cvt_pk_bf16_f32 v234, v54, v56
	v_cvt_pk_bf16_f32 v235, v32, v34
	s_nop 1
	v_permlane16_swap_b32_e32 v232, v234
	v_permlane16_swap_b32_e32 v233, v235
	v_lshl_add_u64 v[236:237], v[58:59], 0, v[238:239]
	global_store_dwordx4 v[236:237], v[232:235], off offset:256
	s_nop 1
	s_cbranch_vccnz .LBB0_258
	v_pk_mul_f32 v[60:61], v[44:45], v[44:45]
	v_pk_add_f32 v[66:67], v[40:41], v[44:45]
	v_pk_mul_f32 v[44:45], v[40:41], v[44:45]
	v_pk_mul_f32 v[58:59], v[40:41], v[40:41]
	v_pk_mul_f32 v[64:65], v[48:49], v[48:49]
	v_mov_b32_e32 v67, v45
	v_pk_add_f32 v[44:45], v[42:43], v[48:49]
	v_pk_mul_f32 v[48:49], v[42:43], v[48:49]
	v_pk_mul_f32 v[62:63], v[42:43], v[42:43]
	v_mul_f32_e32 v48, v46, v46
	v_pk_mov_b32 v[40:41], v[40:41], v[58:59] op_sel:[1,0]
	v_pk_mov_b32 v[42:43], v[42:43], v[60:61] op_sel:[1,0]
	v_mov_b32_e32 v45, v49
	v_pk_fma_f32 v[48:49], v[46:47], v[46:47], v[48:49] op_sel_hi:[1,1,0]
	v_pk_add_f32 v[40:41], v[40:41], v[42:43]
	v_mov_b32_e32 v42, v46
	v_mov_b32_e32 v43, v62
	v_pk_mov_b32 v[46:47], v[46:47], v[64:65] op_sel:[1,0]
	v_mul_f32_e32 v51, v50, v50
	v_mul_f32_e32 v53, v52, v52
	v_mul_f32_e32 v37, v36, v36
	v_mul_f32_e32 v39, v38, v38
	v_pk_add_f32 v[44:45], v[66:67], v[44:45]
	v_mov_b32_e32 v48, v133
	v_pk_add_f32 v[42:43], v[42:43], v[46:47]
	v_mul_f32_e32 v55, v54, v54
	v_mul_f32_e32 v57, v56, v56
	v_mul_f32_e32 v33, v32, v32
	v_mul_f32_e32 v35, v34, v34
	v_pk_add_f32 v[44:45], v[44:45], v[48:49]
	v_pk_add_f32 v[40:41], v[40:41], v[42:43]
	v_pk_add_f32 v[42:43], v[50:51], v[52:53]
	v_pk_add_f32 v[36:37], v[36:37], v[38:39]
	v_pk_add_f32 v[40:41], v[40:41], v[44:45]
	v_pk_add_f32 v[36:37], v[42:43], v[36:37]
	v_pk_add_f32 v[38:39], v[54:55], v[56:57]
	v_pk_add_f32 v[32:33], v[32:33], v[34:35]
	v_pk_add_f32 v[36:37], v[36:37], v[40:41]
	v_pk_add_f32 v[32:33], v[38:39], v[32:33]
	s_nop 0
	v_pk_add_f32 v[32:33], v[32:33], v[36:37]
	v_mov_b32_e32 v34, v32
	v_mov_b32_e32 v35, v33
	s_waitcnt lgkmcnt(0)
	s_nop 1
	v_permlane16_swap_b32_e32 v34, v32
	v_permlane16_swap_b32_e32 v35, v33
	v_pk_add_f32 v[32:33], v[32:33], v[34:35]
	ds_bpermute_b32 v34, v165, v32
	ds_bpermute_b32 v35, v165, v33
	s_and_saveexec_b64 s[30:31], s[2:3]
	s_cbranch_execz .LBB0_257
	s_lshl_b32 s9, s14, 2
	s_add_i32 s9, s9, -16
	v_mov_b32_e32 v132, s9
	v_lshl_add_u64 v[36:37], v[148:149], 4, v[132:133]
	v_or_b32_e32 v36, s59, v36
	v_lshl_add_u64 v[36:37], v[36:37], 3, s[18:19]
	s_waitcnt lgkmcnt(0)
	v_pk_add_f32 v[32:33], v[32:33], v[34:35]
	global_store_dwordx2 v[36:37], v[32:33], off

.LBB0_258:
	v_add_f32_e32 v32, v178, v179
	v_fmamk_f32 v32, v32, 0x3a800000, v175
	v_rsq_f32_e32 v38, v32
	v_lshlrev_b64 v[32:33], 11, v[144:145]
	v_lshl_add_u64 v[42:43], v[146:147], 0, v[32:33]
	s_and_b64 vcc, exec, s[6:7]
	v_pk_mul_f32 v[30:31], v[30:31], v[38:39] op_sel_hi:[1,0]
	v_pk_mul_f32 v[28:29], v[28:29], v[38:39] op_sel_hi:[1,0]
	s_waitcnt lgkmcnt(1)
	v_mul_f32_e32 v34, 0x3d372713, v30
	v_mul_f32_e32 v34, v30, v34
	v_fma_f32 v34, v30, v34, v30
	v_mul_f32_e32 v33, 0x3d372713, v29
	v_mul_f32_e32 v34, 0x3f4c422a, v34
	v_mul_f32_e32 v33, v29, v33
	v_mul_f32_e32 v34, 0xc038aa3b, v34
	v_pk_mul_f32 v[44:45], v[24:25], v[38:39] op_sel_hi:[1,0]
	v_fma_f32 v33, v29, v33, v29
	s_waitcnt lgkmcnt(0)
	v_exp_f32_e32 v35, v34
	v_mul_f32_e32 v34, 0x3d372713, v31
	v_mul_f32_e32 v24, 0x3d372713, v44
	v_mul_f32_e32 v33, 0x3f4c422a, v33
	v_mul_f32_e32 v34, v31, v34
	v_mul_f32_e32 v24, v44, v24
	v_mul_f32_e32 v25, 0x3d372713, v45
	v_mul_f32_e32 v33, 0xc038aa3b, v33
	v_fma_f32 v34, v31, v34, v31
	v_fma_f32 v24, v44, v24, v44
	v_mul_f32_e32 v25, v45, v25
	v_exp_f32_e32 v33, v33
	v_mul_f32_e32 v34, 0x3f4c422a, v34
	v_mul_f32_e32 v24, 0x3f4c422a, v24
	v_fma_f32 v25, v45, v25, v45
	v_mul_f32_e32 v34, 0xc038aa3b, v34
	v_mul_f32_e32 v24, 0xc038aa3b, v24
	v_mul_f32_e32 v25, 0x3f4c422a, v25
	v_exp_f32_e32 v37, v34
	v_exp_f32_e32 v24, v24
	v_mul_f32_e32 v25, 0xc038aa3b, v25
	v_exp_f32_e32 v25, v25
	v_add_f32_e32 v33, 1.0, v33
	v_rcp_f32_e32 v34, v33
	v_add_f32_e32 v33, 1.0, v35
	v_rcp_f32_e32 v36, v33
	v_add_f32_e32 v33, 1.0, v37
	v_add_f32_e32 v24, 1.0, v24
	v_rcp_f32_e32 v40, v33
	v_rcp_f32_e32 v33, v24
	v_add_f32_e32 v24, 1.0, v25
	v_rcp_f32_e32 v37, v24
	v_mul_f32_e32 v32, 0x3d372713, v28
	v_mul_f32_e32 v32, v28, v32
	v_pk_mul_f32 v[46:47], v[26:27], v[38:39] op_sel_hi:[1,0]
	v_mov_b32_e32 v25, v44
	v_pk_mov_b32 v[26:27], v[28:29], v[44:45] op_sel:[1,0]
	v_mov_b32_e32 v35, v33
	v_mov_b32_e32 v44, v30
	v_fma_f32 v32, v28, v32, v28
	v_mov_b32_e32 v24, v28
	v_pk_mul_f32 v[28:29], v[26:27], v[34:35]
	v_pk_mul_f32 v[26:27], v[44:45], v[36:37]
	v_mov_b32_e32 v44, v31
	v_mul_f32_e32 v30, 0x3d372713, v46
	v_mul_f32_e32 v31, 0x3d372713, v47
	v_mul_f32_e32 v30, v46, v30
	v_mul_f32_e32 v31, v47, v31
	v_mul_f32_e32 v32, 0x3f4c422a, v32
	v_fma_f32 v30, v46, v30, v46
	v_fma_f32 v31, v47, v31, v47
	v_mul_f32_e32 v32, 0xc038aa3b, v32
	v_mul_f32_e32 v30, 0x3f4c422a, v30
	v_mul_f32_e32 v31, 0x3f4c422a, v31
	v_exp_f32_e32 v32, v32
	v_mul_f32_e32 v30, 0xc038aa3b, v30
	v_mul_f32_e32 v31, 0xc038aa3b, v31
	v_exp_f32_e32 v30, v30
	v_exp_f32_e32 v31, v31
	v_add_f32_e32 v32, 1.0, v32
	v_rcp_f32_e32 v32, v32
	v_add_f32_e32 v30, 1.0, v30
	v_add_f32_e32 v31, 1.0, v31
	v_rcp_f32_e32 v30, v30
	v_rcp_f32_e32 v31, v31
	v_mov_b32_e32 v41, v37
	v_pk_mul_f32 v[24:25], v[24:25], v[32:33]
	v_pk_mul_f32 v[32:33], v[44:45], v[40:41]
	v_cvt_pk_bf16_f32 v232, v24, v28
	v_pk_mul_f32 v[22:23], v[22:23], v[38:39] op_sel_hi:[1,0]
	v_cvt_pk_bf16_f32 v233, v26, v32
	v_pk_mul_f32 v[30:31], v[46:47], v[30:31]
	v_cvt_pk_bf16_f32 v234, v25, v27
	v_pk_mul_f32 v[20:21], v[20:21], v[38:39] op_sel_hi:[1,0]
	v_cvt_pk_bf16_f32 v235, v30, v31
	v_mul_f32_e32 v36, 0x3d372713, v22
	s_nop 1
	v_permlane16_swap_b32_e32 v232, v234
	v_permlane16_swap_b32_e32 v233, v235
	v_lshl_add_u64 v[236:237], v[42:43], 0, v[238:239]
	global_store_dwordx4 v[236:237], v[232:235], off
	s_nop 1
	v_mul_f32_e32 v34, 0x3d372713, v20
	v_mul_f32_e32 v35, 0x3d372713, v21
	v_mul_f32_e32 v36, v22, v36
	v_mul_f32_e32 v37, 0x3d372713, v23
	v_mul_f32_e32 v34, v20, v34
	v_mul_f32_e32 v35, v21, v35
	v_fma_f32 v36, v22, v36, v22
	v_mul_f32_e32 v37, v23, v37
	v_fma_f32 v34, v20, v34, v20
	v_fma_f32 v35, v21, v35, v21
	v_mul_f32_e32 v36, 0x3f4c422a, v36
	v_fma_f32 v37, v23, v37, v23
	v_mul_f32_e32 v34, 0x3f4c422a, v34
	v_mul_f32_e32 v35, 0x3f4c422a, v35
	v_mul_f32_e32 v36, 0xc038aa3b, v36
	v_mul_f32_e32 v37, 0x3f4c422a, v37
	v_mul_f32_e32 v34, 0xc038aa3b, v34
	v_mul_f32_e32 v35, 0xc038aa3b, v35
	v_exp_f32_e32 v36, v36
	v_mul_f32_e32 v37, 0xc038aa3b, v37
	v_exp_f32_e32 v34, v34
	v_exp_f32_e32 v35, v35
	v_exp_f32_e32 v37, v37
	v_add_f32_e32 v36, 1.0, v36
	v_add_f32_e32 v34, 1.0, v34
	v_add_f32_e32 v35, 1.0, v35
	v_rcp_f32_e32 v39, v36
	v_add_f32_e32 v36, 1.0, v37
	v_rcp_f32_e32 v34, v34
	v_rcp_f32_e32 v35, v35
	v_rcp_f32_e32 v37, v36
	v_pk_mul_f32 v[16:17], v[16:17], v[38:39] op_sel_hi:[1,0]
	v_pk_mul_f32 v[18:19], v[18:19], v[38:39] op_sel_hi:[1,0]
	v_mul_f32_e32 v34, v20, v34
	v_mul_f32_e32 v36, v21, v35
	v_mul_f32_e32 v20, v22, v39
	v_mul_f32_e32 v22, v23, v37
	v_mul_f32_e32 v21, 0x3d372713, v16
	v_mul_f32_e32 v23, 0x3d372713, v17
	v_mul_f32_e32 v35, 0x3d372713, v18
	v_mul_f32_e32 v37, 0x3d372713, v19
	v_mul_f32_e32 v21, v16, v21
	v_mul_f32_e32 v23, v17, v23
	v_mul_f32_e32 v35, v18, v35
	v_mul_f32_e32 v37, v19, v37
	v_fma_f32 v21, v16, v21, v16
	v_fma_f32 v23, v17, v23, v17
	v_fma_f32 v35, v18, v35, v18
	v_fma_f32 v37, v19, v37, v19
	v_mul_f32_e32 v21, 0x3f4c422a, v21
	v_mul_f32_e32 v23, 0x3f4c422a, v23
	v_mul_f32_e32 v35, 0x3f4c422a, v35
	v_mul_f32_e32 v37, 0x3f4c422a, v37
	v_mul_f32_e32 v21, 0xc038aa3b, v21
	v_mul_f32_e32 v23, 0xc038aa3b, v23
	v_mul_f32_e32 v35, 0xc038aa3b, v35
	v_mul_f32_e32 v37, 0xc038aa3b, v37
	v_exp_f32_e32 v21, v21
	v_exp_f32_e32 v23, v23
	v_exp_f32_e32 v35, v35
	v_exp_f32_e32 v37, v37
	v_add_f32_e32 v21, 1.0, v21
	v_add_f32_e32 v23, 1.0, v23
	v_add_f32_e32 v35, 1.0, v35
	v_add_f32_e32 v37, 1.0, v37
	v_rcp_f32_e32 v21, v21
	v_rcp_f32_e32 v23, v23
	v_rcp_f32_e32 v35, v35
	v_rcp_f32_e32 v37, v37
	v_cvt_pk_bf16_f32 v232, v34, v36
	v_cvt_pk_bf16_f32 v233, v20, v22
	v_mul_f32_e32 v38, v16, v21
	v_mul_f32_e32 v40, v17, v23
	v_mul_f32_e32 v16, v18, v35
	v_mul_f32_e32 v18, v19, v37
	v_cvt_pk_bf16_f32 v234, v38, v40
	v_cvt_pk_bf16_f32 v235, v16, v18
	s_nop 1
	v_permlane16_swap_b32_e32 v232, v234
	v_permlane16_swap_b32_e32 v233, v235
	v_lshl_add_u64 v[236:237], v[42:43], 0, v[238:239]
	global_store_dwordx4 v[236:237], v[232:235], off offset:256
	s_nop 1
	s_cbranch_vccnz .LBB0_262
	v_pk_mul_f32 v[44:45], v[28:29], v[28:29]
	v_pk_add_f32 v[50:51], v[24:25], v[28:29]
	v_pk_mul_f32 v[28:29], v[24:25], v[28:29]
	v_pk_mul_f32 v[42:43], v[24:25], v[24:25]
	v_pk_mul_f32 v[48:49], v[32:33], v[32:33]
	v_mov_b32_e32 v51, v29
	v_pk_add_f32 v[28:29], v[26:27], v[32:33]
	v_pk_mul_f32 v[32:33], v[26:27], v[32:33]
	v_pk_mul_f32 v[46:47], v[26:27], v[26:27]
	v_mul_f32_e32 v32, v30, v30
	v_pk_mov_b32 v[24:25], v[24:25], v[42:43] op_sel:[1,0]
	v_pk_mov_b32 v[26:27], v[26:27], v[44:45] op_sel:[1,0]
	v_mov_b32_e32 v29, v33
	v_pk_fma_f32 v[32:33], v[30:31], v[30:31], v[32:33] op_sel_hi:[1,1,0]
	v_pk_add_f32 v[24:25], v[24:25], v[26:27]
	v_mov_b32_e32 v26, v30
	v_mov_b32_e32 v27, v46
	v_pk_mov_b32 v[30:31], v[30:31], v[48:49] op_sel:[1,0]
	v_mul_f32_e32 v35, v34, v34
	v_mul_f32_e32 v37, v36, v36
	v_mul_f32_e32 v21, v20, v20
	v_mul_f32_e32 v23, v22, v22
	v_pk_add_f32 v[28:29], v[50:51], v[28:29]
	v_mov_b32_e32 v32, v133
	v_pk_add_f32 v[26:27], v[26:27], v[30:31]
	v_mul_f32_e32 v39, v38, v38
	v_mul_f32_e32 v41, v40, v40
	v_mul_f32_e32 v17, v16, v16
	v_mul_f32_e32 v19, v18, v18
	v_pk_add_f32 v[28:29], v[28:29], v[32:33]
	v_pk_add_f32 v[24:25], v[24:25], v[26:27]
	v_pk_add_f32 v[26:27], v[34:35], v[36:37]
	v_pk_add_f32 v[20:21], v[20:21], v[22:23]
	v_pk_add_f32 v[24:25], v[24:25], v[28:29]
	v_pk_add_f32 v[20:21], v[26:27], v[20:21]
	v_pk_add_f32 v[22:23], v[38:39], v[40:41]
	v_pk_add_f32 v[16:17], v[16:17], v[18:19]
	v_pk_add_f32 v[20:21], v[20:21], v[24:25]
	v_pk_add_f32 v[16:17], v[22:23], v[16:17]
	s_nop 0
	v_pk_add_f32 v[16:17], v[16:17], v[20:21]
	v_mov_b32_e32 v18, v16
	v_mov_b32_e32 v19, v17
	s_waitcnt lgkmcnt(0)
	s_nop 1
	v_permlane16_swap_b32_e32 v18, v16
	v_permlane16_swap_b32_e32 v19, v17
	v_pk_add_f32 v[16:17], v[16:17], v[18:19]
	ds_bpermute_b32 v18, v165, v16
	ds_bpermute_b32 v19, v165, v17
	s_and_saveexec_b64 s[30:31], s[2:3]
	s_cbranch_execz .LBB0_261
	s_lshl_b32 s9, s14, 2
	s_add_i32 s9, s9, -16
	v_mov_b32_e32 v132, s9
	v_lshl_add_u64 v[20:21], v[144:145], 4, v[132:133]
	v_or_b32_e32 v20, s59, v20
	v_lshl_add_u64 v[20:21], v[20:21], 3, s[18:19]
	s_waitcnt lgkmcnt(0)
	v_pk_add_f32 v[16:17], v[16:17], v[18:19]
	global_store_dwordx2 v[20:21], v[16:17], off

.LBB0_262:
	v_add_f32_e32 v16, v176, v177
	v_fmamk_f32 v16, v16, 0x3a800000, v175
	v_rsq_f32_e32 v22, v16
	v_lshlrev_b64 v[16:17], 11, v[142:143]
	v_lshl_add_u64 v[26:27], v[146:147], 0, v[16:17]
	s_and_b64 vcc, exec, s[6:7]
	v_pk_mul_f32 v[14:15], v[14:15], v[22:23] op_sel_hi:[1,0]
	v_pk_mul_f32 v[12:13], v[12:13], v[22:23] op_sel_hi:[1,0]
	s_waitcnt lgkmcnt(1)
	v_mul_f32_e32 v18, 0x3d372713, v14
	v_mul_f32_e32 v18, v14, v18
	v_fma_f32 v18, v14, v18, v14
	v_mul_f32_e32 v17, 0x3d372713, v13
	v_mul_f32_e32 v18, 0x3f4c422a, v18
	v_mul_f32_e32 v17, v13, v17
	v_mul_f32_e32 v18, 0xc038aa3b, v18
	v_pk_mul_f32 v[28:29], v[8:9], v[22:23] op_sel_hi:[1,0]
	v_fma_f32 v17, v13, v17, v13
	s_waitcnt lgkmcnt(0)
	v_exp_f32_e32 v19, v18
	v_mul_f32_e32 v18, 0x3d372713, v15
	v_mul_f32_e32 v8, 0x3d372713, v28
	v_mul_f32_e32 v17, 0x3f4c422a, v17
	v_mul_f32_e32 v18, v15, v18
	v_mul_f32_e32 v8, v28, v8
	v_mul_f32_e32 v9, 0x3d372713, v29
	v_mul_f32_e32 v17, 0xc038aa3b, v17
	v_fma_f32 v18, v15, v18, v15
	v_fma_f32 v8, v28, v8, v28
	v_mul_f32_e32 v9, v29, v9
	v_exp_f32_e32 v17, v17
	v_mul_f32_e32 v18, 0x3f4c422a, v18
	v_mul_f32_e32 v8, 0x3f4c422a, v8
	v_fma_f32 v9, v29, v9, v29
	v_mul_f32_e32 v18, 0xc038aa3b, v18
	v_mul_f32_e32 v8, 0xc038aa3b, v8
	v_mul_f32_e32 v9, 0x3f4c422a, v9
	v_exp_f32_e32 v21, v18
	v_exp_f32_e32 v8, v8
	v_mul_f32_e32 v9, 0xc038aa3b, v9
	v_exp_f32_e32 v9, v9
	v_add_f32_e32 v17, 1.0, v17
	v_rcp_f32_e32 v18, v17
	v_add_f32_e32 v17, 1.0, v19
	v_rcp_f32_e32 v20, v17
	v_add_f32_e32 v17, 1.0, v21
	v_add_f32_e32 v8, 1.0, v8
	v_rcp_f32_e32 v24, v17
	v_rcp_f32_e32 v17, v8
	v_add_f32_e32 v8, 1.0, v9
	v_rcp_f32_e32 v21, v8
	v_mul_f32_e32 v16, 0x3d372713, v12
	v_mul_f32_e32 v16, v12, v16
	v_pk_mul_f32 v[30:31], v[10:11], v[22:23] op_sel_hi:[1,0]
	v_mov_b32_e32 v9, v28
	v_pk_mov_b32 v[10:11], v[12:13], v[28:29] op_sel:[1,0]
	v_mov_b32_e32 v19, v17
	v_mov_b32_e32 v28, v14
	v_fma_f32 v16, v12, v16, v12
	v_mov_b32_e32 v8, v12
	v_pk_mul_f32 v[12:13], v[10:11], v[18:19]
	v_pk_mul_f32 v[10:11], v[28:29], v[20:21]
	v_mov_b32_e32 v28, v15
	v_mul_f32_e32 v14, 0x3d372713, v30
	v_mul_f32_e32 v15, 0x3d372713, v31
	v_mul_f32_e32 v14, v30, v14
	v_mul_f32_e32 v15, v31, v15
	v_mul_f32_e32 v16, 0x3f4c422a, v16
	v_fma_f32 v14, v30, v14, v30
	v_fma_f32 v15, v31, v15, v31
	v_mul_f32_e32 v16, 0xc038aa3b, v16
	v_mul_f32_e32 v14, 0x3f4c422a, v14
	v_mul_f32_e32 v15, 0x3f4c422a, v15
	v_exp_f32_e32 v16, v16
	v_mul_f32_e32 v14, 0xc038aa3b, v14
	v_mul_f32_e32 v15, 0xc038aa3b, v15
	v_exp_f32_e32 v14, v14
	v_exp_f32_e32 v15, v15
	v_add_f32_e32 v16, 1.0, v16
	v_rcp_f32_e32 v16, v16
	v_add_f32_e32 v14, 1.0, v14
	v_add_f32_e32 v15, 1.0, v15
	v_rcp_f32_e32 v14, v14
	v_rcp_f32_e32 v15, v15
	v_mov_b32_e32 v25, v21
	v_pk_mul_f32 v[8:9], v[8:9], v[16:17]
	v_pk_mul_f32 v[16:17], v[28:29], v[24:25]
	v_cvt_pk_bf16_f32 v232, v8, v12
	v_pk_mul_f32 v[6:7], v[6:7], v[22:23] op_sel_hi:[1,0]
	v_cvt_pk_bf16_f32 v233, v10, v16
	v_pk_mul_f32 v[14:15], v[30:31], v[14:15]
	v_cvt_pk_bf16_f32 v234, v9, v11
	v_pk_mul_f32 v[4:5], v[4:5], v[22:23] op_sel_hi:[1,0]
	v_cvt_pk_bf16_f32 v235, v14, v15
	v_mul_f32_e32 v20, 0x3d372713, v6
	s_nop 1
	v_permlane16_swap_b32_e32 v232, v234
	v_permlane16_swap_b32_e32 v233, v235
	v_lshl_add_u64 v[236:237], v[26:27], 0, v[238:239]
	global_store_dwordx4 v[236:237], v[232:235], off
	s_nop 1
	v_mul_f32_e32 v18, 0x3d372713, v4
	v_mul_f32_e32 v19, 0x3d372713, v5
	v_mul_f32_e32 v20, v6, v20
	v_mul_f32_e32 v21, 0x3d372713, v7
	v_mul_f32_e32 v18, v4, v18
	v_mul_f32_e32 v19, v5, v19
	v_fma_f32 v20, v6, v20, v6
	v_mul_f32_e32 v21, v7, v21
	v_fma_f32 v18, v4, v18, v4
	v_fma_f32 v19, v5, v19, v5
	v_mul_f32_e32 v20, 0x3f4c422a, v20
	v_fma_f32 v21, v7, v21, v7
	v_mul_f32_e32 v18, 0x3f4c422a, v18
	v_mul_f32_e32 v19, 0x3f4c422a, v19
	v_mul_f32_e32 v20, 0xc038aa3b, v20
	v_mul_f32_e32 v21, 0x3f4c422a, v21
	v_mul_f32_e32 v18, 0xc038aa3b, v18
	v_mul_f32_e32 v19, 0xc038aa3b, v19
	v_exp_f32_e32 v20, v20
	v_mul_f32_e32 v21, 0xc038aa3b, v21
	v_exp_f32_e32 v18, v18
	v_exp_f32_e32 v19, v19
	v_exp_f32_e32 v21, v21
	v_add_f32_e32 v20, 1.0, v20
	v_add_f32_e32 v18, 1.0, v18
	v_add_f32_e32 v19, 1.0, v19
	v_rcp_f32_e32 v23, v20
	v_add_f32_e32 v20, 1.0, v21
	v_rcp_f32_e32 v18, v18
	v_rcp_f32_e32 v19, v19
	v_rcp_f32_e32 v21, v20
	v_pk_mul_f32 v[0:1], v[0:1], v[22:23] op_sel_hi:[1,0]
	v_pk_mul_f32 v[2:3], v[2:3], v[22:23] op_sel_hi:[1,0]
	v_mul_f32_e32 v18, v4, v18
	v_mul_f32_e32 v20, v5, v19
	v_mul_f32_e32 v4, v6, v23
	v_mul_f32_e32 v6, v7, v21
	v_mul_f32_e32 v5, 0x3d372713, v0
	v_mul_f32_e32 v7, 0x3d372713, v1
	v_mul_f32_e32 v19, 0x3d372713, v2
	v_mul_f32_e32 v21, 0x3d372713, v3
	v_mul_f32_e32 v5, v0, v5
	v_mul_f32_e32 v7, v1, v7
	v_mul_f32_e32 v19, v2, v19
	v_mul_f32_e32 v21, v3, v21
	v_fma_f32 v5, v0, v5, v0
	v_fma_f32 v7, v1, v7, v1
	v_fma_f32 v19, v2, v19, v2
	v_fma_f32 v21, v3, v21, v3
	v_mul_f32_e32 v5, 0x3f4c422a, v5
	v_mul_f32_e32 v7, 0x3f4c422a, v7
	v_mul_f32_e32 v19, 0x3f4c422a, v19
	v_mul_f32_e32 v21, 0x3f4c422a, v21
	v_mul_f32_e32 v5, 0xc038aa3b, v5
	v_mul_f32_e32 v7, 0xc038aa3b, v7
	v_mul_f32_e32 v19, 0xc038aa3b, v19
	v_mul_f32_e32 v21, 0xc038aa3b, v21
	v_exp_f32_e32 v5, v5
	v_exp_f32_e32 v7, v7
	v_exp_f32_e32 v19, v19
	v_exp_f32_e32 v21, v21
	v_add_f32_e32 v5, 1.0, v5
	v_add_f32_e32 v7, 1.0, v7
	v_add_f32_e32 v19, 1.0, v19
	v_add_f32_e32 v21, 1.0, v21
	v_rcp_f32_e32 v5, v5
	v_rcp_f32_e32 v7, v7
	v_rcp_f32_e32 v19, v19
	v_rcp_f32_e32 v21, v21
	v_cvt_pk_bf16_f32 v232, v18, v20
	v_cvt_pk_bf16_f32 v233, v4, v6
	v_mul_f32_e32 v22, v0, v5
	v_mul_f32_e32 v24, v1, v7
	v_mul_f32_e32 v0, v2, v19
	v_mul_f32_e32 v2, v3, v21
	v_cvt_pk_bf16_f32 v234, v22, v24
	v_cvt_pk_bf16_f32 v235, v0, v2
	s_nop 1
	v_permlane16_swap_b32_e32 v232, v234
	v_permlane16_swap_b32_e32 v233, v235
	v_lshl_add_u64 v[236:237], v[26:27], 0, v[238:239]
	global_store_dwordx4 v[236:237], v[232:235], off offset:256
	s_nop 1
	s_cbranch_vccnz .LBB0_266
	v_pk_mul_f32 v[28:29], v[12:13], v[12:13]
	v_pk_add_f32 v[34:35], v[8:9], v[12:13]
	v_pk_mul_f32 v[12:13], v[8:9], v[12:13]
	v_pk_mul_f32 v[26:27], v[8:9], v[8:9]
	v_pk_mul_f32 v[32:33], v[16:17], v[16:17]
	v_mov_b32_e32 v35, v13
	v_pk_add_f32 v[12:13], v[10:11], v[16:17]
	v_pk_mul_f32 v[16:17], v[10:11], v[16:17]
	v_pk_mul_f32 v[30:31], v[10:11], v[10:11]
	v_mul_f32_e32 v16, v14, v14
	v_pk_mov_b32 v[8:9], v[8:9], v[26:27] op_sel:[1,0]
	v_pk_mov_b32 v[10:11], v[10:11], v[28:29] op_sel:[1,0]
	v_mov_b32_e32 v13, v17
	v_pk_fma_f32 v[16:17], v[14:15], v[14:15], v[16:17] op_sel_hi:[1,1,0]
	v_pk_add_f32 v[8:9], v[8:9], v[10:11]
	v_mov_b32_e32 v10, v14
	v_mov_b32_e32 v11, v30
	v_pk_mov_b32 v[14:15], v[14:15], v[32:33] op_sel:[1,0]
	v_mul_f32_e32 v19, v18, v18
	v_mul_f32_e32 v21, v20, v20
	v_mul_f32_e32 v5, v4, v4
	v_mul_f32_e32 v7, v6, v6
	v_pk_add_f32 v[12:13], v[34:35], v[12:13]
	v_mov_b32_e32 v16, v133
	v_pk_add_f32 v[10:11], v[10:11], v[14:15]
	v_mul_f32_e32 v23, v22, v22
	v_mul_f32_e32 v25, v24, v24
	v_mul_f32_e32 v1, v0, v0
	v_mul_f32_e32 v3, v2, v2
	v_pk_add_f32 v[12:13], v[12:13], v[16:17]
	v_pk_add_f32 v[8:9], v[8:9], v[10:11]
	v_pk_add_f32 v[10:11], v[18:19], v[20:21]
	v_pk_add_f32 v[4:5], v[4:5], v[6:7]
	v_pk_add_f32 v[8:9], v[8:9], v[12:13]
	v_pk_add_f32 v[4:5], v[10:11], v[4:5]
	v_pk_add_f32 v[6:7], v[22:23], v[24:25]
	v_pk_add_f32 v[0:1], v[0:1], v[2:3]
	v_pk_add_f32 v[4:5], v[4:5], v[8:9]
	v_pk_add_f32 v[0:1], v[6:7], v[0:1]
	s_nop 0
	v_pk_add_f32 v[0:1], v[0:1], v[4:5]
	v_mov_b32_e32 v2, v0
	v_mov_b32_e32 v3, v1
	s_waitcnt lgkmcnt(0)
	s_nop 1
	v_permlane16_swap_b32_e32 v2, v0
	v_permlane16_swap_b32_e32 v3, v1
	v_pk_add_f32 v[0:1], v[0:1], v[2:3]
	ds_bpermute_b32 v2, v165, v0
	ds_bpermute_b32 v3, v165, v1
	s_and_saveexec_b64 s[6:7], s[2:3]
	s_cbranch_execz .LBB0_265
	s_lshl_b32 s9, s14, 2
	s_add_i32 s9, s9, -16
	v_mov_b32_e32 v132, s9
	v_lshl_add_u64 v[4:5], v[142:143], 4, v[132:133]
	v_or_b32_e32 v4, s59, v4
	v_lshl_add_u64 v[4:5], v[4:5], 3, s[18:19]
	s_waitcnt lgkmcnt(0)
	v_pk_add_f32 v[0:1], v[0:1], v[2:3]
	global_store_dwordx2 v[4:5], v[0:1], off

.LBB0_442:
	v_lshl_add_u32 v170, s28, 8, v178
	v_lshl_or_b32 v160, s8, 8, v180
	v_ashrrev_i32_e32 v171, 31, v170
	v_lshlrev_b64 v[192:193], 11, v[170:171]
	v_ashrrev_i32_e32 v161, 31, v160
	v_lshl_add_u64 v[128:129], s[42:43], 0, v[192:193]
	v_lshlrev_b64 v[162:163], 1, v[160:161]
	v_lshl_add_u64 v[164:165], v[128:129], 0, v[162:163]
	global_load_dwordx4 v[184:187], v[164:165], off
	global_load_dwordx4 v[188:191], v[164:165], off offset:256
	v_or_b32_e32 v172, 16, v170
	v_or_b32_e32 v166, 32, v170
	v_ashrrev_i32_e32 v173, 31, v172
	v_ashrrev_i32_e32 v167, 31, v166
	v_lshlrev_b64 v[174:175], 11, v[172:173]
	v_lshlrev_b64 v[168:169], 11, v[166:167]
	v_lshl_add_u64 v[128:129], s[42:43], 0, v[174:175]
	v_lshl_add_u64 v[130:131], s[42:43], 0, v[168:169]
	v_lshl_add_u64 v[128:129], v[128:129], 0, v[162:163]
	v_lshl_add_u64 v[130:131], v[130:131], 0, v[162:163]
	global_load_dwordx4 v[140:143], v[128:129], off
	global_load_dwordx4 v[136:139], v[128:129], off offset:256
	global_load_dwordx4 v[132:135], v[130:131], off
	s_nop 0
	global_load_dwordx4 v[128:131], v[130:131], off offset:256
	s_lshl_b32 s28, s8, 2
	s_ashr_i32 s29, s28, 31
	s_waitcnt vmcnt(0)
	v_lshlrev_b32_e32 v194, 16, v184
	v_and_b32_e32 v195, 0xffff0000, v184
	v_lshlrev_b32_e32 v184, 16, v185
	v_and_b32_e32 v185, 0xffff0000, v185
	v_lshlrev_b32_e32 v196, 16, v186
	v_and_b32_e32 v197, 0xffff0000, v186
	v_lshlrev_b32_e32 v186, 16, v187
	v_and_b32_e32 v187, 0xffff0000, v187
	v_lshlrev_b32_e32 v198, 16, v188
	v_and_b32_e32 v199, 0xffff0000, v188
	v_lshlrev_b32_e32 v188, 16, v189
	v_and_b32_e32 v189, 0xffff0000, v189
	v_lshlrev_b32_e32 v200, 16, v190
	v_and_b32_e32 v201, 0xffff0000, v190
	v_lshlrev_b32_e32 v190, 16, v191
	v_and_b32_e32 v191, 0xffff0000, v191
	v_pk_add_f32 v[126:127], v[126:127], v[184:185]
	v_pk_add_f32 v[124:125], v[124:125], v[194:195]
	v_pk_add_f32 v[122:123], v[122:123], v[186:187]
	v_pk_add_f32 v[120:121], v[120:121], v[196:197]
	v_pk_add_f32 v[118:119], v[118:119], v[188:189]
	v_pk_add_f32 v[116:117], v[116:117], v[198:199]
	v_pk_add_f32 v[184:185], v[114:115], v[190:191]
	v_pk_add_f32 v[186:187], v[112:113], v[200:201]
	v_cvt_pk_bf16_f32 v112, v124, v125
	v_cvt_pk_bf16_f32 v113, v126, v127
	v_cvt_pk_bf16_f32 v114, v120, v121
	v_cvt_pk_bf16_f32 v115, v122, v123
	v_mul_f32_e32 v125, v125, v125
	v_mul_f32_e32 v127, v127, v127
	v_mul_f32_e32 v121, v121, v121
	v_mul_f32_e32 v123, v123, v123
	v_mul_f32_e32 v188, v117, v117
	v_mul_f32_e32 v189, v119, v119
	v_mul_f32_e32 v190, v187, v187
	v_mul_f32_e32 v191, v185, v185
	v_fmac_f32_e32 v125, v124, v124
	v_fmac_f32_e32 v127, v126, v126
	v_fmac_f32_e32 v121, v120, v120
	v_fmac_f32_e32 v123, v122, v122
	v_fmac_f32_e32 v188, v116, v116
	v_fmac_f32_e32 v189, v118, v118
	v_fmac_f32_e32 v190, v186, v186
	v_fmac_f32_e32 v191, v184, v184
	v_add_f32_e32 v120, v125, v127
	v_add_f32_e32 v121, v121, v123
	v_add_f32_e32 v122, v188, v189
	v_add_f32_e32 v123, v190, v191
	v_add_f32_e32 v120, v120, v121
	v_add_f32_e32 v121, v122, v123
	v_add_f32_e32 v122, v120, v121
	v_mov_b32_e32 v123, v122
	v_lshl_add_u64 v[120:121], s[46:47], 0, v[192:193]
	v_lshl_add_u64 v[120:121], v[120:121], 0, v[162:163]
	global_store_dwordx4 v[120:121], v[112:115], off
	s_waitcnt lgkmcnt(0)
	s_nop 0
	s_nop 1
	v_permlane16_swap_b32_e32 v123, v122
	v_add_f32_e32 v112, v122, v123
	ds_bpermute_b32 v113, v177, v112
	v_cvt_pk_bf16_f32 v114, v116, v117
	v_cvt_pk_bf16_f32 v115, v118, v119
	v_cvt_pk_bf16_f32 v116, v186, v187
	v_cvt_pk_bf16_f32 v117, v184, v185
	global_store_dwordx4 v[120:121], v[114:117], off offset:256
	s_and_saveexec_b64 s[30:31], s[2:3]
	s_cbranch_execz .LBB0_444
	v_lshlrev_b64 v[114:115], 6, v[170:171]
	v_lshl_add_u64 v[114:115], s[16:17], 0, v[114:115]
	v_lshl_add_u64 v[114:115], s[28:29], 2, v[114:115]
	s_lshl_b32 s8, s65, 2
	v_lshl_add_u64 v[114:115], v[114:115], 0, s[8:9]
	s_waitcnt lgkmcnt(0)
	v_add_f32_e32 v112, v112, v113
	global_store_dword v[114:115], v112, off
.LBB0_444:
	s_or_b64 exec, exec, s[30:31]
	v_or_b32_e32 v120, 48, v170
	v_ashrrev_i32_e32 v121, 31, v120
	v_lshlrev_b64 v[122:123], 11, v[120:121]
	s_waitcnt lgkmcnt(0)
	v_lshl_add_u64 v[112:113], s[42:43], 0, v[122:123]
	v_lshl_add_u64 v[112:113], v[112:113], 0, v[162:163]
	global_load_dwordx4 v[116:119], v[112:113], off
	s_nop 0
	global_load_dwordx4 v[112:115], v[112:113], off offset:256
	v_lshlrev_b32_e32 v124, 16, v140
	v_and_b32_e32 v125, 0xffff0000, v140
	v_lshlrev_b32_e32 v126, 16, v141
	v_and_b32_e32 v127, 0xffff0000, v141
	v_pk_add_f32 v[108:109], v[108:109], v[124:125]
	v_lshlrev_b32_e32 v124, 16, v142
	v_and_b32_e32 v125, 0xffff0000, v142
	v_pk_add_f32 v[110:111], v[110:111], v[126:127]
	v_pk_add_f32 v[124:125], v[104:105], v[124:125]
	v_cvt_pk_bf16_f32 v104, v108, v109
	v_mul_f32_e32 v109, v109, v109
	v_lshlrev_b32_e32 v126, 16, v143
	v_and_b32_e32 v127, 0xffff0000, v143
	v_fmac_f32_e32 v109, v108, v108
	v_mul_f32_e32 v108, v111, v111
	v_pk_add_f32 v[126:127], v[106:107], v[126:127]
	v_fmac_f32_e32 v108, v110, v110
	v_cvt_pk_bf16_f32 v105, v110, v111
	v_add_f32_e32 v108, v109, v108
	v_mul_f32_e32 v109, v125, v125
	v_mul_f32_e32 v110, v127, v127
	v_fmac_f32_e32 v109, v124, v124
	v_fmac_f32_e32 v110, v126, v126
	v_add_f32_e32 v109, v109, v110
	v_cvt_pk_bf16_f32 v106, v124, v125
	v_add_f32_e32 v124, v108, v109
	v_lshlrev_b32_e32 v108, 16, v136
	v_and_b32_e32 v109, 0xffff0000, v136
	v_lshlrev_b32_e32 v110, 16, v137
	v_and_b32_e32 v111, 0xffff0000, v137
	v_pk_add_f32 v[102:103], v[102:103], v[110:111]
	v_pk_add_f32 v[100:101], v[100:101], v[108:109]
	v_lshlrev_b32_e32 v108, 16, v138
	v_and_b32_e32 v109, 0xffff0000, v138
	v_lshlrev_b32_e32 v110, 16, v139
	v_and_b32_e32 v111, 0xffff0000, v139
	v_pk_add_f32 v[108:109], v[96:97], v[108:109]
	v_mul_f32_e32 v96, v101, v101
	v_mul_f32_e32 v97, v103, v103
	v_pk_add_f32 v[110:111], v[98:99], v[110:111]
	v_fmac_f32_e32 v96, v100, v100
	v_fmac_f32_e32 v97, v102, v102
	v_add_f32_e32 v96, v96, v97
	v_mul_f32_e32 v97, v109, v109
	v_mul_f32_e32 v98, v111, v111
	v_fmac_f32_e32 v97, v108, v108
	v_fmac_f32_e32 v98, v110, v110
	v_add_f32_e32 v97, v97, v98
	v_add_f32_e32 v96, v96, v97
	v_add_f32_e32 v99, v124, v96
	v_cvt_pk_bf16_f32 v107, v126, v127
	v_mov_b32_e32 v126, v99
	v_lshl_add_u64 v[96:97], s[46:47], 0, v[174:175]
	v_lshl_add_u64 v[124:125], v[96:97], 0, v[162:163]
	global_store_dwordx4 v[124:125], v[104:107], off
	v_cvt_pk_bf16_f32 v98, v100, v101
	s_waitcnt lgkmcnt(0)
	s_nop 1
	v_permlane16_swap_b32_e32 v126, v99
	v_add_f32_e32 v96, v99, v126
	ds_bpermute_b32 v97, v177, v96
	v_cvt_pk_bf16_f32 v99, v102, v103
	v_cvt_pk_bf16_f32 v100, v108, v109
	v_cvt_pk_bf16_f32 v101, v110, v111
	global_store_dwordx4 v[124:125], v[98:101], off offset:256
	s_and_saveexec_b64 s[30:31], s[2:3]
	s_cbranch_execz .LBB0_446
	v_lshlrev_b64 v[98:99], 6, v[172:173]
	v_lshl_add_u64 v[98:99], s[16:17], 0, v[98:99]
	v_lshl_add_u64 v[98:99], s[28:29], 2, v[98:99]
	s_lshl_b32 s8, s65, 2
	v_lshl_add_u64 v[98:99], v[98:99], 0, s[8:9]
	s_waitcnt lgkmcnt(0)
	v_add_f32_e32 v96, v96, v97
	global_store_dword v[98:99], v96, off
.LBB0_446:
	s_or_b64 exec, exec, s[30:31]
	v_add_u32_e32 v104, 0x80, v170
	v_ashrrev_i32_e32 v105, 31, v104
	v_lshlrev_b64 v[106:107], 11, v[104:105]
	s_waitcnt lgkmcnt(0)
	v_lshl_add_u64 v[96:97], s[42:43], 0, v[106:107]
	v_lshl_add_u64 v[96:97], v[96:97], 0, v[162:163]
	global_load_dwordx4 v[100:103], v[96:97], off
	s_nop 0
	global_load_dwordx4 v[96:99], v[96:97], off offset:256
	v_lshlrev_b32_e32 v108, 16, v132
	v_and_b32_e32 v109, 0xffff0000, v132
	v_lshlrev_b32_e32 v110, 16, v133
	v_and_b32_e32 v111, 0xffff0000, v133
	v_pk_add_f32 v[92:93], v[92:93], v[108:109]
	v_lshlrev_b32_e32 v108, 16, v134
	v_and_b32_e32 v109, 0xffff0000, v134
	v_pk_add_f32 v[94:95], v[94:95], v[110:111]
	v_pk_add_f32 v[108:109], v[88:89], v[108:109]
	v_cvt_pk_bf16_f32 v88, v92, v93
	v_mul_f32_e32 v93, v93, v93
	v_lshlrev_b32_e32 v110, 16, v135
	v_and_b32_e32 v111, 0xffff0000, v135
	v_fmac_f32_e32 v93, v92, v92
	v_mul_f32_e32 v92, v95, v95
	v_pk_add_f32 v[110:111], v[90:91], v[110:111]
	v_fmac_f32_e32 v92, v94, v94
	v_cvt_pk_bf16_f32 v89, v94, v95
	v_add_f32_e32 v92, v93, v92
	v_mul_f32_e32 v93, v109, v109
	v_mul_f32_e32 v94, v111, v111
	v_fmac_f32_e32 v93, v108, v108
	v_fmac_f32_e32 v94, v110, v110
	v_add_f32_e32 v93, v93, v94
	v_cvt_pk_bf16_f32 v90, v108, v109
	v_add_f32_e32 v108, v92, v93
	v_lshlrev_b32_e32 v92, 16, v128
	v_and_b32_e32 v93, 0xffff0000, v128
	v_lshlrev_b32_e32 v94, 16, v129
	v_and_b32_e32 v95, 0xffff0000, v129
	v_pk_add_f32 v[86:87], v[86:87], v[94:95]
	v_pk_add_f32 v[84:85], v[84:85], v[92:93]
	v_lshlrev_b32_e32 v92, 16, v130
	v_and_b32_e32 v93, 0xffff0000, v130
	v_lshlrev_b32_e32 v94, 16, v131
	v_and_b32_e32 v95, 0xffff0000, v131
	v_pk_add_f32 v[92:93], v[80:81], v[92:93]
	v_mul_f32_e32 v80, v85, v85
	v_mul_f32_e32 v81, v87, v87
	v_pk_add_f32 v[94:95], v[82:83], v[94:95]
	v_fmac_f32_e32 v80, v84, v84
	v_fmac_f32_e32 v81, v86, v86
	v_add_f32_e32 v80, v80, v81
	v_mul_f32_e32 v81, v93, v93
	v_mul_f32_e32 v82, v95, v95
	v_fmac_f32_e32 v81, v92, v92
	v_fmac_f32_e32 v82, v94, v94
	v_add_f32_e32 v81, v81, v82
	v_add_f32_e32 v80, v80, v81
	v_add_f32_e32 v83, v108, v80
	v_cvt_pk_bf16_f32 v91, v110, v111
	v_mov_b32_e32 v110, v83
	v_lshl_add_u64 v[80:81], s[46:47], 0, v[168:169]
	v_lshl_add_u64 v[108:109], v[80:81], 0, v[162:163]
	global_store_dwordx4 v[108:109], v[88:91], off
	v_cvt_pk_bf16_f32 v82, v84, v85
	s_waitcnt lgkmcnt(0)
	s_nop 1
	v_permlane16_swap_b32_e32 v110, v83
	v_add_f32_e32 v80, v83, v110
	ds_bpermute_b32 v81, v177, v80
	v_cvt_pk_bf16_f32 v83, v86, v87
	v_cvt_pk_bf16_f32 v84, v92, v93
	v_cvt_pk_bf16_f32 v85, v94, v95
	global_store_dwordx4 v[108:109], v[82:85], off offset:256
	s_and_saveexec_b64 s[30:31], s[2:3]
	s_cbranch_execz .LBB0_448
	v_lshlrev_b64 v[82:83], 6, v[166:167]
	v_lshl_add_u64 v[82:83], s[16:17], 0, v[82:83]
	v_lshl_add_u64 v[82:83], s[28:29], 2, v[82:83]
	s_lshl_b32 s8, s65, 2
	v_lshl_add_u64 v[82:83], v[82:83], 0, s[8:9]
	s_waitcnt lgkmcnt(0)
	v_add_f32_e32 v80, v80, v81
	global_store_dword v[82:83], v80, off
.LBB0_448:
	s_or_b64 exec, exec, s[30:31]
	v_add_co_u32_e32 v82, vcc, 0x48000, v164
	s_waitcnt lgkmcnt(0)
	v_lshl_add_u64 v[80:81], v[164:165], 0, s[18:19]
	v_addc_co_u32_e32 v83, vcc, 0, v165, vcc
	global_load_dwordx4 v[84:87], v[82:83], off
	s_nop 0
	global_load_dwordx4 v[80:83], v[80:81], off offset:256
	s_waitcnt vmcnt(9)
	v_lshlrev_b32_e32 v88, 16, v116
	v_and_b32_e32 v89, 0xffff0000, v116
	v_lshlrev_b32_e32 v90, 16, v117
	v_and_b32_e32 v91, 0xffff0000, v117
	v_pk_add_f32 v[76:77], v[76:77], v[88:89]
	v_lshlrev_b32_e32 v88, 16, v118
	v_and_b32_e32 v89, 0xffff0000, v118
	v_pk_add_f32 v[78:79], v[78:79], v[90:91]
	v_pk_add_f32 v[88:89], v[72:73], v[88:89]
	v_cvt_pk_bf16_f32 v72, v76, v77
	v_mul_f32_e32 v77, v77, v77
	v_lshlrev_b32_e32 v90, 16, v119
	v_and_b32_e32 v91, 0xffff0000, v119
	v_fmac_f32_e32 v77, v76, v76
	v_mul_f32_e32 v76, v79, v79
	v_pk_add_f32 v[90:91], v[74:75], v[90:91]
	v_fmac_f32_e32 v76, v78, v78
	v_cvt_pk_bf16_f32 v73, v78, v79
	v_add_f32_e32 v76, v77, v76
	v_mul_f32_e32 v77, v89, v89
	v_mul_f32_e32 v78, v91, v91
	v_fmac_f32_e32 v77, v88, v88
	v_fmac_f32_e32 v78, v90, v90
	v_add_f32_e32 v77, v77, v78
	v_cvt_pk_bf16_f32 v74, v88, v89
	v_add_f32_e32 v88, v76, v77
	s_waitcnt vmcnt(8)
	v_lshlrev_b32_e32 v76, 16, v112
	v_and_b32_e32 v77, 0xffff0000, v112
	v_lshlrev_b32_e32 v78, 16, v113
	v_and_b32_e32 v79, 0xffff0000, v113
	v_pk_add_f32 v[70:71], v[70:71], v[78:79]
	v_pk_add_f32 v[68:69], v[68:69], v[76:77]
	v_lshlrev_b32_e32 v76, 16, v114
	v_and_b32_e32 v77, 0xffff0000, v114
	v_lshlrev_b32_e32 v78, 16, v115
	v_and_b32_e32 v79, 0xffff0000, v115
	v_pk_add_f32 v[76:77], v[64:65], v[76:77]
	v_mul_f32_e32 v64, v69, v69
	v_mul_f32_e32 v65, v71, v71
	v_pk_add_f32 v[78:79], v[66:67], v[78:79]
	v_fmac_f32_e32 v64, v68, v68
	v_fmac_f32_e32 v65, v70, v70
	v_add_f32_e32 v64, v64, v65
	v_mul_f32_e32 v65, v77, v77
	v_mul_f32_e32 v66, v79, v79
	v_fmac_f32_e32 v65, v76, v76
	v_fmac_f32_e32 v66, v78, v78
	v_add_f32_e32 v65, v65, v66
	v_add_f32_e32 v64, v64, v65
	v_add_f32_e32 v67, v88, v64
	v_cvt_pk_bf16_f32 v75, v90, v91
	v_mov_b32_e32 v90, v67
	v_lshl_add_u64 v[64:65], s[46:47], 0, v[122:123]
	v_lshl_add_u64 v[88:89], v[64:65], 0, v[162:163]
	global_store_dwordx4 v[88:89], v[72:75], off
	v_cvt_pk_bf16_f32 v66, v68, v69
	s_waitcnt lgkmcnt(0)
	s_nop 1
	v_permlane16_swap_b32_e32 v90, v67
	v_add_f32_e32 v64, v67, v90
	ds_bpermute_b32 v65, v177, v64
	v_cvt_pk_bf16_f32 v67, v70, v71
	v_cvt_pk_bf16_f32 v68, v76, v77
	v_cvt_pk_bf16_f32 v69, v78, v79
	global_store_dwordx4 v[88:89], v[66:69], off offset:256
	s_and_saveexec_b64 s[30:31], s[2:3]
	s_cbranch_execz .LBB0_450
	v_lshlrev_b64 v[66:67], 6, v[120:121]
	v_lshl_add_u64 v[66:67], s[16:17], 0, v[66:67]
	v_lshl_add_u64 v[66:67], s[28:29], 2, v[66:67]
	s_lshl_b32 s8, s65, 2
	v_lshl_add_u64 v[66:67], v[66:67], 0, s[8:9]
	s_waitcnt lgkmcnt(0)
	v_add_f32_e32 v64, v64, v65
	global_store_dword v[66:67], v64, off
.LBB0_450:
	s_or_b64 exec, exec, s[30:31]
	v_or_b32_e32 v72, 32, v104
	v_ashrrev_i32_e32 v73, 31, v72
	v_lshlrev_b64 v[74:75], 11, v[72:73]
	s_waitcnt lgkmcnt(0)
	v_lshl_add_u64 v[64:65], s[42:43], 0, v[74:75]
	v_lshl_add_u64 v[64:65], v[64:65], 0, v[162:163]
	global_load_dwordx4 v[68:71], v[64:65], off
	s_nop 0
	global_load_dwordx4 v[64:67], v[64:65], off offset:256
	s_waitcnt vmcnt(9)
	v_lshlrev_b32_e32 v76, 16, v100
	v_and_b32_e32 v77, 0xffff0000, v100
	v_lshlrev_b32_e32 v78, 16, v101
	v_and_b32_e32 v79, 0xffff0000, v101
	v_pk_add_f32 v[60:61], v[60:61], v[76:77]
	v_lshlrev_b32_e32 v76, 16, v102
	v_and_b32_e32 v77, 0xffff0000, v102
	v_pk_add_f32 v[62:63], v[62:63], v[78:79]
	v_pk_add_f32 v[76:77], v[56:57], v[76:77]
	v_cvt_pk_bf16_f32 v56, v60, v61
	v_mul_f32_e32 v61, v61, v61
	v_lshlrev_b32_e32 v78, 16, v103
	v_and_b32_e32 v79, 0xffff0000, v103
	v_fmac_f32_e32 v61, v60, v60
	v_mul_f32_e32 v60, v63, v63
	v_pk_add_f32 v[78:79], v[58:59], v[78:79]
	v_fmac_f32_e32 v60, v62, v62
	v_cvt_pk_bf16_f32 v57, v62, v63
	v_add_f32_e32 v60, v61, v60
	v_mul_f32_e32 v61, v77, v77
	v_mul_f32_e32 v62, v79, v79
	v_fmac_f32_e32 v61, v76, v76
	v_fmac_f32_e32 v62, v78, v78
	v_add_f32_e32 v61, v61, v62
	v_cvt_pk_bf16_f32 v58, v76, v77
	v_add_f32_e32 v76, v60, v61
	s_waitcnt vmcnt(8)
	v_lshlrev_b32_e32 v60, 16, v96
	v_and_b32_e32 v61, 0xffff0000, v96
	v_lshlrev_b32_e32 v62, 16, v97
	v_and_b32_e32 v63, 0xffff0000, v97
	v_pk_add_f32 v[54:55], v[54:55], v[62:63]
	v_pk_add_f32 v[52:53], v[52:53], v[60:61]
	v_lshlrev_b32_e32 v60, 16, v98
	v_and_b32_e32 v61, 0xffff0000, v98
	v_lshlrev_b32_e32 v62, 16, v99
	v_and_b32_e32 v63, 0xffff0000, v99
	v_pk_add_f32 v[60:61], v[48:49], v[60:61]
	v_mul_f32_e32 v48, v53, v53
	v_mul_f32_e32 v49, v55, v55
	v_pk_add_f32 v[62:63], v[50:51], v[62:63]
	v_fmac_f32_e32 v48, v52, v52
	v_fmac_f32_e32 v49, v54, v54
	v_add_f32_e32 v48, v48, v49
	v_mul_f32_e32 v49, v61, v61
	v_mul_f32_e32 v50, v63, v63
	v_fmac_f32_e32 v49, v60, v60
	v_fmac_f32_e32 v50, v62, v62
	v_add_f32_e32 v49, v49, v50
	v_add_f32_e32 v48, v48, v49
	v_add_f32_e32 v51, v76, v48
	v_cvt_pk_bf16_f32 v59, v78, v79
	v_mov_b32_e32 v78, v51
	v_lshl_add_u64 v[48:49], s[46:47], 0, v[106:107]
	v_lshl_add_u64 v[76:77], v[48:49], 0, v[162:163]
	global_store_dwordx4 v[76:77], v[56:59], off
	v_cvt_pk_bf16_f32 v50, v52, v53
	s_waitcnt lgkmcnt(0)
	s_nop 1
	v_permlane16_swap_b32_e32 v78, v51
	v_add_f32_e32 v48, v51, v78
	ds_bpermute_b32 v49, v177, v48
	v_cvt_pk_bf16_f32 v51, v54, v55
	v_cvt_pk_bf16_f32 v52, v60, v61
	v_cvt_pk_bf16_f32 v53, v62, v63
	global_store_dwordx4 v[76:77], v[50:53], off offset:256
	s_and_saveexec_b64 s[30:31], s[2:3]
	s_cbranch_execz .LBB0_452
	v_lshlrev_b64 v[50:51], 6, v[104:105]
	v_lshl_add_u64 v[50:51], s[16:17], 0, v[50:51]
	v_lshl_add_u64 v[50:51], s[28:29], 2, v[50:51]
	s_lshl_b32 s8, s65, 2
	v_lshl_add_u64 v[50:51], v[50:51], 0, s[8:9]
	s_waitcnt lgkmcnt(0)
	v_add_f32_e32 v48, v48, v49
	global_store_dword v[50:51], v48, off
.LBB0_452:
	s_or_b64 exec, exec, s[30:31]
	v_or_b32_e32 v56, 48, v104
	v_ashrrev_i32_e32 v57, 31, v56
	v_lshlrev_b64 v[58:59], 11, v[56:57]
	s_waitcnt lgkmcnt(0)
	v_lshl_add_u64 v[48:49], s[42:43], 0, v[58:59]
	v_lshl_add_u64 v[48:49], v[48:49], 0, v[162:163]
	global_load_dwordx4 v[52:55], v[48:49], off
	s_nop 0
	global_load_dwordx4 v[48:51], v[48:49], off offset:256
	s_waitcnt vmcnt(9)
	v_lshlrev_b32_e32 v76, 16, v84
	v_and_b32_e32 v77, 0xffff0000, v84
	v_lshlrev_b32_e32 v78, 16, v85
	v_and_b32_e32 v79, 0xffff0000, v85
	v_pk_add_f32 v[44:45], v[44:45], v[76:77]
	v_lshlrev_b32_e32 v76, 16, v86
	v_and_b32_e32 v77, 0xffff0000, v86
	v_pk_add_f32 v[46:47], v[46:47], v[78:79]
	v_pk_add_f32 v[76:77], v[40:41], v[76:77]
	v_cvt_pk_bf16_f32 v40, v44, v45
	v_mul_f32_e32 v45, v45, v45
	v_lshlrev_b32_e32 v78, 16, v87
	v_and_b32_e32 v79, 0xffff0000, v87
	v_fmac_f32_e32 v45, v44, v44
	v_mul_f32_e32 v44, v47, v47
	v_pk_add_f32 v[78:79], v[42:43], v[78:79]
	v_fmac_f32_e32 v44, v46, v46
	v_cvt_pk_bf16_f32 v41, v46, v47
	v_add_f32_e32 v44, v45, v44
	v_mul_f32_e32 v45, v77, v77
	v_mul_f32_e32 v46, v79, v79
	v_fmac_f32_e32 v45, v76, v76
	v_fmac_f32_e32 v46, v78, v78
	v_add_f32_e32 v45, v45, v46
	v_cvt_pk_bf16_f32 v42, v76, v77
	v_add_f32_e32 v76, v44, v45
	s_waitcnt vmcnt(8)
	v_lshlrev_b32_e32 v44, 16, v80
	v_and_b32_e32 v45, 0xffff0000, v80
	v_lshlrev_b32_e32 v46, 16, v81
	v_and_b32_e32 v47, 0xffff0000, v81
	v_pk_add_f32 v[38:39], v[38:39], v[46:47]
	v_pk_add_f32 v[36:37], v[36:37], v[44:45]
	v_lshlrev_b32_e32 v44, 16, v82
	v_and_b32_e32 v45, 0xffff0000, v82
	v_lshlrev_b32_e32 v46, 16, v83
	v_and_b32_e32 v47, 0xffff0000, v83
	v_pk_add_f32 v[44:45], v[32:33], v[44:45]
	v_mul_f32_e32 v32, v37, v37
	v_mul_f32_e32 v33, v39, v39
	v_pk_add_f32 v[46:47], v[34:35], v[46:47]
	v_fmac_f32_e32 v32, v36, v36
	v_fmac_f32_e32 v33, v38, v38
	v_add_f32_e32 v32, v32, v33
	v_mul_f32_e32 v33, v45, v45
	v_mul_f32_e32 v34, v47, v47
	v_fmac_f32_e32 v33, v44, v44
	v_fmac_f32_e32 v34, v46, v46
	v_add_f32_e32 v33, v33, v34
	v_add_f32_e32 v32, v32, v33
	v_add_f32_e32 v35, v76, v32
	v_mov_b32_e32 v76, v35
	v_or_b32_e32 v60, 16, v104
	v_ashrrev_i32_e32 v61, 31, v60
	v_lshlrev_b64 v[62:63], 11, v[60:61]
	v_lshl_add_u64 v[32:33], s[46:47], 0, v[62:63]
	v_lshl_add_u64 v[62:63], v[32:33], 0, v[162:163]
	s_waitcnt lgkmcnt(0)
	s_nop 1
	v_permlane16_swap_b32_e32 v76, v35
	v_add_f32_e32 v32, v35, v76
	ds_bpermute_b32 v33, v177, v32
	v_cvt_pk_bf16_f32 v43, v78, v79
	global_store_dwordx4 v[62:63], v[40:43], off
	v_cvt_pk_bf16_f32 v34, v36, v37
	v_cvt_pk_bf16_f32 v35, v38, v39
	v_cvt_pk_bf16_f32 v36, v44, v45
	v_cvt_pk_bf16_f32 v37, v46, v47
	global_store_dwordx4 v[62:63], v[34:37], off offset:256
	s_and_saveexec_b64 s[30:31], s[2:3]
	s_cbranch_execz .LBB0_454
	v_lshlrev_b64 v[34:35], 6, v[60:61]
	v_lshl_add_u64 v[34:35], s[16:17], 0, v[34:35]
	v_lshl_add_u64 v[34:35], s[28:29], 2, v[34:35]
	s_lshl_b32 s8, s65, 2
	v_lshl_add_u64 v[34:35], v[34:35], 0, s[8:9]
	s_waitcnt lgkmcnt(0)
	v_add_f32_e32 v32, v32, v33
	global_store_dword v[34:35], v32, off
.LBB0_454:
	s_or_b64 exec, exec, s[30:31]
	s_waitcnt vmcnt(7)
	v_lshlrev_b32_e32 v32, 16, v68
	s_waitcnt lgkmcnt(0)
	v_and_b32_e32 v33, 0xffff0000, v68
	v_lshlrev_b32_e32 v34, 16, v69
	v_and_b32_e32 v35, 0xffff0000, v69
	v_pk_add_f32 v[28:29], v[28:29], v[32:33]
	v_lshlrev_b32_e32 v32, 16, v70
	v_and_b32_e32 v33, 0xffff0000, v70
	v_pk_add_f32 v[30:31], v[30:31], v[34:35]
	v_pk_add_f32 v[32:33], v[24:25], v[32:33]
	v_cvt_pk_bf16_f32 v24, v28, v29
	v_mul_f32_e32 v29, v29, v29
	v_lshlrev_b32_e32 v34, 16, v71
	v_and_b32_e32 v35, 0xffff0000, v71
	v_fmac_f32_e32 v29, v28, v28
	v_mul_f32_e32 v28, v31, v31
	v_pk_add_f32 v[34:35], v[26:27], v[34:35]
	v_fmac_f32_e32 v28, v30, v30
	v_cvt_pk_bf16_f32 v25, v30, v31
	v_add_f32_e32 v28, v29, v28
	v_mul_f32_e32 v29, v33, v33
	v_mul_f32_e32 v30, v35, v35
	v_fmac_f32_e32 v29, v32, v32
	v_fmac_f32_e32 v30, v34, v34
	v_add_f32_e32 v29, v29, v30
	v_cvt_pk_bf16_f32 v26, v32, v33
	v_add_f32_e32 v32, v28, v29
	s_waitcnt vmcnt(6)
	v_lshlrev_b32_e32 v28, 16, v64
	v_and_b32_e32 v29, 0xffff0000, v64
	v_lshlrev_b32_e32 v30, 16, v65
	v_and_b32_e32 v31, 0xffff0000, v65
	v_pk_add_f32 v[22:23], v[22:23], v[30:31]
	v_pk_add_f32 v[20:21], v[20:21], v[28:29]
	v_lshlrev_b32_e32 v28, 16, v66
	v_and_b32_e32 v29, 0xffff0000, v66
	v_lshlrev_b32_e32 v30, 16, v67
	v_and_b32_e32 v31, 0xffff0000, v67
	v_pk_add_f32 v[28:29], v[16:17], v[28:29]
	v_mul_f32_e32 v16, v21, v21
	v_mul_f32_e32 v17, v23, v23
	v_pk_add_f32 v[30:31], v[18:19], v[30:31]
	v_fmac_f32_e32 v16, v20, v20
	v_fmac_f32_e32 v17, v22, v22
	v_add_f32_e32 v16, v16, v17
	v_mul_f32_e32 v17, v29, v29
	v_mul_f32_e32 v18, v31, v31
	v_fmac_f32_e32 v17, v28, v28
	v_fmac_f32_e32 v18, v30, v30
	v_add_f32_e32 v17, v17, v18
	v_add_f32_e32 v16, v16, v17
	v_add_f32_e32 v19, v32, v16
	v_cvt_pk_bf16_f32 v27, v34, v35
	v_mov_b32_e32 v34, v19
	v_lshl_add_u64 v[16:17], s[46:47], 0, v[74:75]
	v_lshl_add_u64 v[32:33], v[160:161], 1, v[16:17]
	global_store_dwordx4 v[32:33], v[24:27], off
	v_cvt_pk_bf16_f32 v18, v20, v21
	s_waitcnt lgkmcnt(0)
	s_nop 1
	v_permlane16_swap_b32_e32 v34, v19
	v_add_f32_e32 v16, v19, v34
	ds_bpermute_b32 v17, v177, v16
	v_cvt_pk_bf16_f32 v19, v22, v23
	v_cvt_pk_bf16_f32 v20, v28, v29
	v_cvt_pk_bf16_f32 v21, v30, v31
	global_store_dwordx4 v[32:33], v[18:21], off offset:256
	s_and_saveexec_b64 s[30:31], s[2:3]
	s_cbranch_execz .LBB0_456
	v_lshlrev_b64 v[18:19], 6, v[72:73]
	v_lshl_add_u64 v[18:19], s[16:17], 0, v[18:19]
	v_lshl_add_u64 v[18:19], s[28:29], 2, v[18:19]
	s_lshl_b32 s8, s65, 2
	v_lshl_add_u64 v[18:19], v[18:19], 0, s[8:9]
	s_waitcnt lgkmcnt(0)
	v_add_f32_e32 v16, v16, v17
	global_store_dword v[18:19], v16, off
.LBB0_456:
	s_or_b64 exec, exec, s[30:31]
	s_waitcnt vmcnt(5)
	v_lshlrev_b32_e32 v16, 16, v52
	s_waitcnt lgkmcnt(0)
	v_and_b32_e32 v17, 0xffff0000, v52
	v_lshlrev_b32_e32 v18, 16, v53
	v_and_b32_e32 v19, 0xffff0000, v53
	v_pk_add_f32 v[12:13], v[12:13], v[16:17]
	v_lshlrev_b32_e32 v16, 16, v54
	v_and_b32_e32 v17, 0xffff0000, v54
	v_pk_add_f32 v[14:15], v[14:15], v[18:19]
	v_pk_add_f32 v[16:17], v[8:9], v[16:17]
	v_cvt_pk_bf16_f32 v8, v12, v13
	v_mul_f32_e32 v13, v13, v13
	v_lshlrev_b32_e32 v18, 16, v55
	v_and_b32_e32 v19, 0xffff0000, v55
	v_fmac_f32_e32 v13, v12, v12
	v_mul_f32_e32 v12, v15, v15
	v_pk_add_f32 v[18:19], v[10:11], v[18:19]
	v_fmac_f32_e32 v12, v14, v14
	v_cvt_pk_bf16_f32 v9, v14, v15
	v_add_f32_e32 v12, v13, v12
	v_mul_f32_e32 v13, v17, v17
	v_mul_f32_e32 v14, v19, v19
	v_fmac_f32_e32 v13, v16, v16
	v_fmac_f32_e32 v14, v18, v18
	v_add_f32_e32 v13, v13, v14
	v_cvt_pk_bf16_f32 v10, v16, v17
	v_add_f32_e32 v16, v12, v13
	s_waitcnt vmcnt(4)
	v_lshlrev_b32_e32 v12, 16, v48
	v_and_b32_e32 v13, 0xffff0000, v48
	v_lshlrev_b32_e32 v14, 16, v49
	v_and_b32_e32 v15, 0xffff0000, v49
	v_pk_add_f32 v[6:7], v[6:7], v[14:15]
	v_pk_add_f32 v[4:5], v[4:5], v[12:13]
	v_lshlrev_b32_e32 v12, 16, v50
	v_and_b32_e32 v13, 0xffff0000, v50
	v_lshlrev_b32_e32 v14, 16, v51
	v_and_b32_e32 v15, 0xffff0000, v51
	v_pk_add_f32 v[12:13], v[0:1], v[12:13]
	v_mul_f32_e32 v0, v5, v5
	v_mul_f32_e32 v1, v7, v7
	v_pk_add_f32 v[14:15], v[2:3], v[14:15]
	v_fmac_f32_e32 v0, v4, v4
	v_fmac_f32_e32 v1, v6, v6
	v_add_f32_e32 v0, v0, v1
	v_mul_f32_e32 v1, v13, v13
	v_mul_f32_e32 v2, v15, v15
	v_fmac_f32_e32 v1, v12, v12
	v_fmac_f32_e32 v2, v14, v14
	v_add_f32_e32 v1, v1, v2
	v_add_f32_e32 v0, v0, v1
	v_add_f32_e32 v3, v16, v0
	v_cvt_pk_bf16_f32 v11, v18, v19
	v_mov_b32_e32 v18, v3
	v_lshl_add_u64 v[0:1], s[46:47], 0, v[58:59]
	v_lshl_add_u64 v[16:17], v[160:161], 1, v[0:1]
	global_store_dwordx4 v[16:17], v[8:11], off
	v_cvt_pk_bf16_f32 v2, v4, v5
	s_waitcnt lgkmcnt(0)
	s_nop 1
	v_permlane16_swap_b32_e32 v18, v3
	v_add_f32_e32 v0, v3, v18
	ds_bpermute_b32 v1, v177, v0
	v_cvt_pk_bf16_f32 v3, v6, v7
	v_cvt_pk_bf16_f32 v4, v12, v13
	v_cvt_pk_bf16_f32 v5, v14, v15
	global_store_dwordx4 v[16:17], v[2:5], off offset:256
	s_and_saveexec_b64 s[30:31], s[2:3]
	s_cbranch_execz .LBB0_458
	v_lshlrev_b64 v[2:3], 6, v[56:57]
	v_lshl_add_u64 v[2:3], s[16:17], 0, v[2:3]
	v_lshl_add_u64 v[2:3], s[28:29], 2, v[2:3]
	s_lshl_b32 s8, s65, 2
	v_lshl_add_u64 v[2:3], v[2:3], 0, s[8:9]
	s_waitcnt lgkmcnt(0)
	v_add_f32_e32 v0, v0, v1
	global_store_dword v[2:3], v0, off

.LBB0_491:
	s_lshl_b32 s57, s64, 8
	s_add_i32 s57, s57, s87
	v_or_b32_e32 v156, s57, v215
	v_ashrrev_i32_e32 v157, 31, v156
	v_or_b32_e32 v174, 16, v156
	v_or_b32_e32 v172, 32, v156
	v_or_b32_e32 v170, 48, v156
	v_lshlrev_b64 v[146:147], 6, v[156:157]
	v_ashrrev_i32_e32 v175, 31, v174
	v_ashrrev_i32_e32 v173, 31, v172
	v_ashrrev_i32_e32 v171, 31, v170
	v_lshl_add_u64 v[154:155], v[136:137], 0, v[146:147]
	v_lshlrev_b64 v[146:147], 6, v[174:175]
	v_lshlrev_b64 v[158:159], 6, v[172:173]
	v_lshlrev_b64 v[162:163], 6, v[170:171]
	v_lshl_add_u64 v[150:151], v[136:137], 0, v[146:147]
	v_lshl_add_u64 v[158:159], v[136:137], 0, v[158:159]
	v_lshl_add_u64 v[162:163], v[136:137], 0, v[162:163]
	global_load_dwordx4 v[146:149], v[154:155], off
	s_nop 0
	global_load_dwordx4 v[150:153], v[150:151], off
	s_waitcnt vmcnt(0)
	v_mov_b32_e32 v166, v147
	global_load_dwordx4 v[158:161], v[158:159], off
	v_mov_b32_e32 v167, v148
	global_load_dwordx4 v[162:165], v[162:163], off
	v_mov_b32_e32 v147, v149
	v_pk_add_f32 v[146:147], v[166:167], v[146:147]
	v_mov_b32_e32 v148, v151
	v_mov_b32_e32 v149, v152
	v_mov_b32_e32 v151, v153
	v_add_f32_e32 v157, v146, v147
	v_pk_add_f32 v[146:147], v[148:149], v[150:151]
	s_waitcnt vmcnt(1)
	v_mov_b32_e32 v152, v159
	v_mov_b32_e32 v153, v160
	v_mov_b32_e32 v159, v161
	s_waitcnt vmcnt(0)
	v_mov_b32_e32 v160, v163
	v_mov_b32_e32 v161, v164
	v_mov_b32_e32 v163, v165
	v_pk_add_f32 v[148:149], v[152:153], v[158:159]
	v_pk_add_f32 v[150:151], v[160:161], v[162:163]
	v_add_f32_e32 v146, v146, v147
	v_add_f32_e32 v147, v148, v149
	v_add_f32_e32 v148, v150, v151
	v_mov_b32_e32 v152, v157
	v_mov_b32_e32 v149, v146
	v_mov_b32_e32 v150, v147
	v_mov_b32_e32 v151, v148
	s_waitcnt lgkmcnt(3)
	s_nop 1
	v_permlane16_swap_b32_e32 v152, v157
	v_add_f32_e32 v152, v157, v152
	s_waitcnt lgkmcnt(2)
	s_nop 1
	v_permlane16_swap_b32_e32 v149, v146
	v_add_f32_e32 v146, v146, v149
	s_waitcnt lgkmcnt(1)
	s_nop 1
	v_permlane16_swap_b32_e32 v150, v147
	v_add_f32_e32 v147, v147, v150
	s_waitcnt lgkmcnt(0)
	s_nop 1
	v_permlane16_swap_b32_e32 v151, v148
	v_add_f32_e32 v148, v148, v151
	v_mov_b32_e32 v153, v152
	v_mov_b32_e32 v149, v146
	v_mov_b32_e32 v150, v147
	v_mov_b32_e32 v151, v148
	s_waitcnt lgkmcnt(3)
	s_nop 1
	v_permlane32_swap_b32_e32 v153, v152
	v_add_f32_e32 v152, v152, v153
	s_waitcnt lgkmcnt(2)
	s_nop 1
	v_permlane32_swap_b32_e32 v149, v146
	v_add_f32_e32 v146, v146, v149
	s_waitcnt lgkmcnt(1)
	s_nop 1
	v_permlane32_swap_b32_e32 v150, v147
	v_add_f32_e32 v147, v147, v150
	s_waitcnt lgkmcnt(0)
	s_nop 1
	v_permlane32_swap_b32_e32 v151, v148
	v_add_f32_e32 v148, v148, v151
	v_fmamk_f32 v152, v152, 0x3a800000, v223
	v_fmamk_f32 v146, v146, 0x3a800000, v223
	v_fmamk_f32 v147, v147, 0x3a800000, v223
	v_fmamk_f32 v148, v148, 0x3a800000, v223
	v_rsq_f32_e32 v168, v152
	v_rsq_f32_e32 v162, v146
	v_rsq_f32_e32 v160, v147
	v_rsq_f32_e32 v158, v148
	v_add_co_u32_e32 v154, vcc, s81, v154
	s_nop 1
	v_addc_co_u32_e32 v155, vcc, 0, v155, vcc
	global_load_dwordx4 v[146:149], v[154:155], off
	global_load_dwordx4 v[150:153], v[154:155], off offset:1024
	global_load_dwordx4 v[164:167], v[154:155], off offset:2048
	global_load_dwordx4 v[176:179], v[154:155], off offset:3072
	s_waitcnt vmcnt(3)
	v_mov_b32_e32 v154, v147
	v_mov_b32_e32 v155, v148
	v_mov_b32_e32 v147, v149
	s_waitcnt vmcnt(2)
	v_mov_b32_e32 v148, v151
	v_mov_b32_e32 v149, v152
	v_mov_b32_e32 v151, v153
	s_waitcnt vmcnt(1)
	v_mov_b32_e32 v152, v165
	v_mov_b32_e32 v153, v166
	v_mov_b32_e32 v165, v167
	s_waitcnt vmcnt(0)
	v_mov_b32_e32 v166, v177
	v_mov_b32_e32 v167, v178
	v_mov_b32_e32 v177, v179
	v_pk_add_f32 v[146:147], v[154:155], v[146:147]
	v_pk_add_f32 v[148:149], v[148:149], v[150:151]
	v_pk_add_f32 v[150:151], v[152:153], v[164:165]
	v_pk_add_f32 v[152:153], v[166:167], v[176:177]
	v_add_f32_e32 v146, v146, v147
	v_add_f32_e32 v147, v148, v149
	v_add_f32_e32 v148, v150, v151
	v_add_f32_e32 v149, v152, v153
	v_mov_b32_e32 v150, v146
	v_mov_b32_e32 v151, v147
	v_mov_b32_e32 v152, v148
	v_mov_b32_e32 v153, v149
	s_waitcnt lgkmcnt(3)
	s_nop 1
	v_permlane16_swap_b32_e32 v150, v146
	v_add_f32_e32 v146, v146, v150
	s_waitcnt lgkmcnt(2)
	s_nop 1
	v_permlane16_swap_b32_e32 v151, v147
	v_add_f32_e32 v147, v147, v151
	s_waitcnt lgkmcnt(1)
	s_nop 1
	v_permlane16_swap_b32_e32 v152, v148
	v_add_f32_e32 v148, v148, v152
	s_waitcnt lgkmcnt(0)
	s_nop 1
	v_permlane16_swap_b32_e32 v153, v149
	v_add_f32_e32 v149, v149, v153
	v_mov_b32_e32 v150, v146
	ds_bpermute_b32 v151, v218, v147
	v_mov_b32_e32 v152, v148
	ds_bpermute_b32 v153, v218, v149
	s_waitcnt lgkmcnt(3)
	s_nop 1
	v_permlane32_swap_b32_e32 v150, v146
	v_add_f32_e32 v146, v146, v150
	s_waitcnt lgkmcnt(2)
	v_add_f32_e32 v147, v147, v151
	s_waitcnt lgkmcnt(1)
	s_nop 1
	v_permlane32_swap_b32_e32 v152, v148
	v_add_f32_e32 v148, v148, v152
	s_waitcnt lgkmcnt(0)
	v_add_f32_e32 v149, v149, v153
	v_fmamk_f32 v146, v146, 0x3a800000, v223
	v_fmamk_f32 v147, v147, 0x3a800000, v223
	v_fmamk_f32 v148, v148, 0x3a800000, v223
	v_fmamk_f32 v149, v149, 0x3a800000, v223
	v_rsq_f32_e32 v154, v146
	v_rsq_f32_e32 v152, v147
	v_rsq_f32_e32 v150, v148
	v_rsq_f32_e32 v148, v149
	v_lshl_or_b32 v146, s62, 7, v219
	v_ashrrev_i32_e32 v147, 31, v146
	v_lshlrev_b64 v[176:177], 2, v[146:147]
	v_lshl_add_u64 v[164:165], s[10:11], 0, v[176:177]
	v_lshl_add_u64 v[178:179], s[16:17], 0, v[176:177]
	v_lshl_add_u64 v[180:181], s[24:25], 0, v[176:177]
	v_lshl_add_u64 v[166:167], s[12:13], 0, v[176:177]
	global_load_dwordx2 v[200:201], v[164:165], off
	global_load_dwordx2 v[208:209], v[166:167], off
	v_lshl_add_u64 v[182:183], s[26:27], 0, v[176:177]
	v_lshl_add_u64 v[184:185], s[28:29], 0, v[176:177]
	global_load_dwordx2 v[212:213], v[178:179], off
	global_load_dwordx2 v[210:211], v[180:181], off
	s_nop 0
	global_load_dwordx2 v[180:181], v[182:183], off
	global_load_dwordx2 v[206:207], v[184:185], off
	v_lshl_add_u64 v[178:179], s[30:31], 0, v[176:177]
	v_lshl_add_u64 v[176:177], s[52:53], 0, v[176:177]
	global_load_dwordx2 v[202:203], v[178:179], off
	global_load_dwordx2 v[204:205], v[176:177], off
	v_pk_mul_f32 v[126:127], v[126:127], v[168:169] op_sel_hi:[1,0]
	v_pk_mul_f32 v[124:125], v[124:125], v[168:169] op_sel_hi:[1,0]
	v_pk_mul_f32 v[122:123], v[122:123], v[168:169] op_sel_hi:[1,0]
	v_pk_mul_f32 v[120:121], v[120:121], v[168:169] op_sel_hi:[1,0]
	v_pk_mul_f32 v[184:185], v[116:117], v[162:163] op_sel_hi:[1,0]
	v_pk_mul_f32 v[186:187], v[104:105], v[162:163] op_sel_hi:[1,0]
	v_pk_mul_f32 v[182:183], v[112:113], v[160:161] op_sel_hi:[1,0]
	v_pk_mul_f32 v[176:177], v[100:101], v[160:161] op_sel_hi:[1,0]
	v_pk_mul_f32 v[100:101], v[108:109], v[158:159] op_sel_hi:[1,0]
	v_pk_mul_f32 v[96:97], v[96:97], v[158:159] op_sel_hi:[1,0]
	v_pk_mul_f32 v[92:93], v[92:93], v[154:155] op_sel_hi:[1,0]
	v_pk_mul_f32 v[88:89], v[88:89], v[154:155] op_sel_hi:[1,0]
	v_pk_mul_f32 v[116:117], v[84:85], v[152:153] op_sel_hi:[1,0]
	v_pk_mul_f32 v[84:85], v[68:69], v[150:151] op_sel_hi:[1,0]
	v_pk_mul_f32 v[68:69], v[76:77], v[148:149] op_sel_hi:[1,0]
	v_pk_mul_f32 v[64:65], v[64:65], v[148:149] op_sel_hi:[1,0]
	v_pk_mul_f32 v[112:113], v[72:73], v[152:153] op_sel_hi:[1,0]
	v_pk_mul_f32 v[104:105], v[80:81], v[150:151] op_sel_hi:[1,0]
	s_waitcnt vmcnt(5)
	v_mul_f32_dpp v73, v124, v212 row_shr:1 row_mask:0xf bank_mask:0xf bound_ctrl:1
	v_mov_b32_dpp v72, v124 row_shr:2 row_mask:0xf bank_mask:0xf bound_ctrl:1
	s_waitcnt vmcnt(4)
	v_fmac_f32_e32 v73, v124, v210
	v_fmac_f32_e32 v73, v200, v72
	v_add_f32_e32 v72, v208, v73
	v_mul_f32_e32 v73, 0xbfb8aa3b, v72
	v_exp_f32_e32 v73, v73
	s_waitcnt vmcnt(2)
	v_mul_f32_dpp v77, v120, v206 row_shr:1 row_mask:0xf bank_mask:0xf bound_ctrl:1
	v_mov_b32_dpp v76, v120 row_shr:2 row_mask:0xf bank_mask:0xf bound_ctrl:1
	s_waitcnt vmcnt(1)
	v_fmac_f32_e32 v77, v120, v202
	v_add_f32_e32 v73, 1.0, v73
	v_rcp_f32_e32 v73, v73
	v_fmac_f32_e32 v77, v180, v76
	s_waitcnt vmcnt(0)
	v_add_f32_e32 v76, v204, v77
	v_mul_f32_dpp v80, v121, v207 row_shr:1 row_mask:0xf bank_mask:0xf bound_ctrl:1
	v_mul_f32_dpp v77, v125, v213 row_shr:1 row_mask:0xf bank_mask:0xf bound_ctrl:1
	v_mul_f32_e32 v72, v72, v73
	v_mov_b32_dpp v73, v125 row_shr:2 row_mask:0xf bank_mask:0xf bound_ctrl:1
	v_fmac_f32_e32 v77, v125, v211
	v_fmac_f32_e32 v77, v201, v73
	v_add_f32_e32 v73, v209, v77
	v_mul_f32_e32 v77, 0xbfb8aa3b, v73
	v_exp_f32_e32 v77, v77
	v_mul_f32_e32 v72, v76, v72
	v_mov_b32_dpp v76, v121 row_shr:2 row_mask:0xf bank_mask:0xf bound_ctrl:1
	v_fmac_f32_e32 v80, v121, v203
	v_add_f32_e32 v77, 1.0, v77
	v_rcp_f32_e32 v77, v77
	v_fmac_f32_e32 v80, v181, v76
	v_add_f32_e32 v76, v205, v80
	v_or_b32_e32 v178, 2, v146
	v_mul_f32_e32 v73, v73, v77
	v_mul_f32_e32 v73, v76, v73
	v_cvt_pk_bf16_f32 v80, v72, v73
	v_ashrrev_i32_e32 v179, 31, v178
	v_mov_b32_dpp v72, v124 row_ror:1 row_mask:0xf bank_mask:0xf bound_ctrl:1
	v_mov_b32_dpp v73, v124 row_ror:2 row_mask:0xf bank_mask:0xf bound_ctrl:1
	v_mov_b32_dpp v76, v120 row_ror:1 row_mask:0xf bank_mask:0xf bound_ctrl:1
	v_mov_b32_dpp v72, v184 row_shr:1 row_mask:0xf bank_mask:0xf
	v_mul_f32_e32 v72, v212, v72
	v_mov_b32_dpp v73, v184 row_shr:2 row_mask:0xf bank_mask:0xf
	v_fmac_f32_e32 v72, v184, v210
	v_fmac_f32_e32 v72, v200, v73
	v_add_f32_e32 v72, v208, v72
	v_mul_f32_e32 v73, 0xbfb8aa3b, v72
	v_exp_f32_e32 v73, v73
	v_mov_b32_dpp v76, v186 row_shr:1 row_mask:0xf bank_mask:0xf
	v_mov_b32_dpp v77, v120 row_ror:2 row_mask:0xf bank_mask:0xf bound_ctrl:1
	v_mul_f32_e32 v76, v206, v76
	v_add_f32_e32 v73, 1.0, v73
	v_rcp_f32_e32 v73, v73
	v_mov_b32_dpp v77, v186 row_shr:2 row_mask:0xf bank_mask:0xf
	v_fmac_f32_e32 v76, v186, v202
	v_fmac_f32_e32 v76, v180, v77
	v_mul_f32_e32 v72, v72, v73
	v_mov_b32_dpp v73, v125 row_ror:1 row_mask:0xf bank_mask:0xf bound_ctrl:1
	v_add_f32_e32 v76, v204, v76
	v_mul_f32_e32 v72, v76, v72
	v_mov_b32_dpp v73, v185 row_shr:1 row_mask:0xf bank_mask:0xf
	v_mov_b32_dpp v76, v125 row_ror:2 row_mask:0xf bank_mask:0xf bound_ctrl:1
	v_mul_f32_e32 v73, v213, v73
	v_fmac_f32_e32 v73, v185, v211
	v_mov_b32_dpp v76, v185 row_shr:2 row_mask:0xf bank_mask:0xf
	v_fmac_f32_e32 v73, v201, v76
	v_add_f32_e32 v73, v209, v73
	v_mul_f32_e32 v76, 0xbfb8aa3b, v73
	v_exp_f32_e32 v76, v76
	v_mov_b32_dpp v77, v121 row_ror:1 row_mask:0xf bank_mask:0xf bound_ctrl:1
	v_mov_b32_dpp v81, v121 row_ror:2 row_mask:0xf bank_mask:0xf bound_ctrl:1
	v_add_f32_e32 v76, 1.0, v76
	v_mov_b32_dpp v77, v187 row_shr:1 row_mask:0xf bank_mask:0xf
	v_rcp_f32_e32 v76, v76
	v_mul_f32_e32 v77, v207, v77
	v_mov_b32_dpp v81, v187 row_shr:2 row_mask:0xf bank_mask:0xf
	v_fmac_f32_e32 v77, v187, v203
	v_fmac_f32_e32 v77, v181, v81
	v_add_f32_e32 v77, v205, v77
	v_mul_f32_e32 v73, v73, v76
	v_mul_f32_e32 v73, v77, v73
	v_cvt_pk_bf16_f32 v72, v72, v73
	s_nop 1
	v_mov_b32_dpp v73, v184 row_ror:1 row_mask:0xf bank_mask:0xf bound_ctrl:1
	v_mov_b32_dpp v76, v184 row_ror:2 row_mask:0xf bank_mask:0xf bound_ctrl:1
	v_mov_b32_dpp v77, v186 row_ror:1 row_mask:0xf bank_mask:0xf bound_ctrl:1
	v_mov_b32_dpp v73, v182 row_shr:1 row_mask:0xf bank_mask:0xf
	v_mul_f32_e32 v73, v212, v73
	v_mov_b32_dpp v76, v182 row_shr:2 row_mask:0xf bank_mask:0xf
	v_fmac_f32_e32 v73, v182, v210
	v_fmac_f32_e32 v73, v200, v76
	v_add_f32_e32 v73, v208, v73
	v_mul_f32_e32 v76, 0xbfb8aa3b, v73
	v_exp_f32_e32 v76, v76
	v_mov_b32_dpp v77, v176 row_shr:1 row_mask:0xf bank_mask:0xf
	v_mov_b32_dpp v81, v186 row_ror:2 row_mask:0xf bank_mask:0xf bound_ctrl:1
	v_mul_f32_e32 v77, v206, v77
	v_add_f32_e32 v76, 1.0, v76
	v_rcp_f32_e32 v76, v76
	v_mov_b32_dpp v81, v176 row_shr:2 row_mask:0xf bank_mask:0xf
	v_fmac_f32_e32 v77, v176, v202
	v_fmac_f32_e32 v77, v180, v81
	v_mul_f32_e32 v73, v73, v76
	v_mov_b32_dpp v76, v185 row_ror:1 row_mask:0xf bank_mask:0xf bound_ctrl:1
	v_add_f32_e32 v77, v204, v77
	v_mul_f32_e32 v73, v77, v73
	v_mov_b32_dpp v76, v183 row_shr:1 row_mask:0xf bank_mask:0xf
	v_mov_b32_dpp v77, v185 row_ror:2 row_mask:0xf bank_mask:0xf bound_ctrl:1
	v_mul_f32_e32 v76, v213, v76
	v_fmac_f32_e32 v76, v183, v211
	v_mov_b32_dpp v77, v183 row_shr:2 row_mask:0xf bank_mask:0xf
	v_fmac_f32_e32 v76, v201, v77
	v_add_f32_e32 v76, v209, v76
	v_mul_f32_e32 v77, 0xbfb8aa3b, v76
	v_exp_f32_e32 v77, v77
	v_mov_b32_dpp v81, v187 row_ror:1 row_mask:0xf bank_mask:0xf bound_ctrl:1
	v_mov_b32_dpp v108, v187 row_ror:2 row_mask:0xf bank_mask:0xf bound_ctrl:1
	v_add_f32_e32 v77, 1.0, v77
	v_mov_b32_dpp v81, v177 row_shr:1 row_mask:0xf bank_mask:0xf
	v_rcp_f32_e32 v77, v77
	v_mul_f32_e32 v81, v207, v81
	v_mov_b32_dpp v108, v177 row_shr:2 row_mask:0xf bank_mask:0xf
	v_fmac_f32_e32 v81, v177, v203
	v_fmac_f32_e32 v81, v181, v108
	v_add_f32_e32 v81, v205, v81
	v_mul_f32_e32 v76, v76, v77
	v_mul_f32_e32 v76, v81, v76
	v_cvt_pk_bf16_f32 v76, v73, v76
	v_mov_b32_dpp v73, v182 row_ror:1 row_mask:0xf bank_mask:0xf bound_ctrl:1
	v_mov_b32_dpp v77, v182 row_ror:2 row_mask:0xf bank_mask:0xf bound_ctrl:1
	v_mov_b32_dpp v81, v176 row_ror:1 row_mask:0xf bank_mask:0xf bound_ctrl:1
	v_mov_b32_dpp v73, v100 row_shr:1 row_mask:0xf bank_mask:0xf
	v_mul_f32_e32 v73, v212, v73
	v_mov_b32_dpp v77, v100 row_shr:2 row_mask:0xf bank_mask:0xf
	v_fmac_f32_e32 v73, v100, v210
	v_fmac_f32_e32 v73, v200, v77
	v_add_f32_e32 v73, v208, v73
	v_mul_f32_e32 v77, 0xbfb8aa3b, v73
	v_exp_f32_e32 v77, v77
	v_mov_b32_dpp v81, v96 row_shr:1 row_mask:0xf bank_mask:0xf
	v_mov_b32_dpp v108, v176 row_ror:2 row_mask:0xf bank_mask:0xf bound_ctrl:1
	v_mul_f32_e32 v81, v206, v81
	v_add_f32_e32 v77, 1.0, v77
	v_rcp_f32_e32 v77, v77
	v_mov_b32_dpp v108, v96 row_shr:2 row_mask:0xf bank_mask:0xf
	v_fmac_f32_e32 v81, v96, v202
	v_fmac_f32_e32 v81, v180, v108
	v_mul_f32_e32 v73, v73, v77
	v_mov_b32_dpp v77, v183 row_ror:1 row_mask:0xf bank_mask:0xf bound_ctrl:1
	v_add_f32_e32 v81, v204, v81
	v_mul_f32_e32 v73, v81, v73
	v_mov_b32_dpp v77, v101 row_shr:1 row_mask:0xf bank_mask:0xf
	v_mov_b32_dpp v81, v183 row_ror:2 row_mask:0xf bank_mask:0xf bound_ctrl:1
	v_mul_f32_e32 v77, v213, v77
	v_fmac_f32_e32 v77, v101, v211
	v_mov_b32_dpp v81, v101 row_shr:2 row_mask:0xf bank_mask:0xf
	v_fmac_f32_e32 v77, v201, v81
	v_add_f32_e32 v77, v209, v77
	v_mul_f32_e32 v81, 0xbfb8aa3b, v77
	v_exp_f32_e32 v81, v81
	v_mov_b32_dpp v108, v177 row_ror:1 row_mask:0xf bank_mask:0xf bound_ctrl:1
	v_mov_b32_dpp v109, v177 row_ror:2 row_mask:0xf bank_mask:0xf bound_ctrl:1
	v_add_f32_e32 v81, 1.0, v81
	v_mov_b32_dpp v108, v97 row_shr:1 row_mask:0xf bank_mask:0xf
	v_rcp_f32_e32 v81, v81
	v_mul_f32_e32 v108, v207, v108
	v_mov_b32_dpp v109, v97 row_shr:2 row_mask:0xf bank_mask:0xf
	v_fmac_f32_e32 v108, v97, v203
	v_fmac_f32_e32 v108, v181, v109
	v_add_f32_e32 v108, v205, v108
	v_mul_f32_e32 v77, v77, v81
	v_mul_f32_e32 v77, v108, v77
	v_cvt_pk_bf16_f32 v108, v73, v77
	v_lshlrev_b64 v[176:177], 2, v[178:179]
	v_lshl_add_u64 v[178:179], s[16:17], 0, v[176:177]
	v_lshl_add_u64 v[182:183], s[24:25], 0, v[176:177]
	global_load_dwordx2 v[184:185], v[164:165], off offset:8
	global_load_dwordx2 v[192:193], v[166:167], off offset:8
	v_lshl_add_u64 v[186:187], s[26:27], 0, v[176:177]
	v_lshl_add_u64 v[188:189], s[28:29], 0, v[176:177]
	global_load_dwordx2 v[196:197], v[178:179], off
	global_load_dwordx2 v[194:195], v[182:183], off
	s_nop 0
	global_load_dwordx2 v[182:183], v[186:187], off
	global_load_dwordx2 v[190:191], v[188:189], off
	v_lshl_add_u64 v[178:179], s[30:31], 0, v[176:177]
	v_lshl_add_u64 v[176:177], s[52:53], 0, v[176:177]
	global_load_dwordx2 v[186:187], v[178:179], off
	global_load_dwordx2 v[188:189], v[176:177], off
	v_mul_f32_dpp v77, v92, v212 row_shr:1 row_mask:0xf bank_mask:0xf bound_ctrl:1
	v_mov_b32_dpp v73, v92 row_shr:2 row_mask:0xf bank_mask:0xf bound_ctrl:1
	v_fmac_f32_e32 v77, v92, v210
	v_fmac_f32_e32 v77, v200, v73
	v_add_f32_e32 v73, v208, v77
	v_mul_f32_e32 v77, 0xbfb8aa3b, v73
	v_exp_f32_e32 v77, v77
	v_mul_f32_dpp v109, v88, v206 row_shr:1 row_mask:0xf bank_mask:0xf bound_ctrl:1
	v_mov_b32_dpp v81, v88 row_shr:2 row_mask:0xf bank_mask:0xf bound_ctrl:1
	v_fmac_f32_e32 v109, v88, v202
	v_add_f32_e32 v77, 1.0, v77
	v_rcp_f32_e32 v77, v77
	v_fmac_f32_e32 v109, v180, v81
	v_add_f32_e32 v81, v204, v109
	v_mul_f32_dpp v149, v89, v207 row_shr:1 row_mask:0xf bank_mask:0xf bound_ctrl:1
	v_mul_f32_dpp v109, v93, v213 row_shr:1 row_mask:0xf bank_mask:0xf bound_ctrl:1
	v_mul_f32_e32 v73, v73, v77
	v_mov_b32_dpp v77, v93 row_shr:2 row_mask:0xf bank_mask:0xf bound_ctrl:1
	v_fmac_f32_e32 v109, v93, v211
	v_fmac_f32_e32 v109, v201, v77
	v_add_f32_e32 v77, v209, v109
	v_mul_f32_e32 v109, 0xbfb8aa3b, v77
	v_exp_f32_e32 v109, v109
	v_mul_f32_e32 v73, v81, v73
	v_mov_b32_dpp v81, v89 row_shr:2 row_mask:0xf bank_mask:0xf bound_ctrl:1
	v_fmac_f32_e32 v149, v89, v203
	v_add_f32_e32 v109, 1.0, v109
	v_rcp_f32_e32 v109, v109
	v_fmac_f32_e32 v149, v181, v81
	v_add_f32_e32 v81, v205, v149
	v_mul_f32_e32 v77, v77, v109
	v_mul_f32_e32 v77, v81, v77
	v_cvt_pk_bf16_f32 v198, v73, v77
	v_mov_b32_dpp v73, v92 row_ror:1 row_mask:0xf bank_mask:0xf bound_ctrl:1
	s_nop 0
	v_mov_b32_dpp v77, v92 row_ror:2 row_mask:0xf bank_mask:0xf bound_ctrl:1
	v_mov_b32_dpp v81, v88 row_ror:1 row_mask:0xf bank_mask:0xf bound_ctrl:1
	v_mov_b32_dpp v73, v116 row_shr:1 row_mask:0xf bank_mask:0xf
	v_mul_f32_e32 v73, v212, v73
	v_mov_b32_dpp v77, v116 row_shr:2 row_mask:0xf bank_mask:0xf
	v_fmac_f32_e32 v73, v210, v116
	v_fmac_f32_e32 v73, v200, v77
	v_add_f32_e32 v73, v208, v73
	v_mul_f32_e32 v77, 0xbfb8aa3b, v73
	v_exp_f32_e32 v77, v77
	v_mov_b32_dpp v81, v112 row_shr:1 row_mask:0xf bank_mask:0xf
	v_mov_b32_dpp v109, v88 row_ror:2 row_mask:0xf bank_mask:0xf bound_ctrl:1
	v_mul_f32_e32 v81, v206, v81
	v_add_f32_e32 v77, 1.0, v77
	v_rcp_f32_e32 v77, v77
	v_mov_b32_dpp v109, v112 row_shr:2 row_mask:0xf bank_mask:0xf
	v_fmac_f32_e32 v81, v112, v202
	v_fmac_f32_e32 v81, v180, v109
	v_mul_f32_e32 v73, v73, v77
	v_mov_b32_dpp v77, v93 row_ror:1 row_mask:0xf bank_mask:0xf bound_ctrl:1
	v_add_f32_e32 v81, v204, v81
	v_mul_f32_e32 v73, v81, v73
	v_mov_b32_dpp v77, v117 row_shr:1 row_mask:0xf bank_mask:0xf
	v_mov_b32_dpp v81, v93 row_ror:2 row_mask:0xf bank_mask:0xf bound_ctrl:1
	v_mul_f32_e32 v77, v213, v77
	v_fmac_f32_e32 v77, v211, v117
	v_mov_b32_dpp v81, v117 row_shr:2 row_mask:0xf bank_mask:0xf
	v_fmac_f32_e32 v77, v201, v81
	v_add_f32_e32 v77, v209, v77
	v_mul_f32_e32 v81, 0xbfb8aa3b, v77
	v_exp_f32_e32 v81, v81
	v_mov_b32_dpp v109, v89 row_ror:1 row_mask:0xf bank_mask:0xf bound_ctrl:1
	v_mov_b32_dpp v149, v89 row_ror:2 row_mask:0xf bank_mask:0xf bound_ctrl:1
	v_add_f32_e32 v81, 1.0, v81
	v_mov_b32_dpp v109, v113 row_shr:1 row_mask:0xf bank_mask:0xf
	v_rcp_f32_e32 v81, v81
	v_mul_f32_e32 v109, v207, v109
	v_mov_b32_dpp v149, v113 row_shr:2 row_mask:0xf bank_mask:0xf
	v_fmac_f32_e32 v109, v113, v203
	v_fmac_f32_e32 v109, v181, v149
	v_add_f32_e32 v109, v205, v109
	v_mul_f32_e32 v77, v77, v81
	v_mul_f32_e32 v77, v109, v77
	v_cvt_pk_bf16_f32 v176, v73, v77
	v_mov_b32_dpp v73, v116 row_ror:1 row_mask:0xf bank_mask:0xf bound_ctrl:1
	s_nop 0
	v_mov_b32_dpp v77, v116 row_ror:2 row_mask:0xf bank_mask:0xf bound_ctrl:1
	v_mov_b32_dpp v81, v112 row_ror:1 row_mask:0xf bank_mask:0xf bound_ctrl:1
	v_mov_b32_dpp v73, v104 row_shr:1 row_mask:0xf bank_mask:0xf
	v_mul_f32_e32 v73, v212, v73
	v_mov_b32_dpp v77, v104 row_shr:2 row_mask:0xf bank_mask:0xf
	v_fmac_f32_e32 v73, v210, v104
	v_fmac_f32_e32 v73, v200, v77
	v_add_f32_e32 v73, v208, v73
	v_mul_f32_e32 v77, 0xbfb8aa3b, v73
	v_exp_f32_e32 v77, v77
	v_mov_b32_dpp v81, v84 row_shr:1 row_mask:0xf bank_mask:0xf
	v_mov_b32_dpp v109, v112 row_ror:2 row_mask:0xf bank_mask:0xf bound_ctrl:1
	v_mul_f32_e32 v81, v206, v81
	v_add_f32_e32 v77, 1.0, v77
	v_rcp_f32_e32 v77, v77
	v_mov_b32_dpp v109, v84 row_shr:2 row_mask:0xf bank_mask:0xf
	v_fmac_f32_e32 v81, v84, v202
	v_fmac_f32_e32 v81, v180, v109
	v_mul_f32_e32 v73, v73, v77
	v_mov_b32_dpp v77, v117 row_ror:1 row_mask:0xf bank_mask:0xf bound_ctrl:1
	v_add_f32_e32 v81, v204, v81
	v_mul_f32_e32 v73, v81, v73
	v_mov_b32_dpp v77, v105 row_shr:1 row_mask:0xf bank_mask:0xf
	v_mov_b32_dpp v81, v117 row_ror:2 row_mask:0xf bank_mask:0xf bound_ctrl:1
	v_mul_f32_e32 v77, v213, v77
	v_fmac_f32_e32 v77, v211, v105
	v_mov_b32_dpp v81, v105 row_shr:2 row_mask:0xf bank_mask:0xf
	v_fmac_f32_e32 v77, v201, v81
	v_add_f32_e32 v77, v209, v77
	v_mul_f32_e32 v81, 0xbfb8aa3b, v77
	v_exp_f32_e32 v81, v81
	v_mov_b32_dpp v109, v113 row_ror:1 row_mask:0xf bank_mask:0xf bound_ctrl:1
	v_mov_b32_dpp v112, v113 row_ror:2 row_mask:0xf bank_mask:0xf bound_ctrl:1
	v_add_f32_e32 v81, 1.0, v81
	v_mov_b32_dpp v109, v85 row_shr:1 row_mask:0xf bank_mask:0xf
	v_rcp_f32_e32 v81, v81
	v_mul_f32_e32 v109, v207, v109
	v_mov_b32_dpp v112, v85 row_shr:2 row_mask:0xf bank_mask:0xf
	v_fmac_f32_e32 v109, v85, v203
	v_fmac_f32_e32 v109, v181, v112
	v_add_f32_e32 v109, v205, v109
	v_mul_f32_e32 v77, v77, v81
	v_mul_f32_e32 v77, v109, v77
	v_cvt_pk_bf16_f32 v178, v73, v77
	v_mov_b32_dpp v73, v104 row_ror:1 row_mask:0xf bank_mask:0xf bound_ctrl:1
	s_nop 0
	v_mov_b32_dpp v77, v104 row_ror:2 row_mask:0xf bank_mask:0xf bound_ctrl:1
	v_mov_b32_dpp v81, v84 row_ror:1 row_mask:0xf bank_mask:0xf bound_ctrl:1
	v_mov_b32_dpp v73, v68 row_shr:1 row_mask:0xf bank_mask:0xf
	v_mul_f32_e32 v73, v212, v73
	v_mov_b32_dpp v77, v68 row_shr:2 row_mask:0xf bank_mask:0xf
	v_fmac_f32_e32 v73, v210, v68
	v_fmac_f32_e32 v73, v200, v77
	v_add_f32_e32 v73, v208, v73
	v_mul_f32_e32 v77, 0xbfb8aa3b, v73
	v_exp_f32_e32 v77, v77
	v_mov_b32_dpp v81, v64 row_shr:1 row_mask:0xf bank_mask:0xf
	v_mov_b32_dpp v84, v84 row_ror:2 row_mask:0xf bank_mask:0xf bound_ctrl:1
	v_mul_f32_e32 v81, v206, v81
	v_add_f32_e32 v77, 1.0, v77
	v_rcp_f32_e32 v77, v77
	v_mov_b32_dpp v84, v64 row_shr:2 row_mask:0xf bank_mask:0xf
	v_fmac_f32_e32 v81, v202, v64
	v_fmac_f32_e32 v81, v180, v84
	v_mul_f32_e32 v73, v73, v77
	v_mov_b32_dpp v77, v105 row_ror:1 row_mask:0xf bank_mask:0xf bound_ctrl:1
	v_add_f32_e32 v81, v204, v81
	v_mul_f32_e32 v73, v81, v73
	v_mov_b32_dpp v77, v69 row_shr:1 row_mask:0xf bank_mask:0xf
	v_mov_b32_dpp v81, v105 row_ror:2 row_mask:0xf bank_mask:0xf bound_ctrl:1
	v_mul_f32_e32 v77, v213, v77
	v_fmac_f32_e32 v77, v211, v69
	v_mov_b32_dpp v81, v69 row_shr:2 row_mask:0xf bank_mask:0xf
	v_fmac_f32_e32 v77, v201, v81
	v_add_f32_e32 v77, v209, v77
	v_mul_f32_e32 v81, 0xbfb8aa3b, v77
	v_exp_f32_e32 v81, v81
	v_mov_b32_dpp v84, v85 row_ror:1 row_mask:0xf bank_mask:0xf bound_ctrl:1
	v_mov_b32_dpp v85, v85 row_ror:2 row_mask:0xf bank_mask:0xf bound_ctrl:1
	v_add_f32_e32 v81, 1.0, v81
	v_mov_b32_dpp v84, v65 row_shr:1 row_mask:0xf bank_mask:0xf
	v_rcp_f32_e32 v81, v81
	v_mul_f32_e32 v84, v207, v84
	v_mov_b32_dpp v85, v65 row_shr:2 row_mask:0xf bank_mask:0xf
	v_fmac_f32_e32 v84, v203, v65
	v_fmac_f32_e32 v84, v181, v85
	v_add_f32_e32 v84, v205, v84
	v_mul_f32_e32 v77, v77, v81
	v_mul_f32_e32 v77, v84, v77
	v_cvt_pk_bf16_f32 v180, v73, v77
	s_waitcnt vmcnt(5)
	s_nop 0
	v_mul_f32_dpp v77, v126, v196 row_shr:1 row_mask:0xf bank_mask:0xf bound_ctrl:1
	v_mov_b32_dpp v73, v126 row_shr:2 row_mask:0xf bank_mask:0xf bound_ctrl:1
	s_waitcnt vmcnt(4)
	v_fmac_f32_e32 v77, v126, v194
	v_fmac_f32_e32 v77, v184, v73
	v_add_f32_e32 v73, v192, v77
	v_mul_f32_e32 v77, 0xbfb8aa3b, v73
	v_exp_f32_e32 v77, v77
	s_waitcnt vmcnt(2)
	v_mul_f32_dpp v84, v122, v190 row_shr:1 row_mask:0xf bank_mask:0xf bound_ctrl:1
	v_mov_b32_dpp v81, v122 row_shr:2 row_mask:0xf bank_mask:0xf bound_ctrl:1
	s_waitcnt vmcnt(1)
	v_fmac_f32_e32 v84, v122, v186
	v_add_f32_e32 v77, 1.0, v77
	v_rcp_f32_e32 v77, v77
	v_fmac_f32_e32 v84, v182, v81
	s_waitcnt vmcnt(0)
	v_add_f32_e32 v81, v188, v84
	v_mul_f32_dpp v85, v123, v191 row_shr:1 row_mask:0xf bank_mask:0xf bound_ctrl:1
	v_mul_f32_dpp v84, v127, v197 row_shr:1 row_mask:0xf bank_mask:0xf bound_ctrl:1
	v_mul_f32_e32 v73, v73, v77
	v_mov_b32_dpp v77, v127 row_shr:2 row_mask:0xf bank_mask:0xf bound_ctrl:1
	v_fmac_f32_e32 v84, v127, v195
	v_fmac_f32_e32 v84, v185, v77
	v_add_f32_e32 v77, v193, v84
	v_mul_f32_e32 v84, 0xbfb8aa3b, v77
	v_exp_f32_e32 v84, v84
	v_mul_f32_e32 v73, v81, v73
	v_mov_b32_dpp v81, v123 row_shr:2 row_mask:0xf bank_mask:0xf bound_ctrl:1
	v_fmac_f32_e32 v85, v123, v187
	v_add_f32_e32 v84, 1.0, v84
	v_rcp_f32_e32 v84, v84
	v_fmac_f32_e32 v85, v183, v81
	v_add_f32_e32 v81, v189, v85
	v_mul_f32_e32 v77, v77, v84
	v_mul_f32_e32 v77, v81, v77
	v_cvt_pk_bf16_f32 v81, v73, v77
	s_and_saveexec_b64 s[62:63], s[2:3]
	s_xor_b64 s[62:63], exec, s[62:63]
	s_cbranch_execz .LBB0_493
	v_mov_b64_e32 v[84:85], s[48:49]
	v_mad_i64_i32 v[84:85], s[64:65], v156, s93, v[84:85]
	v_lshl_add_u64 v[84:85], v[146:147], 1, v[84:85]
	v_mov_b32_e32 v251, v80
	v_mov_b32_e32 v252, v81

.LBB0_661:
	v_lshl_add_u32 v166, s73, 8, v174
	v_lshl_or_b32 v158, s71, 8, v176
	v_ashrrev_i32_e32 v167, 31, v166
	v_lshlrev_b64 v[128:129], 11, v[166:167]
	v_ashrrev_i32_e32 v159, 31, v158
	v_lshl_add_u64 v[160:161], s[46:47], 0, v[128:129]
	v_lshlrev_b64 v[128:129], 1, v[158:159]
	v_lshl_add_u64 v[188:189], v[160:161], 0, v[128:129]
	global_load_dwordx4 v[180:183], v[188:189], off
	global_load_dwordx4 v[184:187], v[188:189], off offset:256
	v_or_b32_e32 v168, 16, v166
	v_or_b32_e32 v162, 32, v166
	v_ashrrev_i32_e32 v169, 31, v168
	v_ashrrev_i32_e32 v163, 31, v162
	v_lshlrev_b64 v[130:131], 11, v[168:169]
	v_lshlrev_b64 v[132:133], 11, v[162:163]
	v_lshl_add_u64 v[130:131], s[46:47], 0, v[130:131]
	v_lshl_add_u64 v[132:133], s[46:47], 0, v[132:133]
	v_lshl_add_u64 v[170:171], v[130:131], 0, v[128:129]
	v_lshl_add_u64 v[164:165], v[132:133], 0, v[128:129]
	global_load_dwordx4 v[140:143], v[170:171], off
	global_load_dwordx4 v[136:139], v[170:171], off offset:256
	global_load_dwordx4 v[132:135], v[164:165], off
	global_load_dwordx4 v[128:131], v[164:165], off offset:256
	s_lshl_b32 s24, s71, 2
	s_ashr_i32 s25, s24, 31
	s_waitcnt vmcnt(0)
	v_lshlrev_b32_e32 v190, 16, v180
	v_and_b32_e32 v191, 0xffff0000, v180
	v_lshlrev_b32_e32 v180, 16, v181
	v_and_b32_e32 v181, 0xffff0000, v181
	v_lshlrev_b32_e32 v192, 16, v182
	v_and_b32_e32 v193, 0xffff0000, v182
	v_lshlrev_b32_e32 v182, 16, v183
	v_and_b32_e32 v183, 0xffff0000, v183
	v_lshlrev_b32_e32 v194, 16, v184
	v_and_b32_e32 v195, 0xffff0000, v184
	v_lshlrev_b32_e32 v184, 16, v185
	v_and_b32_e32 v185, 0xffff0000, v185
	v_lshlrev_b32_e32 v196, 16, v186
	v_and_b32_e32 v197, 0xffff0000, v186
	v_lshlrev_b32_e32 v186, 16, v187
	v_and_b32_e32 v187, 0xffff0000, v187
	v_pk_add_f32 v[126:127], v[126:127], v[180:181]
	v_pk_add_f32 v[124:125], v[124:125], v[190:191]
	v_pk_add_f32 v[122:123], v[122:123], v[182:183]
	v_pk_add_f32 v[120:121], v[120:121], v[192:193]
	v_pk_add_f32 v[118:119], v[118:119], v[184:185]
	v_pk_add_f32 v[116:117], v[116:117], v[194:195]
	v_pk_add_f32 v[180:181], v[114:115], v[186:187]
	v_pk_add_f32 v[182:183], v[112:113], v[196:197]
	v_cvt_pk_bf16_f32 v112, v124, v125
	v_cvt_pk_bf16_f32 v113, v126, v127
	v_mul_f32_e32 v114, v125, v125
	v_mul_f32_e32 v115, v127, v127
	v_mul_f32_e32 v125, v121, v121
	v_mul_f32_e32 v127, v123, v123
	v_mul_f32_e32 v184, v117, v117
	v_mul_f32_e32 v185, v119, v119
	v_mul_f32_e32 v186, v183, v183
	v_mul_f32_e32 v187, v181, v181
	v_fmac_f32_e32 v114, v124, v124
	v_fmac_f32_e32 v115, v126, v126
	v_fmac_f32_e32 v125, v120, v120
	v_fmac_f32_e32 v127, v122, v122
	v_fmac_f32_e32 v184, v116, v116
	v_fmac_f32_e32 v185, v118, v118
	v_fmac_f32_e32 v186, v182, v182
	v_fmac_f32_e32 v187, v180, v180
	v_add_f32_e32 v114, v114, v115
	v_add_f32_e32 v115, v125, v127
	v_add_f32_e32 v124, v184, v185
	v_add_f32_e32 v125, v186, v187
	v_add_f32_e32 v114, v114, v115
	v_add_f32_e32 v115, v124, v125
	v_add_f32_e32 v124, v114, v115
	v_mov_b32_e32 v125, v124
	v_cvt_pk_bf16_f32 v114, v120, v121
	v_cvt_pk_bf16_f32 v115, v122, v123
	global_store_dwordx4 v[188:189], v[112:115], off
	s_waitcnt lgkmcnt(0)
	s_nop 0
	s_nop 1
	v_permlane16_swap_b32_e32 v125, v124
	v_add_f32_e32 v112, v124, v125
	ds_bpermute_b32 v113, v173, v112
	v_cvt_pk_bf16_f32 v114, v116, v117
	v_cvt_pk_bf16_f32 v115, v118, v119
	v_cvt_pk_bf16_f32 v116, v182, v183
	v_cvt_pk_bf16_f32 v117, v180, v181
	global_store_dwordx4 v[188:189], v[114:117], off offset:256
	s_and_saveexec_b64 s[26:27], s[2:3]
	s_cbranch_execz .LBB0_663
	v_lshlrev_b64 v[114:115], 6, v[166:167]
	v_lshl_add_u64 v[114:115], s[8:9], 0, v[114:115]
	v_lshl_add_u64 v[114:115], s[24:25], 2, v[114:115]
	s_lshl_b32 s12, s63, 2
	v_lshl_add_u64 v[114:115], v[114:115], 0, s[12:13]
	s_waitcnt lgkmcnt(0)
	v_add_f32_e32 v112, v112, v113
	global_store_dword v[114:115], v112, off
.LBB0_663:
	s_or_b64 exec, exec, s[26:27]
	v_or_b32_e32 v120, 48, v166
	v_ashrrev_i32_e32 v121, 31, v120
	s_waitcnt lgkmcnt(0)
	v_lshlrev_b64 v[112:113], 11, v[120:121]
	v_lshl_add_u64 v[112:113], s[46:47], 0, v[112:113]
	v_lshl_add_u64 v[122:123], v[158:159], 1, v[112:113]
	global_load_dwordx4 v[116:119], v[122:123], off
	global_load_dwordx4 v[112:115], v[122:123], off offset:256
	v_lshlrev_b32_e32 v124, 16, v140
	v_and_b32_e32 v125, 0xffff0000, v140
	v_lshlrev_b32_e32 v126, 16, v141
	v_and_b32_e32 v127, 0xffff0000, v141
	v_pk_add_f32 v[110:111], v[110:111], v[126:127]
	v_pk_add_f32 v[108:109], v[108:109], v[124:125]
	v_lshlrev_b32_e32 v124, 16, v142
	v_and_b32_e32 v125, 0xffff0000, v142
	v_lshlrev_b32_e32 v126, 16, v143
	v_and_b32_e32 v127, 0xffff0000, v143
	v_pk_add_f32 v[126:127], v[106:107], v[126:127]
	v_pk_add_f32 v[106:107], v[104:105], v[124:125]
	v_cvt_pk_bf16_f32 v104, v108, v109
	v_mul_f32_e32 v109, v109, v109
	v_fmac_f32_e32 v109, v108, v108
	v_mul_f32_e32 v108, v111, v111
	v_fmac_f32_e32 v108, v110, v110
	v_cvt_pk_bf16_f32 v105, v110, v111
	v_add_f32_e32 v108, v109, v108
	v_mul_f32_e32 v109, v107, v107
	v_mul_f32_e32 v110, v127, v127
	v_fmac_f32_e32 v109, v106, v106
	v_fmac_f32_e32 v110, v126, v126
	v_add_f32_e32 v109, v109, v110
	v_add_f32_e32 v124, v108, v109
	v_lshlrev_b32_e32 v108, 16, v136
	v_and_b32_e32 v109, 0xffff0000, v136
	v_lshlrev_b32_e32 v110, 16, v137
	v_and_b32_e32 v111, 0xffff0000, v137
	v_pk_add_f32 v[102:103], v[102:103], v[110:111]
	v_pk_add_f32 v[100:101], v[100:101], v[108:109]
	v_lshlrev_b32_e32 v108, 16, v138
	v_and_b32_e32 v109, 0xffff0000, v138
	v_lshlrev_b32_e32 v110, 16, v139
	v_and_b32_e32 v111, 0xffff0000, v139
	v_pk_add_f32 v[108:109], v[96:97], v[108:109]
	v_mul_f32_e32 v96, v101, v101
	v_mul_f32_e32 v97, v103, v103
	v_pk_add_f32 v[110:111], v[98:99], v[110:111]
	v_fmac_f32_e32 v96, v100, v100
	v_fmac_f32_e32 v97, v102, v102
	v_add_f32_e32 v96, v96, v97
	v_mul_f32_e32 v97, v109, v109
	v_mul_f32_e32 v98, v111, v111
	v_fmac_f32_e32 v97, v108, v108
	v_fmac_f32_e32 v98, v110, v110
	v_add_f32_e32 v97, v97, v98
	v_add_f32_e32 v96, v96, v97
	v_add_f32_e32 v96, v124, v96
	v_mov_b32_e32 v97, v96
	v_cvt_pk_bf16_f32 v106, v106, v107
	v_cvt_pk_bf16_f32 v107, v126, v127
	global_store_dwordx4 v[170:171], v[104:107], off
	v_cvt_pk_bf16_f32 v98, v100, v101
	s_waitcnt lgkmcnt(0)
	s_nop 1
	v_permlane16_swap_b32_e32 v97, v96
	v_add_f32_e32 v96, v96, v97
	ds_bpermute_b32 v97, v173, v96
	v_cvt_pk_bf16_f32 v99, v102, v103
	v_cvt_pk_bf16_f32 v100, v108, v109
	v_cvt_pk_bf16_f32 v101, v110, v111
	global_store_dwordx4 v[170:171], v[98:101], off offset:256
	s_and_saveexec_b64 s[26:27], s[2:3]
	s_cbranch_execz .LBB0_665
	v_lshlrev_b64 v[98:99], 6, v[168:169]
	v_lshl_add_u64 v[98:99], s[8:9], 0, v[98:99]
	v_lshl_add_u64 v[98:99], s[24:25], 2, v[98:99]
	s_lshl_b32 s12, s63, 2
	v_lshl_add_u64 v[98:99], v[98:99], 0, s[12:13]
	s_waitcnt lgkmcnt(0)
	v_add_f32_e32 v96, v96, v97
	global_store_dword v[98:99], v96, off
.LBB0_665:
	s_or_b64 exec, exec, s[26:27]
	v_add_u32_e32 v104, 0x80, v166
	v_ashrrev_i32_e32 v105, 31, v104
	s_waitcnt lgkmcnt(0)
	v_lshlrev_b64 v[96:97], 11, v[104:105]
	v_lshl_add_u64 v[96:97], s[46:47], 0, v[96:97]
	v_lshl_add_u64 v[106:107], v[158:159], 1, v[96:97]
	global_load_dwordx4 v[100:103], v[106:107], off
	global_load_dwordx4 v[96:99], v[106:107], off offset:256
	v_lshlrev_b32_e32 v108, 16, v132
	v_and_b32_e32 v109, 0xffff0000, v132
	v_lshlrev_b32_e32 v110, 16, v133
	v_and_b32_e32 v111, 0xffff0000, v133
	v_pk_add_f32 v[94:95], v[94:95], v[110:111]
	v_pk_add_f32 v[92:93], v[92:93], v[108:109]
	v_lshlrev_b32_e32 v108, 16, v134
	v_and_b32_e32 v109, 0xffff0000, v134
	v_lshlrev_b32_e32 v110, 16, v135
	v_and_b32_e32 v111, 0xffff0000, v135
	v_pk_add_f32 v[110:111], v[90:91], v[110:111]
	v_pk_add_f32 v[90:91], v[88:89], v[108:109]
	v_cvt_pk_bf16_f32 v88, v92, v93
	v_mul_f32_e32 v93, v93, v93
	v_fmac_f32_e32 v93, v92, v92
	v_mul_f32_e32 v92, v95, v95
	v_fmac_f32_e32 v92, v94, v94
	v_cvt_pk_bf16_f32 v89, v94, v95
	v_add_f32_e32 v92, v93, v92
	v_mul_f32_e32 v93, v91, v91
	v_mul_f32_e32 v94, v111, v111
	v_fmac_f32_e32 v93, v90, v90
	v_fmac_f32_e32 v94, v110, v110
	v_add_f32_e32 v93, v93, v94
	v_add_f32_e32 v108, v92, v93
	v_lshlrev_b32_e32 v92, 16, v128
	v_and_b32_e32 v93, 0xffff0000, v128
	v_lshlrev_b32_e32 v94, 16, v129
	v_and_b32_e32 v95, 0xffff0000, v129
	v_pk_add_f32 v[86:87], v[86:87], v[94:95]
	v_pk_add_f32 v[84:85], v[84:85], v[92:93]
	v_lshlrev_b32_e32 v92, 16, v130
	v_and_b32_e32 v93, 0xffff0000, v130
	v_lshlrev_b32_e32 v94, 16, v131
	v_and_b32_e32 v95, 0xffff0000, v131
	v_pk_add_f32 v[92:93], v[80:81], v[92:93]
	v_mul_f32_e32 v80, v85, v85
	v_mul_f32_e32 v81, v87, v87
	v_pk_add_f32 v[94:95], v[82:83], v[94:95]
	v_fmac_f32_e32 v80, v84, v84
	v_fmac_f32_e32 v81, v86, v86
	v_add_f32_e32 v80, v80, v81
	v_mul_f32_e32 v81, v93, v93
	v_mul_f32_e32 v82, v95, v95
	v_fmac_f32_e32 v81, v92, v92
	v_fmac_f32_e32 v82, v94, v94
	v_add_f32_e32 v81, v81, v82
	v_add_f32_e32 v80, v80, v81
	v_add_f32_e32 v80, v108, v80
	v_mov_b32_e32 v81, v80
	v_cvt_pk_bf16_f32 v90, v90, v91
	v_cvt_pk_bf16_f32 v91, v110, v111
	global_store_dwordx4 v[164:165], v[88:91], off
	v_cvt_pk_bf16_f32 v82, v84, v85
	s_waitcnt lgkmcnt(0)
	s_nop 1
	v_permlane16_swap_b32_e32 v81, v80
	v_add_f32_e32 v80, v80, v81
	ds_bpermute_b32 v81, v173, v80
	v_cvt_pk_bf16_f32 v83, v86, v87
	v_cvt_pk_bf16_f32 v84, v92, v93
	v_cvt_pk_bf16_f32 v85, v94, v95
	global_store_dwordx4 v[164:165], v[82:85], off offset:256
	s_and_saveexec_b64 s[26:27], s[2:3]
	s_cbranch_execz .LBB0_667
	v_lshlrev_b64 v[82:83], 6, v[162:163]
	v_lshl_add_u64 v[82:83], s[8:9], 0, v[82:83]
	v_lshl_add_u64 v[82:83], s[24:25], 2, v[82:83]
	s_lshl_b32 s12, s63, 2
	v_lshl_add_u64 v[82:83], v[82:83], 0, s[12:13]
	s_waitcnt lgkmcnt(0)
	v_add_f32_e32 v80, v80, v81
	global_store_dword v[82:83], v80, off
.LBB0_667:
	s_or_b64 exec, exec, s[26:27]
	s_waitcnt lgkmcnt(0)
	v_lshl_add_u64 v[80:81], v[158:159], 1, v[160:161]
	v_lshl_add_u64 v[88:89], v[80:81], 0, s[20:21]
	v_add_co_u32_e32 v80, vcc, 0x48000, v80
	s_waitcnt vmcnt(7)
	v_lshlrev_b32_e32 v90, 16, v116
	v_addc_co_u32_e32 v81, vcc, 0, v81, vcc
	global_load_dwordx4 v[84:87], v[80:81], off
	s_nop 0
	global_load_dwordx4 v[80:83], v[88:89], off offset:256
	v_and_b32_e32 v91, 0xffff0000, v116
	v_lshlrev_b32_e32 v92, 16, v117
	v_and_b32_e32 v93, 0xffff0000, v117
	v_pk_add_f32 v[78:79], v[78:79], v[92:93]
	v_pk_add_f32 v[76:77], v[76:77], v[90:91]
	v_lshlrev_b32_e32 v90, 16, v118
	v_and_b32_e32 v91, 0xffff0000, v118
	v_lshlrev_b32_e32 v92, 16, v119
	v_and_b32_e32 v93, 0xffff0000, v119
	v_pk_add_f32 v[92:93], v[74:75], v[92:93]
	v_pk_add_f32 v[74:75], v[72:73], v[90:91]
	v_cvt_pk_bf16_f32 v72, v76, v77
	v_mul_f32_e32 v77, v77, v77
	v_fmac_f32_e32 v77, v76, v76
	v_mul_f32_e32 v76, v79, v79
	v_fmac_f32_e32 v76, v78, v78
	v_cvt_pk_bf16_f32 v73, v78, v79
	v_add_f32_e32 v76, v77, v76
	v_mul_f32_e32 v77, v75, v75
	v_mul_f32_e32 v78, v93, v93
	v_fmac_f32_e32 v77, v74, v74
	v_fmac_f32_e32 v78, v92, v92
	v_add_f32_e32 v77, v77, v78
	v_add_f32_e32 v90, v76, v77
	s_waitcnt vmcnt(8)
	v_lshlrev_b32_e32 v76, 16, v112
	v_and_b32_e32 v77, 0xffff0000, v112
	v_lshlrev_b32_e32 v78, 16, v113
	v_and_b32_e32 v79, 0xffff0000, v113
	v_pk_add_f32 v[70:71], v[70:71], v[78:79]
	v_pk_add_f32 v[68:69], v[68:69], v[76:77]
	v_lshlrev_b32_e32 v76, 16, v114
	v_and_b32_e32 v77, 0xffff0000, v114
	v_lshlrev_b32_e32 v78, 16, v115
	v_and_b32_e32 v79, 0xffff0000, v115
	v_pk_add_f32 v[76:77], v[64:65], v[76:77]
	v_mul_f32_e32 v64, v69, v69
	v_mul_f32_e32 v65, v71, v71
	v_pk_add_f32 v[78:79], v[66:67], v[78:79]
	v_fmac_f32_e32 v64, v68, v68
	v_fmac_f32_e32 v65, v70, v70
	v_add_f32_e32 v64, v64, v65
	v_mul_f32_e32 v65, v77, v77
	v_mul_f32_e32 v66, v79, v79
	v_fmac_f32_e32 v65, v76, v76
	v_fmac_f32_e32 v66, v78, v78
	v_add_f32_e32 v65, v65, v66
	v_add_f32_e32 v64, v64, v65
	v_add_f32_e32 v64, v90, v64
	v_mov_b32_e32 v65, v64
	v_cvt_pk_bf16_f32 v74, v74, v75
	v_cvt_pk_bf16_f32 v75, v92, v93
	global_store_dwordx4 v[122:123], v[72:75], off
	v_cvt_pk_bf16_f32 v66, v68, v69
	s_waitcnt lgkmcnt(0)
	s_nop 1
	v_permlane16_swap_b32_e32 v65, v64
	v_add_f32_e32 v64, v64, v65
	ds_bpermute_b32 v65, v173, v64
	v_cvt_pk_bf16_f32 v67, v70, v71
	v_cvt_pk_bf16_f32 v68, v76, v77
	v_cvt_pk_bf16_f32 v69, v78, v79
	global_store_dwordx4 v[122:123], v[66:69], off offset:256
	s_and_saveexec_b64 s[26:27], s[2:3]
	s_cbranch_execz .LBB0_669
	v_lshlrev_b64 v[66:67], 6, v[120:121]
	v_lshl_add_u64 v[66:67], s[8:9], 0, v[66:67]
	v_lshl_add_u64 v[66:67], s[24:25], 2, v[66:67]
	s_lshl_b32 s12, s63, 2
	v_lshl_add_u64 v[66:67], v[66:67], 0, s[12:13]
	s_waitcnt lgkmcnt(0)
	v_add_f32_e32 v64, v64, v65
	global_store_dword v[66:67], v64, off
.LBB0_669:
	s_or_b64 exec, exec, s[26:27]
	v_or_b32_e32 v72, 32, v104
	v_ashrrev_i32_e32 v73, 31, v72
	s_waitcnt lgkmcnt(0)
	v_lshlrev_b64 v[64:65], 11, v[72:73]
	v_lshl_add_u64 v[64:65], s[46:47], 0, v[64:65]
	v_lshl_add_u64 v[74:75], v[158:159], 1, v[64:65]
	global_load_dwordx4 v[68:71], v[74:75], off
	global_load_dwordx4 v[64:67], v[74:75], off offset:256
	s_waitcnt vmcnt(9)
	v_lshlrev_b32_e32 v76, 16, v100
	v_and_b32_e32 v77, 0xffff0000, v100
	v_lshlrev_b32_e32 v78, 16, v101
	v_and_b32_e32 v79, 0xffff0000, v101
	v_pk_add_f32 v[62:63], v[62:63], v[78:79]
	v_pk_add_f32 v[60:61], v[60:61], v[76:77]
	v_lshlrev_b32_e32 v76, 16, v102
	v_and_b32_e32 v77, 0xffff0000, v102
	v_lshlrev_b32_e32 v78, 16, v103
	v_and_b32_e32 v79, 0xffff0000, v103
	v_pk_add_f32 v[78:79], v[58:59], v[78:79]
	v_pk_add_f32 v[58:59], v[56:57], v[76:77]
	v_cvt_pk_bf16_f32 v56, v60, v61
	v_mul_f32_e32 v61, v61, v61
	v_fmac_f32_e32 v61, v60, v60
	v_mul_f32_e32 v60, v63, v63
	v_fmac_f32_e32 v60, v62, v62
	v_cvt_pk_bf16_f32 v57, v62, v63
	v_add_f32_e32 v60, v61, v60
	v_mul_f32_e32 v61, v59, v59
	v_mul_f32_e32 v62, v79, v79
	v_fmac_f32_e32 v61, v58, v58
	v_fmac_f32_e32 v62, v78, v78
	v_add_f32_e32 v61, v61, v62
	v_add_f32_e32 v76, v60, v61
	s_waitcnt vmcnt(8)
	v_lshlrev_b32_e32 v60, 16, v96
	v_and_b32_e32 v61, 0xffff0000, v96
	v_lshlrev_b32_e32 v62, 16, v97
	v_and_b32_e32 v63, 0xffff0000, v97
	v_pk_add_f32 v[54:55], v[54:55], v[62:63]
	v_pk_add_f32 v[52:53], v[52:53], v[60:61]
	v_lshlrev_b32_e32 v60, 16, v98
	v_and_b32_e32 v61, 0xffff0000, v98
	v_lshlrev_b32_e32 v62, 16, v99
	v_and_b32_e32 v63, 0xffff0000, v99
	v_pk_add_f32 v[60:61], v[48:49], v[60:61]
	v_mul_f32_e32 v48, v53, v53
	v_mul_f32_e32 v49, v55, v55
	v_pk_add_f32 v[62:63], v[50:51], v[62:63]
	v_fmac_f32_e32 v48, v52, v52
	v_fmac_f32_e32 v49, v54, v54
	v_add_f32_e32 v48, v48, v49
	v_mul_f32_e32 v49, v61, v61
	v_mul_f32_e32 v50, v63, v63
	v_fmac_f32_e32 v49, v60, v60
	v_fmac_f32_e32 v50, v62, v62
	v_add_f32_e32 v49, v49, v50
	v_add_f32_e32 v48, v48, v49
	v_add_f32_e32 v48, v76, v48
	v_mov_b32_e32 v49, v48
	v_cvt_pk_bf16_f32 v58, v58, v59
	v_cvt_pk_bf16_f32 v59, v78, v79
	global_store_dwordx4 v[106:107], v[56:59], off
	v_cvt_pk_bf16_f32 v50, v52, v53
	s_waitcnt lgkmcnt(0)
	s_nop 1
	v_permlane16_swap_b32_e32 v49, v48
	v_add_f32_e32 v48, v48, v49
	ds_bpermute_b32 v49, v173, v48
	v_cvt_pk_bf16_f32 v51, v54, v55
	v_cvt_pk_bf16_f32 v52, v60, v61
	v_cvt_pk_bf16_f32 v53, v62, v63
	global_store_dwordx4 v[106:107], v[50:53], off offset:256
	s_and_saveexec_b64 s[26:27], s[2:3]
	s_cbranch_execz .LBB0_671
	v_lshlrev_b64 v[50:51], 6, v[104:105]
	v_lshl_add_u64 v[50:51], s[8:9], 0, v[50:51]
	v_lshl_add_u64 v[50:51], s[24:25], 2, v[50:51]
	s_lshl_b32 s12, s63, 2
	v_lshl_add_u64 v[50:51], v[50:51], 0, s[12:13]
	s_waitcnt lgkmcnt(0)
	v_add_f32_e32 v48, v48, v49
	global_store_dword v[50:51], v48, off
.LBB0_671:
	s_or_b64 exec, exec, s[26:27]
	v_or_b32_e32 v56, 48, v104
	v_ashrrev_i32_e32 v57, 31, v56
	s_waitcnt lgkmcnt(0)
	v_lshlrev_b64 v[48:49], 11, v[56:57]
	v_lshl_add_u64 v[48:49], s[46:47], 0, v[48:49]
	v_lshl_add_u64 v[58:59], v[158:159], 1, v[48:49]
	global_load_dwordx4 v[52:55], v[58:59], off
	global_load_dwordx4 v[48:51], v[58:59], off offset:256
	s_waitcnt vmcnt(9)
	v_lshlrev_b32_e32 v60, 16, v84
	v_and_b32_e32 v61, 0xffff0000, v84
	v_lshlrev_b32_e32 v62, 16, v85
	v_and_b32_e32 v63, 0xffff0000, v85
	v_pk_add_f32 v[46:47], v[46:47], v[62:63]
	v_pk_add_f32 v[44:45], v[44:45], v[60:61]
	v_lshlrev_b32_e32 v60, 16, v86
	v_and_b32_e32 v61, 0xffff0000, v86
	v_lshlrev_b32_e32 v62, 16, v87
	v_and_b32_e32 v63, 0xffff0000, v87
	v_pk_add_f32 v[62:63], v[42:43], v[62:63]
	v_pk_add_f32 v[42:43], v[40:41], v[60:61]
	v_cvt_pk_bf16_f32 v40, v44, v45
	v_mul_f32_e32 v45, v45, v45
	v_fmac_f32_e32 v45, v44, v44
	v_mul_f32_e32 v44, v47, v47
	v_fmac_f32_e32 v44, v46, v46
	v_cvt_pk_bf16_f32 v41, v46, v47
	v_add_f32_e32 v44, v45, v44
	v_mul_f32_e32 v45, v43, v43
	v_mul_f32_e32 v46, v63, v63
	v_fmac_f32_e32 v45, v42, v42
	v_fmac_f32_e32 v46, v62, v62
	v_add_f32_e32 v45, v45, v46
	v_add_f32_e32 v60, v44, v45
	s_waitcnt vmcnt(8)
	v_lshlrev_b32_e32 v44, 16, v80
	v_and_b32_e32 v45, 0xffff0000, v80
	v_lshlrev_b32_e32 v46, 16, v81
	v_and_b32_e32 v47, 0xffff0000, v81
	v_pk_add_f32 v[38:39], v[38:39], v[46:47]
	v_pk_add_f32 v[36:37], v[36:37], v[44:45]
	v_lshlrev_b32_e32 v44, 16, v82
	v_and_b32_e32 v45, 0xffff0000, v82
	v_lshlrev_b32_e32 v46, 16, v83
	v_and_b32_e32 v47, 0xffff0000, v83
	v_pk_add_f32 v[44:45], v[32:33], v[44:45]
	v_mul_f32_e32 v32, v37, v37
	v_mul_f32_e32 v33, v39, v39
	v_pk_add_f32 v[46:47], v[34:35], v[46:47]
	v_fmac_f32_e32 v32, v36, v36
	v_fmac_f32_e32 v33, v38, v38
	v_add_f32_e32 v32, v32, v33
	v_mul_f32_e32 v33, v45, v45
	v_mul_f32_e32 v34, v47, v47
	v_fmac_f32_e32 v33, v44, v44
	v_fmac_f32_e32 v34, v46, v46
	v_add_f32_e32 v33, v33, v34
	v_add_f32_e32 v32, v32, v33
	v_add_f32_e32 v32, v60, v32
	v_mov_b32_e32 v33, v32
	v_cvt_pk_bf16_f32 v42, v42, v43
	v_cvt_pk_bf16_f32 v43, v62, v63
	global_store_dwordx4 v[88:89], v[40:43], off
	v_cvt_pk_bf16_f32 v34, v36, v37
	s_waitcnt lgkmcnt(0)
	s_nop 1
	v_permlane16_swap_b32_e32 v33, v32
	v_add_f32_e32 v32, v32, v33
	ds_bpermute_b32 v33, v173, v32
	v_cvt_pk_bf16_f32 v35, v38, v39
	v_cvt_pk_bf16_f32 v36, v44, v45
	v_cvt_pk_bf16_f32 v37, v46, v47
	global_store_dwordx4 v[88:89], v[34:37], off offset:256
	s_and_saveexec_b64 s[26:27], s[2:3]
	s_cbranch_execz .LBB0_673
	v_or_b32_e32 v34, 16, v104
	v_ashrrev_i32_e32 v35, 31, v34
	v_lshlrev_b64 v[34:35], 6, v[34:35]
	v_lshl_add_u64 v[34:35], s[8:9], 0, v[34:35]
	v_lshl_add_u64 v[34:35], s[24:25], 2, v[34:35]
	s_lshl_b32 s12, s63, 2
	v_lshl_add_u64 v[34:35], v[34:35], 0, s[12:13]
	s_waitcnt lgkmcnt(0)
	v_add_f32_e32 v32, v32, v33
	global_store_dword v[34:35], v32, off
.LBB0_673:
	s_or_b64 exec, exec, s[26:27]
	s_waitcnt vmcnt(7)
	v_lshlrev_b32_e32 v32, 16, v68
	s_waitcnt lgkmcnt(0)
	v_and_b32_e32 v33, 0xffff0000, v68
	v_lshlrev_b32_e32 v34, 16, v69
	v_and_b32_e32 v35, 0xffff0000, v69
	v_pk_add_f32 v[30:31], v[30:31], v[34:35]
	v_pk_add_f32 v[28:29], v[28:29], v[32:33]
	v_lshlrev_b32_e32 v32, 16, v70
	v_and_b32_e32 v33, 0xffff0000, v70
	v_lshlrev_b32_e32 v34, 16, v71
	v_and_b32_e32 v35, 0xffff0000, v71
	v_pk_add_f32 v[34:35], v[26:27], v[34:35]
	v_pk_add_f32 v[26:27], v[24:25], v[32:33]
	v_cvt_pk_bf16_f32 v24, v28, v29
	v_mul_f32_e32 v29, v29, v29
	v_fmac_f32_e32 v29, v28, v28
	v_mul_f32_e32 v28, v31, v31
	v_fmac_f32_e32 v28, v30, v30
	v_cvt_pk_bf16_f32 v25, v30, v31
	v_add_f32_e32 v28, v29, v28
	v_mul_f32_e32 v29, v27, v27
	v_mul_f32_e32 v30, v35, v35
	v_fmac_f32_e32 v29, v26, v26
	v_fmac_f32_e32 v30, v34, v34
	v_add_f32_e32 v29, v29, v30
	v_add_f32_e32 v32, v28, v29
	s_waitcnt vmcnt(6)
	v_lshlrev_b32_e32 v28, 16, v64
	v_and_b32_e32 v29, 0xffff0000, v64
	v_lshlrev_b32_e32 v30, 16, v65
	v_and_b32_e32 v31, 0xffff0000, v65
	v_pk_add_f32 v[22:23], v[22:23], v[30:31]
	v_pk_add_f32 v[20:21], v[20:21], v[28:29]
	v_lshlrev_b32_e32 v28, 16, v66
	v_and_b32_e32 v29, 0xffff0000, v66
	v_lshlrev_b32_e32 v30, 16, v67
	v_and_b32_e32 v31, 0xffff0000, v67
	v_pk_add_f32 v[28:29], v[16:17], v[28:29]
	v_mul_f32_e32 v16, v21, v21
	v_mul_f32_e32 v17, v23, v23
	v_pk_add_f32 v[30:31], v[18:19], v[30:31]
	v_fmac_f32_e32 v16, v20, v20
	v_fmac_f32_e32 v17, v22, v22
	v_add_f32_e32 v16, v16, v17
	v_mul_f32_e32 v17, v29, v29
	v_mul_f32_e32 v18, v31, v31
	v_fmac_f32_e32 v17, v28, v28
	v_fmac_f32_e32 v18, v30, v30
	v_add_f32_e32 v17, v17, v18
	v_add_f32_e32 v16, v16, v17
	v_add_f32_e32 v16, v32, v16
	v_mov_b32_e32 v17, v16
	v_cvt_pk_bf16_f32 v26, v26, v27
	v_cvt_pk_bf16_f32 v27, v34, v35
	global_store_dwordx4 v[74:75], v[24:27], off
	v_cvt_pk_bf16_f32 v18, v20, v21
	s_waitcnt lgkmcnt(0)
	s_nop 1
	v_permlane16_swap_b32_e32 v17, v16
	v_add_f32_e32 v16, v16, v17
	ds_bpermute_b32 v17, v173, v16
	v_cvt_pk_bf16_f32 v19, v22, v23
	v_cvt_pk_bf16_f32 v20, v28, v29
	v_cvt_pk_bf16_f32 v21, v30, v31
	global_store_dwordx4 v[74:75], v[18:21], off offset:256
	s_and_saveexec_b64 s[26:27], s[2:3]
	s_cbranch_execz .LBB0_675
	v_lshlrev_b64 v[18:19], 6, v[72:73]
	v_lshl_add_u64 v[18:19], s[8:9], 0, v[18:19]
	v_lshl_add_u64 v[18:19], s[24:25], 2, v[18:19]
	s_lshl_b32 s12, s63, 2
	v_lshl_add_u64 v[18:19], v[18:19], 0, s[12:13]
	s_waitcnt lgkmcnt(0)
	v_add_f32_e32 v16, v16, v17
	global_store_dword v[18:19], v16, off
.LBB0_675:
	s_or_b64 exec, exec, s[26:27]
	s_waitcnt vmcnt(5)
	v_lshlrev_b32_e32 v16, 16, v52
	s_waitcnt lgkmcnt(0)
	v_and_b32_e32 v17, 0xffff0000, v52
	v_lshlrev_b32_e32 v18, 16, v53
	v_and_b32_e32 v19, 0xffff0000, v53
	v_pk_add_f32 v[14:15], v[14:15], v[18:19]
	v_pk_add_f32 v[12:13], v[12:13], v[16:17]
	v_lshlrev_b32_e32 v16, 16, v54
	v_and_b32_e32 v17, 0xffff0000, v54
	v_lshlrev_b32_e32 v18, 16, v55
	v_and_b32_e32 v19, 0xffff0000, v55
	v_pk_add_f32 v[18:19], v[10:11], v[18:19]
	v_pk_add_f32 v[10:11], v[8:9], v[16:17]
	v_cvt_pk_bf16_f32 v8, v12, v13
	v_mul_f32_e32 v13, v13, v13
	v_fmac_f32_e32 v13, v12, v12
	v_mul_f32_e32 v12, v15, v15
	v_fmac_f32_e32 v12, v14, v14
	v_cvt_pk_bf16_f32 v9, v14, v15
	v_add_f32_e32 v12, v13, v12
	v_mul_f32_e32 v13, v11, v11
	v_mul_f32_e32 v14, v19, v19
	v_fmac_f32_e32 v13, v10, v10
	v_fmac_f32_e32 v14, v18, v18
	v_add_f32_e32 v13, v13, v14
	v_add_f32_e32 v16, v12, v13
	s_waitcnt vmcnt(4)
	v_lshlrev_b32_e32 v12, 16, v48
	v_and_b32_e32 v13, 0xffff0000, v48
	v_lshlrev_b32_e32 v14, 16, v49
	v_and_b32_e32 v15, 0xffff0000, v49
	v_pk_add_f32 v[6:7], v[6:7], v[14:15]
	v_pk_add_f32 v[4:5], v[4:5], v[12:13]
	v_lshlrev_b32_e32 v12, 16, v50
	v_and_b32_e32 v13, 0xffff0000, v50
	v_lshlrev_b32_e32 v14, 16, v51
	v_and_b32_e32 v15, 0xffff0000, v51
	v_pk_add_f32 v[12:13], v[0:1], v[12:13]
	v_mul_f32_e32 v0, v5, v5
	v_mul_f32_e32 v1, v7, v7
	v_pk_add_f32 v[14:15], v[2:3], v[14:15]
	v_fmac_f32_e32 v0, v4, v4
	v_fmac_f32_e32 v1, v6, v6
	v_add_f32_e32 v0, v0, v1
	v_mul_f32_e32 v1, v13, v13
	v_mul_f32_e32 v2, v15, v15
	v_fmac_f32_e32 v1, v12, v12
	v_fmac_f32_e32 v2, v14, v14
	v_add_f32_e32 v1, v1, v2
	v_add_f32_e32 v0, v0, v1
	v_add_f32_e32 v0, v16, v0
	v_mov_b32_e32 v1, v0
	v_cvt_pk_bf16_f32 v10, v10, v11
	v_cvt_pk_bf16_f32 v11, v18, v19
	global_store_dwordx4 v[58:59], v[8:11], off
	v_cvt_pk_bf16_f32 v2, v4, v5
	s_waitcnt lgkmcnt(0)
	s_nop 1
	v_permlane16_swap_b32_e32 v1, v0
	v_add_f32_e32 v0, v0, v1
	ds_bpermute_b32 v1, v173, v0
	v_cvt_pk_bf16_f32 v3, v6, v7
	v_cvt_pk_bf16_f32 v4, v12, v13
	v_cvt_pk_bf16_f32 v5, v14, v15
	global_store_dwordx4 v[58:59], v[2:5], off offset:256
	s_and_saveexec_b64 s[26:27], s[2:3]
	s_cbranch_execz .LBB0_677
	v_lshlrev_b64 v[2:3], 6, v[56:57]
	v_lshl_add_u64 v[2:3], s[8:9], 0, v[2:3]
	v_lshl_add_u64 v[2:3], s[24:25], 2, v[2:3]
	s_lshl_b32 s12, s63, 2
	v_lshl_add_u64 v[2:3], v[2:3], 0, s[12:13]
	s_waitcnt lgkmcnt(0)
	v_add_f32_e32 v0, v0, v1
	global_store_dword v[2:3], v0, off

.LBB0_718:
	v_lshl_add_u32 v162, s52, 8, v192
	v_or_b32_e32 v176, 16, v162
	v_or_b32_e32 v174, 32, v162
	v_ashrrev_i32_e32 v163, 31, v162
	v_ashrrev_i32_e32 v177, 31, v176
	v_ashrrev_i32_e32 v175, 31, v174
	v_lshlrev_b64 v[164:165], 6, v[162:163]
	v_lshlrev_b64 v[166:167], 6, v[176:177]
	v_lshlrev_b64 v[172:173], 6, v[174:175]
	v_lshl_add_u64 v[164:165], v[152:153], 0, v[164:165]
	v_lshl_add_u64 v[168:169], v[152:153], 0, v[166:167]
	v_lshl_add_u64 v[172:173], v[152:153], 0, v[172:173]
	global_load_dwordx4 v[164:167], v[164:165], off
	s_nop 0
	global_load_dwordx4 v[168:171], v[168:169], off
	s_waitcnt vmcnt(0)
	v_mov_b32_e32 v186, v165
	global_load_dwordx4 v[178:181], v[172:173], off
	v_or_b32_e32 v172, 48, v162
	v_ashrrev_i32_e32 v173, 31, v172
	v_lshlrev_b64 v[182:183], 6, v[172:173]
	v_lshl_add_u64 v[182:183], v[152:153], 0, v[182:183]
	global_load_dwordx4 v[182:185], v[182:183], off
	v_mov_b32_e32 v187, v166
	v_mov_b32_e32 v165, v167
	v_pk_add_f32 v[164:165], v[186:187], v[164:165]
	v_add_f32_e32 v166, v168, v169
	v_add_f32_e32 v167, v170, v171
	v_add_f32_e32 v164, v164, v165
	v_add_f32_e32 v165, v166, v167
	v_mov_b32_e32 v167, v164
	s_waitcnt lgkmcnt(0)
	s_nop 1
	v_permlane16_swap_b32_e32 v167, v164
	v_add_f32_e32 v164, v164, v167
	s_waitcnt vmcnt(1)
	v_add_f32_e32 v168, v178, v179
	v_add_f32_e32 v169, v180, v181
	v_add_f32_e32 v166, v168, v169
	v_mov_b32_e32 v168, v165
	s_waitcnt vmcnt(0)
	v_add_f32_e32 v170, v182, v183
	v_add_f32_e32 v171, v184, v185
	v_add_f32_e32 v169, v170, v171
	v_mov_b32_e32 v170, v166
	v_mov_b32_e32 v171, v169
	s_waitcnt lgkmcnt(2)
	s_nop 1
	v_permlane16_swap_b32_e32 v168, v165
	v_add_f32_e32 v212, v165, v168
	v_mov_b32_e32 v165, v164
	ds_bpermute_b32 v213, v195, v212
	s_waitcnt lgkmcnt(3)
	s_nop 1
	v_permlane16_swap_b32_e32 v170, v166
	v_add_f32_e32 v210, v166, v170
	s_waitcnt lgkmcnt(2)
	s_nop 1
	v_permlane16_swap_b32_e32 v171, v169
	v_add_f32_e32 v208, v169, v171
	ds_bpermute_b32 v211, v195, v210
	ds_bpermute_b32 v209, v195, v208
	s_waitcnt lgkmcnt(3)
	s_nop 1
	v_permlane32_swap_b32_e32 v165, v164
	v_add_f32_e32 v164, v164, v165
	v_fmamk_f32 v164, v164, 0x3a800000, v199
	v_rsq_f32_e32 v190, v164
	v_add_u32_e32 v170, 0x80, v162
	v_add_u32_e32 v168, 0x90, v162
	v_ashrrev_i32_e32 v171, 31, v170
	v_ashrrev_i32_e32 v169, 31, v168
	v_lshlrev_b64 v[164:165], 6, v[170:171]
	v_lshlrev_b64 v[166:167], 6, v[168:169]
	v_lshl_add_u64 v[164:165], v[152:153], 0, v[164:165]
	v_lshl_add_u64 v[166:167], v[152:153], 0, v[166:167]
	global_load_dwordx4 v[178:181], v[164:165], off
	global_load_dwordx4 v[182:185], v[166:167], off
	v_add_u32_e32 v166, 0xa0, v162
	v_ashrrev_i32_e32 v167, 31, v166
	v_lshlrev_b64 v[164:165], 6, v[166:167]
	v_lshl_add_u64 v[164:165], v[152:153], 0, v[164:165]
	global_load_dwordx4 v[186:189], v[164:165], off
	v_add_u32_e32 v164, 0xb0, v162
	v_ashrrev_i32_e32 v165, 31, v164
	v_lshlrev_b64 v[200:201], 6, v[164:165]
	v_lshl_add_u64 v[200:201], v[152:153], 0, v[200:201]
	global_load_dwordx4 v[200:203], v[200:201], off
	s_waitcnt vmcnt(3)
	v_add_f32_e32 v178, v178, v179
	v_add_f32_e32 v179, v180, v181
	s_waitcnt vmcnt(2)
	v_add_f32_e32 v180, v182, v183
	v_add_f32_e32 v181, v184, v185
	v_add_f32_e32 v178, v178, v179
	v_add_f32_e32 v179, v180, v181
	s_waitcnt vmcnt(1)
	v_add_f32_e32 v182, v186, v187
	v_add_f32_e32 v183, v188, v189
	v_add_f32_e32 v180, v182, v183
	v_mov_b32_e32 v182, v178
	v_mov_b32_e32 v183, v179
	s_waitcnt vmcnt(0)
	v_add_f32_e32 v184, v200, v201
	v_add_f32_e32 v185, v202, v203
	v_add_f32_e32 v181, v184, v185
	v_mov_b32_e32 v184, v180
	v_mov_b32_e32 v185, v181
	s_waitcnt lgkmcnt(3)
	s_nop 1
	v_permlane16_swap_b32_e32 v182, v178
	v_add_f32_e32 v206, v178, v182
	s_waitcnt lgkmcnt(2)
	s_nop 1
	v_permlane16_swap_b32_e32 v183, v179
	v_add_f32_e32 v204, v179, v183
	ds_bpermute_b32 v207, v195, v206
	s_waitcnt lgkmcnt(2)
	s_nop 1
	v_permlane16_swap_b32_e32 v184, v180
	v_add_f32_e32 v202, v180, v184
	s_waitcnt lgkmcnt(1)
	s_nop 1
	v_permlane16_swap_b32_e32 v185, v181
	v_add_f32_e32 v200, v181, v185
	ds_bpermute_b32 v205, v195, v204
	ds_bpermute_b32 v203, v195, v202
	ds_bpermute_b32 v201, v195, v200
	v_pk_mul_f32 v[184:185], v[142:143], v[190:191] op_sel_hi:[1,0]
	v_pk_mul_f32 v[186:187], v[140:141], v[190:191] op_sel_hi:[1,0]
	v_pk_mul_f32 v[178:179], v[138:139], v[190:191] op_sel_hi:[1,0]
	v_pk_mul_f32 v[180:181], v[136:137], v[190:191] op_sel_hi:[1,0]
	v_pk_mul_f32 v[140:141], v[134:135], v[190:191] op_sel_hi:[1,0]
	v_pk_mul_f32 v[142:143], v[132:133], v[190:191] op_sel_hi:[1,0]
	v_pk_mul_f32 v[136:137], v[130:131], v[190:191] op_sel_hi:[1,0]
	v_pk_mul_f32 v[138:139], v[128:129], v[190:191] op_sel_hi:[1,0]
	s_and_b64 vcc, exec, s[6:7]
	v_mov_b32_e32 v182, 1.0
	s_cbranch_vccnz .LBB0_720
	v_pk_mul_f32 v[128:129], v[184:185], v[184:185]
	v_pk_mul_f32 v[130:131], v[186:187], v[186:187]
	s_nop 0
	v_pk_mov_b32 v[132:133], v[130:131], v[128:129] op_sel:[1,0]
	v_mov_b32_e32 v131, v129
	v_pk_add_f32 v[128:129], v[132:133], v[130:131]
	v_pk_mul_f32 v[130:131], v[178:179], v[178:179]
	v_pk_add_f32 v[128:129], v[128:129], v[128:129] op_sel_hi:[0,1]
	v_pk_mul_f32 v[132:133], v[180:181], v[180:181]
	v_mul_f32_e32 v128, v142, v142
	v_pk_mov_b32 v[134:135], v[132:133], v[130:131] op_sel:[1,0]
	v_mov_b32_e32 v133, v131
	v_pk_add_f32 v[130:131], v[134:135], v[132:133]
	v_pk_fma_f32 v[132:133], v[142:143], v[142:143], v[128:129] op_sel_hi:[1,1,0]
	v_mul_f32_e32 v128, v140, v140
	v_pk_add_f32 v[130:131], v[130:131], v[130:131] op_sel_hi:[0,1]
	v_pk_fma_f32 v[134:135], v[140:141], v[140:141], v[128:129] op_sel_hi:[1,1,0]
	v_mul_f32_e32 v132, v138, v138
	v_mul_f32_e32 v134, v139, v139
	v_mul_f32_e32 v128, v136, v136
	v_mul_f32_e32 v130, v137, v137
	v_pk_add_f32 v[132:133], v[132:133], v[134:135]
	v_pk_add_f32 v[128:129], v[128:129], v[130:131]
	s_nop 0
	v_pk_add_f32 v[128:129], v[132:133], v[128:129]
	s_nop 0
	v_add_f32_e32 v128, v128, v129
	v_mov_b32_e32 v129, v128
	s_waitcnt lgkmcnt(0)
	s_nop 1
	v_permlane16_swap_b32_e32 v129, v128
	v_add_f32_e32 v128, v128, v129
	v_mov_b32_e32 v129, v128
	s_waitcnt lgkmcnt(0)
	s_nop 1
	v_permlane32_swap_b32_e32 v129, v128
	v_add_f32_e32 v128, v128, v129
	v_fmamk_f32 v128, v128, 0x3c800000, v199
	v_rsq_f32_e32 v128, v128
	s_nop 0
	v_mul_f32_e32 v129, 0x3e38aa3b, v128
	v_cndmask_b32_e64 v182, v128, v129, s[4:5]

.LBB0_728:
	s_or_b64 exec, exec, s[52:53]
	s_nop 0
	v_add_f32_e32 v128, v212, v213
	v_fmamk_f32 v128, v128, 0x3a800000, v199
	v_rsq_f32_e32 v128, v128
	s_and_b64 vcc, exec, s[6:7]
	v_pk_mul_f32 v[136:137], v[126:127], v[128:129] op_sel_hi:[1,0]
	v_pk_mul_f32 v[138:139], v[124:125], v[128:129] op_sel_hi:[1,0]
	v_pk_mul_f32 v[124:125], v[122:123], v[128:129] op_sel_hi:[1,0]
	v_pk_mul_f32 v[126:127], v[120:121], v[128:129] op_sel_hi:[1,0]
	v_pk_mul_f32 v[120:121], v[118:119], v[128:129] op_sel_hi:[1,0]
	v_pk_mul_f32 v[122:123], v[116:117], v[128:129] op_sel_hi:[1,0]
	v_pk_mul_f32 v[116:117], v[114:115], v[128:129] op_sel_hi:[1,0]
	v_pk_mul_f32 v[118:119], v[112:113], v[128:129] op_sel_hi:[1,0]
	v_mov_b32_e32 v128, 1.0
	s_cbranch_vccnz .LBB0_730
	v_pk_mul_f32 v[112:113], v[136:137], v[136:137]
	v_pk_mul_f32 v[114:115], v[138:139], v[138:139]
	s_nop 0
	v_pk_mov_b32 v[128:129], v[114:115], v[112:113] op_sel:[1,0]
	v_mov_b32_e32 v115, v113
	v_pk_add_f32 v[112:113], v[128:129], v[114:115]
	v_pk_mul_f32 v[114:115], v[124:125], v[124:125]
	v_pk_add_f32 v[112:113], v[112:113], v[112:113] op_sel_hi:[0,1]
	v_pk_mul_f32 v[128:129], v[126:127], v[126:127]
	v_mul_f32_e32 v112, v122, v122
	v_pk_mov_b32 v[130:131], v[128:129], v[114:115] op_sel:[1,0]
	v_mov_b32_e32 v129, v115
	v_pk_add_f32 v[114:115], v[130:131], v[128:129]
	v_pk_fma_f32 v[128:129], v[122:123], v[122:123], v[112:113] op_sel_hi:[1,1,0]
	v_mul_f32_e32 v112, v120, v120
	v_pk_add_f32 v[114:115], v[114:115], v[114:115] op_sel_hi:[0,1]
	v_pk_fma_f32 v[130:131], v[120:121], v[120:121], v[112:113] op_sel_hi:[1,1,0]
	v_mul_f32_e32 v128, v118, v118
	v_mul_f32_e32 v130, v119, v119
	v_mul_f32_e32 v112, v116, v116
	v_mul_f32_e32 v114, v117, v117
	v_pk_add_f32 v[128:129], v[128:129], v[130:131]
	v_pk_add_f32 v[112:113], v[112:113], v[114:115]
	s_nop 0
	v_pk_add_f32 v[112:113], v[128:129], v[112:113]
	s_nop 0
	v_add_f32_e32 v112, v112, v113
	v_mov_b32_e32 v113, v112
	s_waitcnt lgkmcnt(0)
	s_nop 1
	v_permlane16_swap_b32_e32 v113, v112
	v_add_f32_e32 v112, v112, v113
	v_mov_b32_e32 v113, v112
	s_waitcnt lgkmcnt(0)
	s_nop 1
	v_permlane32_swap_b32_e32 v113, v112
	v_add_f32_e32 v112, v112, v113
	v_fmamk_f32 v112, v112, 0x3c800000, v199
	v_rsq_f32_e32 v112, v112
	s_nop 0
	v_mul_f32_e32 v113, 0x3e38aa3b, v112
	v_cndmask_b32_e64 v128, v112, v113, s[4:5]

.LBB0_738:
	s_or_b64 exec, exec, s[52:53]
	s_nop 0
	v_add_f32_e32 v112, v210, v211
	v_fmamk_f32 v112, v112, 0x3a800000, v199
	v_rsq_f32_e32 v112, v112
	s_and_b64 vcc, exec, s[6:7]
	v_pk_mul_f32 v[116:117], v[110:111], v[112:113] op_sel_hi:[1,0]
	v_pk_mul_f32 v[118:119], v[108:109], v[112:113] op_sel_hi:[1,0]
	v_pk_mul_f32 v[108:109], v[106:107], v[112:113] op_sel_hi:[1,0]
	v_pk_mul_f32 v[110:111], v[104:105], v[112:113] op_sel_hi:[1,0]
	v_pk_mul_f32 v[104:105], v[102:103], v[112:113] op_sel_hi:[1,0]
	v_pk_mul_f32 v[106:107], v[100:101], v[112:113] op_sel_hi:[1,0]
	v_pk_mul_f32 v[100:101], v[98:99], v[112:113] op_sel_hi:[1,0]
	v_pk_mul_f32 v[102:103], v[96:97], v[112:113] op_sel_hi:[1,0]
	v_mov_b32_e32 v112, 1.0
	s_cbranch_vccnz .LBB0_740
	v_pk_mul_f32 v[96:97], v[116:117], v[116:117]
	v_pk_mul_f32 v[98:99], v[118:119], v[118:119]
	s_nop 0
	v_pk_mov_b32 v[112:113], v[98:99], v[96:97] op_sel:[1,0]
	v_mov_b32_e32 v99, v97
	v_pk_add_f32 v[96:97], v[112:113], v[98:99]
	v_pk_mul_f32 v[98:99], v[108:109], v[108:109]
	v_pk_add_f32 v[96:97], v[96:97], v[96:97] op_sel_hi:[0,1]
	v_pk_mul_f32 v[112:113], v[110:111], v[110:111]
	v_mul_f32_e32 v96, v106, v106
	v_pk_mov_b32 v[114:115], v[112:113], v[98:99] op_sel:[1,0]
	v_mov_b32_e32 v113, v99
	v_pk_add_f32 v[98:99], v[114:115], v[112:113]
	v_pk_fma_f32 v[112:113], v[106:107], v[106:107], v[96:97] op_sel_hi:[1,1,0]
	v_mul_f32_e32 v96, v104, v104
	v_pk_add_f32 v[98:99], v[98:99], v[98:99] op_sel_hi:[0,1]
	v_pk_fma_f32 v[114:115], v[104:105], v[104:105], v[96:97] op_sel_hi:[1,1,0]
	v_mul_f32_e32 v112, v102, v102
	v_mul_f32_e32 v114, v103, v103
	v_mul_f32_e32 v96, v100, v100
	v_mul_f32_e32 v98, v101, v101
	v_pk_add_f32 v[112:113], v[112:113], v[114:115]
	v_pk_add_f32 v[96:97], v[96:97], v[98:99]
	s_nop 0
	v_pk_add_f32 v[96:97], v[112:113], v[96:97]
	s_nop 0
	v_add_f32_e32 v96, v96, v97
	v_mov_b32_e32 v97, v96
	s_waitcnt lgkmcnt(0)
	s_nop 1
	v_permlane16_swap_b32_e32 v97, v96
	v_add_f32_e32 v96, v96, v97
	v_mov_b32_e32 v97, v96
	s_waitcnt lgkmcnt(0)
	s_nop 1
	v_permlane32_swap_b32_e32 v97, v96
	v_add_f32_e32 v96, v96, v97
	v_fmamk_f32 v96, v96, 0x3c800000, v199
	v_rsq_f32_e32 v96, v96
	s_nop 0
	v_mul_f32_e32 v97, 0x3e38aa3b, v96
	v_cndmask_b32_e64 v112, v96, v97, s[4:5]

.LBB0_748:
	s_or_b64 exec, exec, s[52:53]
	s_nop 0
	v_add_f32_e32 v96, v208, v209
	v_fmamk_f32 v96, v96, 0x3a800000, v199
	v_rsq_f32_e32 v96, v96
	s_and_b64 vcc, exec, s[6:7]
	v_pk_mul_f32 v[100:101], v[94:95], v[96:97] op_sel_hi:[1,0]
	v_pk_mul_f32 v[102:103], v[92:93], v[96:97] op_sel_hi:[1,0]
	v_pk_mul_f32 v[92:93], v[90:91], v[96:97] op_sel_hi:[1,0]
	v_pk_mul_f32 v[94:95], v[88:89], v[96:97] op_sel_hi:[1,0]
	v_pk_mul_f32 v[88:89], v[86:87], v[96:97] op_sel_hi:[1,0]
	v_pk_mul_f32 v[90:91], v[84:85], v[96:97] op_sel_hi:[1,0]
	v_pk_mul_f32 v[84:85], v[82:83], v[96:97] op_sel_hi:[1,0]
	v_pk_mul_f32 v[86:87], v[80:81], v[96:97] op_sel_hi:[1,0]
	v_mov_b32_e32 v96, 1.0
	s_cbranch_vccnz .LBB0_750
	v_pk_mul_f32 v[80:81], v[100:101], v[100:101]
	v_pk_mul_f32 v[82:83], v[102:103], v[102:103]
	s_nop 0
	v_pk_mov_b32 v[96:97], v[82:83], v[80:81] op_sel:[1,0]
	v_mov_b32_e32 v83, v81
	v_pk_add_f32 v[80:81], v[96:97], v[82:83]
	v_pk_mul_f32 v[82:83], v[92:93], v[92:93]
	v_pk_add_f32 v[80:81], v[80:81], v[80:81] op_sel_hi:[0,1]
	v_pk_mul_f32 v[96:97], v[94:95], v[94:95]
	v_mul_f32_e32 v80, v90, v90
	v_pk_mov_b32 v[98:99], v[96:97], v[82:83] op_sel:[1,0]
	v_mov_b32_e32 v97, v83
	v_pk_add_f32 v[82:83], v[98:99], v[96:97]
	v_pk_fma_f32 v[96:97], v[90:91], v[90:91], v[80:81] op_sel_hi:[1,1,0]
	v_mul_f32_e32 v80, v88, v88
	v_pk_add_f32 v[82:83], v[82:83], v[82:83] op_sel_hi:[0,1]
	v_pk_fma_f32 v[98:99], v[88:89], v[88:89], v[80:81] op_sel_hi:[1,1,0]
	v_mul_f32_e32 v96, v86, v86
	v_mul_f32_e32 v98, v87, v87
	v_mul_f32_e32 v80, v84, v84
	v_mul_f32_e32 v82, v85, v85
	v_pk_add_f32 v[96:97], v[96:97], v[98:99]
	v_pk_add_f32 v[80:81], v[80:81], v[82:83]
	s_nop 0
	v_pk_add_f32 v[80:81], v[96:97], v[80:81]
	s_nop 0
	v_add_f32_e32 v80, v80, v81
	v_mov_b32_e32 v81, v80
	s_waitcnt lgkmcnt(0)
	s_nop 1
	v_permlane16_swap_b32_e32 v81, v80
	v_add_f32_e32 v80, v80, v81
	v_mov_b32_e32 v81, v80
	s_waitcnt lgkmcnt(0)
	s_nop 1
	v_permlane32_swap_b32_e32 v81, v80
	v_add_f32_e32 v80, v80, v81
	v_fmamk_f32 v80, v80, 0x3c800000, v199
	v_rsq_f32_e32 v80, v80
	s_nop 0
	v_mul_f32_e32 v81, 0x3e38aa3b, v80
	v_cndmask_b32_e64 v96, v80, v81, s[4:5]

.LBB0_758:
	s_or_b64 exec, exec, s[52:53]
	s_waitcnt lgkmcnt(0)
	v_add_f32_e32 v80, v206, v207
	v_fmamk_f32 v80, v80, 0x3a800000, v199
	v_rsq_f32_e32 v80, v80
	s_and_b64 vcc, exec, s[6:7]
	v_pk_mul_f32 v[84:85], v[78:79], v[80:81] op_sel_hi:[1,0]
	v_pk_mul_f32 v[86:87], v[76:77], v[80:81] op_sel_hi:[1,0]
	v_pk_mul_f32 v[76:77], v[74:75], v[80:81] op_sel_hi:[1,0]
	v_pk_mul_f32 v[78:79], v[72:73], v[80:81] op_sel_hi:[1,0]
	v_pk_mul_f32 v[72:73], v[70:71], v[80:81] op_sel_hi:[1,0]
	v_pk_mul_f32 v[74:75], v[68:69], v[80:81] op_sel_hi:[1,0]
	v_pk_mul_f32 v[68:69], v[66:67], v[80:81] op_sel_hi:[1,0]
	v_pk_mul_f32 v[70:71], v[64:65], v[80:81] op_sel_hi:[1,0]
	v_mov_b32_e32 v80, 1.0
	s_cbranch_vccnz .LBB0_760
	v_pk_mul_f32 v[64:65], v[84:85], v[84:85]
	v_pk_mul_f32 v[66:67], v[86:87], v[86:87]
	s_nop 0
	v_pk_mov_b32 v[80:81], v[66:67], v[64:65] op_sel:[1,0]
	v_mov_b32_e32 v67, v65
	v_pk_add_f32 v[64:65], v[80:81], v[66:67]
	v_pk_mul_f32 v[66:67], v[76:77], v[76:77]
	v_pk_add_f32 v[64:65], v[64:65], v[64:65] op_sel_hi:[0,1]
	v_pk_mul_f32 v[80:81], v[78:79], v[78:79]
	v_mul_f32_e32 v64, v74, v74
	v_pk_mov_b32 v[82:83], v[80:81], v[66:67] op_sel:[1,0]
	v_mov_b32_e32 v81, v67
	v_pk_add_f32 v[66:67], v[82:83], v[80:81]
	v_pk_fma_f32 v[80:81], v[74:75], v[74:75], v[64:65] op_sel_hi:[1,1,0]
	v_mul_f32_e32 v64, v72, v72
	v_pk_add_f32 v[66:67], v[66:67], v[66:67] op_sel_hi:[0,1]
	v_pk_fma_f32 v[82:83], v[72:73], v[72:73], v[64:65] op_sel_hi:[1,1,0]
	v_mul_f32_e32 v80, v70, v70
	v_mul_f32_e32 v82, v71, v71
	v_mul_f32_e32 v64, v68, v68
	v_mul_f32_e32 v66, v69, v69
	v_pk_add_f32 v[80:81], v[80:81], v[82:83]
	v_pk_add_f32 v[64:65], v[64:65], v[66:67]
	s_nop 0
	v_pk_add_f32 v[64:65], v[80:81], v[64:65]
	s_nop 0
	v_add_f32_e32 v64, v64, v65
	v_mov_b32_e32 v65, v64
	s_waitcnt lgkmcnt(0)
	s_nop 1
	v_permlane16_swap_b32_e32 v65, v64
	v_add_f32_e32 v64, v64, v65
	v_mov_b32_e32 v65, v64
	s_waitcnt lgkmcnt(0)
	s_nop 1
	v_permlane32_swap_b32_e32 v65, v64
	v_add_f32_e32 v64, v64, v65
	v_fmamk_f32 v64, v64, 0x3c800000, v199
	v_rsq_f32_e32 v64, v64
	s_nop 0
	v_mul_f32_e32 v65, 0x3e38aa3b, v64
	v_cndmask_b32_e64 v80, v64, v65, s[4:5]

.LBB0_768:
	s_or_b64 exec, exec, s[52:53]
	s_nop 0
	v_add_f32_e32 v64, v204, v205
	v_fmamk_f32 v64, v64, 0x3a800000, v199
	v_rsq_f32_e32 v64, v64
	s_and_b64 vcc, exec, s[6:7]
	v_pk_mul_f32 v[68:69], v[46:47], v[64:65] op_sel_hi:[1,0]
	v_pk_mul_f32 v[70:71], v[44:45], v[64:65] op_sel_hi:[1,0]
	v_pk_mul_f32 v[44:45], v[42:43], v[64:65] op_sel_hi:[1,0]
	v_pk_mul_f32 v[46:47], v[40:41], v[64:65] op_sel_hi:[1,0]
	v_pk_mul_f32 v[40:41], v[38:39], v[64:65] op_sel_hi:[1,0]
	v_pk_mul_f32 v[42:43], v[36:37], v[64:65] op_sel_hi:[1,0]
	v_pk_mul_f32 v[36:37], v[34:35], v[64:65] op_sel_hi:[1,0]
	v_pk_mul_f32 v[38:39], v[32:33], v[64:65] op_sel_hi:[1,0]
	v_mov_b32_e32 v64, 1.0
	s_cbranch_vccnz .LBB0_770
	v_pk_mul_f32 v[32:33], v[68:69], v[68:69]
	v_pk_mul_f32 v[34:35], v[70:71], v[70:71]
	s_nop 0
	v_pk_mov_b32 v[64:65], v[34:35], v[32:33] op_sel:[1,0]
	v_mov_b32_e32 v35, v33
	v_pk_add_f32 v[32:33], v[64:65], v[34:35]
	v_pk_mul_f32 v[34:35], v[44:45], v[44:45]
	v_pk_add_f32 v[32:33], v[32:33], v[32:33] op_sel_hi:[0,1]
	v_pk_mul_f32 v[64:65], v[46:47], v[46:47]
	v_mul_f32_e32 v32, v42, v42
	v_pk_mov_b32 v[66:67], v[64:65], v[34:35] op_sel:[1,0]
	v_mov_b32_e32 v65, v35
	v_pk_add_f32 v[34:35], v[66:67], v[64:65]
	v_pk_fma_f32 v[64:65], v[42:43], v[42:43], v[32:33] op_sel_hi:[1,1,0]
	v_mul_f32_e32 v32, v40, v40
	v_pk_add_f32 v[34:35], v[34:35], v[34:35] op_sel_hi:[0,1]
	v_pk_fma_f32 v[66:67], v[40:41], v[40:41], v[32:33] op_sel_hi:[1,1,0]
	v_mul_f32_e32 v64, v38, v38
	v_mul_f32_e32 v66, v39, v39
	v_mul_f32_e32 v32, v36, v36
	v_mul_f32_e32 v34, v37, v37
	v_pk_add_f32 v[64:65], v[64:65], v[66:67]
	v_pk_add_f32 v[32:33], v[32:33], v[34:35]
	s_nop 0
	v_pk_add_f32 v[32:33], v[64:65], v[32:33]
	s_nop 0
	v_add_f32_e32 v32, v32, v33
	v_mov_b32_e32 v33, v32
	s_waitcnt lgkmcnt(0)
	s_nop 1
	v_permlane16_swap_b32_e32 v33, v32
	v_add_f32_e32 v32, v32, v33
	v_mov_b32_e32 v33, v32
	s_waitcnt lgkmcnt(0)
	s_nop 1
	v_permlane32_swap_b32_e32 v33, v32
	v_add_f32_e32 v32, v32, v33
	v_fmamk_f32 v32, v32, 0x3c800000, v199
	v_rsq_f32_e32 v32, v32
	s_nop 0
	v_mul_f32_e32 v33, 0x3e38aa3b, v32
	v_cndmask_b32_e64 v64, v32, v33, s[4:5]

.LBB0_778:
	s_or_b64 exec, exec, s[52:53]
	s_nop 0
	v_add_f32_e32 v32, v202, v203
	v_fmamk_f32 v32, v32, 0x3a800000, v199
	v_rsq_f32_e32 v32, v32
	s_and_b64 vcc, exec, s[6:7]
	v_pk_mul_f32 v[36:37], v[30:31], v[32:33] op_sel_hi:[1,0]
	v_pk_mul_f32 v[38:39], v[28:29], v[32:33] op_sel_hi:[1,0]
	v_pk_mul_f32 v[28:29], v[26:27], v[32:33] op_sel_hi:[1,0]
	v_pk_mul_f32 v[30:31], v[24:25], v[32:33] op_sel_hi:[1,0]
	v_pk_mul_f32 v[24:25], v[22:23], v[32:33] op_sel_hi:[1,0]
	v_pk_mul_f32 v[26:27], v[20:21], v[32:33] op_sel_hi:[1,0]
	v_pk_mul_f32 v[20:21], v[18:19], v[32:33] op_sel_hi:[1,0]
	v_pk_mul_f32 v[22:23], v[16:17], v[32:33] op_sel_hi:[1,0]
	v_mov_b32_e32 v32, 1.0
	s_cbranch_vccnz .LBB0_780
	v_pk_mul_f32 v[16:17], v[36:37], v[36:37]
	v_pk_mul_f32 v[18:19], v[38:39], v[38:39]
	s_nop 0
	v_pk_mov_b32 v[32:33], v[18:19], v[16:17] op_sel:[1,0]
	v_mov_b32_e32 v19, v17
	v_pk_add_f32 v[16:17], v[32:33], v[18:19]
	v_pk_mul_f32 v[18:19], v[28:29], v[28:29]
	v_pk_add_f32 v[16:17], v[16:17], v[16:17] op_sel_hi:[0,1]
	v_pk_mul_f32 v[32:33], v[30:31], v[30:31]
	v_mul_f32_e32 v16, v26, v26
	v_pk_mov_b32 v[34:35], v[32:33], v[18:19] op_sel:[1,0]
	v_mov_b32_e32 v33, v19
	v_pk_add_f32 v[18:19], v[34:35], v[32:33]
	v_pk_fma_f32 v[32:33], v[26:27], v[26:27], v[16:17] op_sel_hi:[1,1,0]
	v_mul_f32_e32 v16, v24, v24
	v_pk_add_f32 v[18:19], v[18:19], v[18:19] op_sel_hi:[0,1]
	v_pk_fma_f32 v[34:35], v[24:25], v[24:25], v[16:17] op_sel_hi:[1,1,0]
	v_mul_f32_e32 v32, v22, v22
	v_mul_f32_e32 v34, v23, v23
	v_mul_f32_e32 v16, v20, v20
	v_mul_f32_e32 v18, v21, v21
	v_pk_add_f32 v[32:33], v[32:33], v[34:35]
	v_pk_add_f32 v[16:17], v[16:17], v[18:19]
	s_nop 0
	v_pk_add_f32 v[16:17], v[32:33], v[16:17]
	s_nop 0
	v_add_f32_e32 v16, v16, v17
	v_mov_b32_e32 v17, v16
	s_waitcnt lgkmcnt(0)
	s_nop 1
	v_permlane16_swap_b32_e32 v17, v16
	v_add_f32_e32 v16, v16, v17
	v_mov_b32_e32 v17, v16
	s_waitcnt lgkmcnt(0)
	s_nop 1
	v_permlane32_swap_b32_e32 v17, v16
	v_add_f32_e32 v16, v16, v17
	v_fmamk_f32 v16, v16, 0x3c800000, v199
	v_rsq_f32_e32 v16, v16
	s_nop 0
	v_mul_f32_e32 v17, 0x3e38aa3b, v16
	v_cndmask_b32_e64 v32, v16, v17, s[4:5]

.LBB0_788:
	s_or_b64 exec, exec, s[52:53]
	s_nop 0
	v_add_f32_e32 v16, v200, v201
	v_fmamk_f32 v16, v16, 0x3a800000, v199
	v_rsq_f32_e32 v16, v16
	s_and_b64 vcc, exec, s[6:7]
	v_pk_mul_f32 v[20:21], v[14:15], v[16:17] op_sel_hi:[1,0]
	v_pk_mul_f32 v[22:23], v[12:13], v[16:17] op_sel_hi:[1,0]
	v_pk_mul_f32 v[12:13], v[10:11], v[16:17] op_sel_hi:[1,0]
	v_pk_mul_f32 v[14:15], v[8:9], v[16:17] op_sel_hi:[1,0]
	v_pk_mul_f32 v[8:9], v[6:7], v[16:17] op_sel_hi:[1,0]
	v_pk_mul_f32 v[10:11], v[4:5], v[16:17] op_sel_hi:[1,0]
	v_pk_mul_f32 v[4:5], v[2:3], v[16:17] op_sel_hi:[1,0]
	v_pk_mul_f32 v[6:7], v[0:1], v[16:17] op_sel_hi:[1,0]
	v_mov_b32_e32 v16, 1.0
	s_cbranch_vccnz .LBB0_790
	v_pk_mul_f32 v[0:1], v[20:21], v[20:21]
	v_pk_mul_f32 v[2:3], v[22:23], v[22:23]
	s_nop 0
	v_pk_mov_b32 v[16:17], v[2:3], v[0:1] op_sel:[1,0]
	v_mov_b32_e32 v3, v1
	v_pk_add_f32 v[0:1], v[16:17], v[2:3]
	v_pk_mul_f32 v[2:3], v[12:13], v[12:13]
	v_pk_add_f32 v[0:1], v[0:1], v[0:1] op_sel_hi:[0,1]
	v_pk_mul_f32 v[16:17], v[14:15], v[14:15]
	v_mul_f32_e32 v0, v10, v10
	v_pk_mov_b32 v[18:19], v[16:17], v[2:3] op_sel:[1,0]
	v_mov_b32_e32 v17, v3
	v_pk_add_f32 v[2:3], v[18:19], v[16:17]
	v_pk_fma_f32 v[16:17], v[10:11], v[10:11], v[0:1] op_sel_hi:[1,1,0]
	v_mul_f32_e32 v0, v8, v8
	v_pk_add_f32 v[2:3], v[2:3], v[2:3] op_sel_hi:[0,1]
	v_pk_fma_f32 v[18:19], v[8:9], v[8:9], v[0:1] op_sel_hi:[1,1,0]
	v_mul_f32_e32 v16, v6, v6
	v_mul_f32_e32 v18, v7, v7
	v_mul_f32_e32 v0, v4, v4
	v_mul_f32_e32 v2, v5, v5
	v_pk_add_f32 v[16:17], v[16:17], v[18:19]
	v_pk_add_f32 v[0:1], v[0:1], v[2:3]
	s_nop 0
	v_pk_add_f32 v[0:1], v[16:17], v[0:1]
	s_nop 0
	v_add_f32_e32 v0, v0, v1
	v_mov_b32_e32 v1, v0
	s_waitcnt lgkmcnt(0)
	s_nop 1
	v_permlane16_swap_b32_e32 v1, v0
	v_add_f32_e32 v0, v0, v1
	v_mov_b32_e32 v1, v0
	s_waitcnt lgkmcnt(0)
	s_nop 1
	v_permlane32_swap_b32_e32 v1, v0
	v_add_f32_e32 v0, v0, v1
	v_fmamk_f32 v0, v0, 0x3c800000, v199
	v_rsq_f32_e32 v0, v0
	s_nop 0
	v_mul_f32_e32 v1, 0x3e38aa3b, v0
	v_cndmask_b32_e64 v16, v0, v1, s[4:5]

.LBB0_1163:
	v_lshl_add_u32 v168, s28, 8, v176
	v_lshl_or_b32 v160, s10, 8, v178
	v_ashrrev_i32_e32 v169, 31, v168
	v_lshlrev_b64 v[128:129], 11, v[168:169]
	v_ashrrev_i32_e32 v161, 31, v160
	v_lshl_add_u64 v[162:163], s[46:47], 0, v[128:129]
	v_lshlrev_b64 v[128:129], 1, v[160:161]
	v_lshl_add_u64 v[190:191], v[162:163], 0, v[128:129]
	global_load_dwordx4 v[182:185], v[190:191], off
	global_load_dwordx4 v[186:189], v[190:191], off offset:256
	v_or_b32_e32 v170, 16, v168
	v_or_b32_e32 v164, 32, v168
	v_ashrrev_i32_e32 v171, 31, v170
	v_ashrrev_i32_e32 v165, 31, v164
	v_lshlrev_b64 v[130:131], 11, v[170:171]
	v_lshlrev_b64 v[132:133], 11, v[164:165]
	v_lshl_add_u64 v[130:131], s[46:47], 0, v[130:131]
	v_lshl_add_u64 v[132:133], s[46:47], 0, v[132:133]
	v_lshl_add_u64 v[172:173], v[130:131], 0, v[128:129]
	v_lshl_add_u64 v[166:167], v[132:133], 0, v[128:129]
	global_load_dwordx4 v[140:143], v[172:173], off
	global_load_dwordx4 v[136:139], v[172:173], off offset:256
	global_load_dwordx4 v[132:135], v[166:167], off
	global_load_dwordx4 v[128:131], v[166:167], off offset:256
	s_lshl_b32 s28, s10, 2
	s_ashr_i32 s29, s28, 31
	s_waitcnt vmcnt(0)
	v_lshlrev_b32_e32 v192, 16, v182
	v_and_b32_e32 v193, 0xffff0000, v182
	v_lshlrev_b32_e32 v182, 16, v183
	v_and_b32_e32 v183, 0xffff0000, v183
	v_lshlrev_b32_e32 v194, 16, v184
	v_and_b32_e32 v195, 0xffff0000, v184
	v_lshlrev_b32_e32 v184, 16, v185
	v_and_b32_e32 v185, 0xffff0000, v185
	v_lshlrev_b32_e32 v196, 16, v186
	v_and_b32_e32 v197, 0xffff0000, v186
	v_lshlrev_b32_e32 v186, 16, v187
	v_and_b32_e32 v187, 0xffff0000, v187
	v_lshlrev_b32_e32 v198, 16, v188
	v_and_b32_e32 v199, 0xffff0000, v188
	v_lshlrev_b32_e32 v188, 16, v189
	v_and_b32_e32 v189, 0xffff0000, v189
	v_pk_add_f32 v[126:127], v[126:127], v[182:183]
	v_pk_add_f32 v[124:125], v[124:125], v[192:193]
	v_pk_add_f32 v[122:123], v[122:123], v[184:185]
	v_pk_add_f32 v[120:121], v[120:121], v[194:195]
	v_pk_add_f32 v[118:119], v[118:119], v[186:187]
	v_pk_add_f32 v[116:117], v[116:117], v[196:197]
	v_pk_add_f32 v[182:183], v[114:115], v[188:189]
	v_pk_add_f32 v[184:185], v[112:113], v[198:199]
	v_cvt_pk_bf16_f32 v112, v124, v125
	v_cvt_pk_bf16_f32 v113, v126, v127
	v_mul_f32_e32 v114, v125, v125
	v_mul_f32_e32 v115, v127, v127
	v_mul_f32_e32 v125, v121, v121
	v_mul_f32_e32 v127, v123, v123
	v_mul_f32_e32 v186, v117, v117
	v_mul_f32_e32 v187, v119, v119
	v_mul_f32_e32 v188, v185, v185
	v_mul_f32_e32 v189, v183, v183
	v_fmac_f32_e32 v114, v124, v124
	v_fmac_f32_e32 v115, v126, v126
	v_fmac_f32_e32 v125, v120, v120
	v_fmac_f32_e32 v127, v122, v122
	v_fmac_f32_e32 v186, v116, v116
	v_fmac_f32_e32 v187, v118, v118
	v_fmac_f32_e32 v188, v184, v184
	v_fmac_f32_e32 v189, v182, v182
	v_add_f32_e32 v114, v114, v115
	v_add_f32_e32 v115, v125, v127
	v_add_f32_e32 v124, v186, v187
	v_add_f32_e32 v125, v188, v189
	v_add_f32_e32 v114, v114, v115
	v_add_f32_e32 v115, v124, v125
	v_add_f32_e32 v124, v114, v115
	v_mov_b32_e32 v125, v124
	v_cvt_pk_bf16_f32 v114, v120, v121
	v_cvt_pk_bf16_f32 v115, v122, v123
	global_store_dwordx4 v[190:191], v[112:115], off
	s_waitcnt lgkmcnt(0)
	s_nop 0
	s_nop 1
	v_permlane16_swap_b32_e32 v125, v124
	v_add_f32_e32 v112, v124, v125
	ds_bpermute_b32 v113, v175, v112
	v_cvt_pk_bf16_f32 v114, v116, v117
	v_cvt_pk_bf16_f32 v115, v118, v119
	v_cvt_pk_bf16_f32 v116, v184, v185
	v_cvt_pk_bf16_f32 v117, v182, v183
	global_store_dwordx4 v[190:191], v[114:117], off offset:256
	s_and_saveexec_b64 s[30:31], s[2:3]
	s_cbranch_execz .LBB0_1165
	v_lshlrev_b64 v[114:115], 6, v[168:169]
	v_lshl_add_u64 v[114:115], s[8:9], 0, v[114:115]
	v_lshl_add_u64 v[114:115], s[28:29], 2, v[114:115]
	s_lshl_b32 s10, s63, 2
	v_lshl_add_u64 v[114:115], v[114:115], 0, s[10:11]
	s_waitcnt lgkmcnt(0)
	v_add_f32_e32 v112, v112, v113
	global_store_dword v[114:115], v112, off
.LBB0_1165:
	s_or_b64 exec, exec, s[30:31]
	v_or_b32_e32 v120, 48, v168
	v_ashrrev_i32_e32 v121, 31, v120
	s_waitcnt lgkmcnt(0)
	v_lshlrev_b64 v[112:113], 11, v[120:121]
	v_lshl_add_u64 v[112:113], s[46:47], 0, v[112:113]
	v_lshl_add_u64 v[122:123], v[160:161], 1, v[112:113]
	global_load_dwordx4 v[116:119], v[122:123], off
	global_load_dwordx4 v[112:115], v[122:123], off offset:256
	v_lshlrev_b32_e32 v124, 16, v140
	v_and_b32_e32 v125, 0xffff0000, v140
	v_lshlrev_b32_e32 v126, 16, v141
	v_and_b32_e32 v127, 0xffff0000, v141
	v_pk_add_f32 v[110:111], v[110:111], v[126:127]
	v_pk_add_f32 v[108:109], v[108:109], v[124:125]
	v_lshlrev_b32_e32 v124, 16, v142
	v_and_b32_e32 v125, 0xffff0000, v142
	v_lshlrev_b32_e32 v126, 16, v143
	v_and_b32_e32 v127, 0xffff0000, v143
	v_pk_add_f32 v[126:127], v[106:107], v[126:127]
	v_pk_add_f32 v[106:107], v[104:105], v[124:125]
	v_cvt_pk_bf16_f32 v104, v108, v109
	v_mul_f32_e32 v109, v109, v109
	v_fmac_f32_e32 v109, v108, v108
	v_mul_f32_e32 v108, v111, v111
	v_fmac_f32_e32 v108, v110, v110
	v_cvt_pk_bf16_f32 v105, v110, v111
	v_add_f32_e32 v108, v109, v108
	v_mul_f32_e32 v109, v107, v107
	v_mul_f32_e32 v110, v127, v127
	v_fmac_f32_e32 v109, v106, v106
	v_fmac_f32_e32 v110, v126, v126
	v_add_f32_e32 v109, v109, v110
	v_add_f32_e32 v124, v108, v109
	v_lshlrev_b32_e32 v108, 16, v136
	v_and_b32_e32 v109, 0xffff0000, v136
	v_lshlrev_b32_e32 v110, 16, v137
	v_and_b32_e32 v111, 0xffff0000, v137
	v_pk_add_f32 v[102:103], v[102:103], v[110:111]
	v_pk_add_f32 v[100:101], v[100:101], v[108:109]
	v_lshlrev_b32_e32 v108, 16, v138
	v_and_b32_e32 v109, 0xffff0000, v138
	v_lshlrev_b32_e32 v110, 16, v139
	v_and_b32_e32 v111, 0xffff0000, v139
	v_pk_add_f32 v[108:109], v[96:97], v[108:109]
	v_mul_f32_e32 v96, v101, v101
	v_mul_f32_e32 v97, v103, v103
	v_pk_add_f32 v[110:111], v[98:99], v[110:111]
	v_fmac_f32_e32 v96, v100, v100
	v_fmac_f32_e32 v97, v102, v102
	v_add_f32_e32 v96, v96, v97
	v_mul_f32_e32 v97, v109, v109
	v_mul_f32_e32 v98, v111, v111
	v_fmac_f32_e32 v97, v108, v108
	v_fmac_f32_e32 v98, v110, v110
	v_add_f32_e32 v97, v97, v98
	v_add_f32_e32 v96, v96, v97
	v_add_f32_e32 v96, v124, v96
	v_mov_b32_e32 v97, v96
	v_cvt_pk_bf16_f32 v106, v106, v107
	v_cvt_pk_bf16_f32 v107, v126, v127
	global_store_dwordx4 v[172:173], v[104:107], off
	v_cvt_pk_bf16_f32 v98, v100, v101
	s_waitcnt lgkmcnt(0)
	s_nop 1
	v_permlane16_swap_b32_e32 v97, v96
	v_add_f32_e32 v96, v96, v97
	ds_bpermute_b32 v97, v175, v96
	v_cvt_pk_bf16_f32 v99, v102, v103
	v_cvt_pk_bf16_f32 v100, v108, v109
	v_cvt_pk_bf16_f32 v101, v110, v111
	global_store_dwordx4 v[172:173], v[98:101], off offset:256
	s_and_saveexec_b64 s[30:31], s[2:3]
	s_cbranch_execz .LBB0_1167
	v_lshlrev_b64 v[98:99], 6, v[170:171]
	v_lshl_add_u64 v[98:99], s[8:9], 0, v[98:99]
	v_lshl_add_u64 v[98:99], s[28:29], 2, v[98:99]
	s_lshl_b32 s10, s63, 2
	v_lshl_add_u64 v[98:99], v[98:99], 0, s[10:11]
	s_waitcnt lgkmcnt(0)
	v_add_f32_e32 v96, v96, v97
	global_store_dword v[98:99], v96, off
.LBB0_1167:
	s_or_b64 exec, exec, s[30:31]
	v_add_u32_e32 v104, 0x80, v168
	v_ashrrev_i32_e32 v105, 31, v104
	s_waitcnt lgkmcnt(0)
	v_lshlrev_b64 v[96:97], 11, v[104:105]
	v_lshl_add_u64 v[96:97], s[46:47], 0, v[96:97]
	v_lshl_add_u64 v[106:107], v[160:161], 1, v[96:97]
	global_load_dwordx4 v[100:103], v[106:107], off
	global_load_dwordx4 v[96:99], v[106:107], off offset:256
	v_lshlrev_b32_e32 v108, 16, v132
	v_and_b32_e32 v109, 0xffff0000, v132
	v_lshlrev_b32_e32 v110, 16, v133
	v_and_b32_e32 v111, 0xffff0000, v133
	v_pk_add_f32 v[94:95], v[94:95], v[110:111]
	v_pk_add_f32 v[92:93], v[92:93], v[108:109]
	v_lshlrev_b32_e32 v108, 16, v134
	v_and_b32_e32 v109, 0xffff0000, v134
	v_lshlrev_b32_e32 v110, 16, v135
	v_and_b32_e32 v111, 0xffff0000, v135
	v_pk_add_f32 v[110:111], v[90:91], v[110:111]
	v_pk_add_f32 v[90:91], v[88:89], v[108:109]
	v_cvt_pk_bf16_f32 v88, v92, v93
	v_mul_f32_e32 v93, v93, v93
	v_fmac_f32_e32 v93, v92, v92
	v_mul_f32_e32 v92, v95, v95
	v_fmac_f32_e32 v92, v94, v94
	v_cvt_pk_bf16_f32 v89, v94, v95
	v_add_f32_e32 v92, v93, v92
	v_mul_f32_e32 v93, v91, v91
	v_mul_f32_e32 v94, v111, v111
	v_fmac_f32_e32 v93, v90, v90
	v_fmac_f32_e32 v94, v110, v110
	v_add_f32_e32 v93, v93, v94
	v_add_f32_e32 v108, v92, v93
	v_lshlrev_b32_e32 v92, 16, v128
	v_and_b32_e32 v93, 0xffff0000, v128
	v_lshlrev_b32_e32 v94, 16, v129
	v_and_b32_e32 v95, 0xffff0000, v129
	v_pk_add_f32 v[86:87], v[86:87], v[94:95]
	v_pk_add_f32 v[84:85], v[84:85], v[92:93]
	v_lshlrev_b32_e32 v92, 16, v130
	v_and_b32_e32 v93, 0xffff0000, v130
	v_lshlrev_b32_e32 v94, 16, v131
	v_and_b32_e32 v95, 0xffff0000, v131
	v_pk_add_f32 v[92:93], v[80:81], v[92:93]
	v_mul_f32_e32 v80, v85, v85
	v_mul_f32_e32 v81, v87, v87
	v_pk_add_f32 v[94:95], v[82:83], v[94:95]
	v_fmac_f32_e32 v80, v84, v84
	v_fmac_f32_e32 v81, v86, v86
	v_add_f32_e32 v80, v80, v81
	v_mul_f32_e32 v81, v93, v93
	v_mul_f32_e32 v82, v95, v95
	v_fmac_f32_e32 v81, v92, v92
	v_fmac_f32_e32 v82, v94, v94
	v_add_f32_e32 v81, v81, v82
	v_add_f32_e32 v80, v80, v81
	v_add_f32_e32 v80, v108, v80
	v_mov_b32_e32 v81, v80
	v_cvt_pk_bf16_f32 v90, v90, v91
	v_cvt_pk_bf16_f32 v91, v110, v111
	global_store_dwordx4 v[166:167], v[88:91], off
	v_cvt_pk_bf16_f32 v82, v84, v85
	s_waitcnt lgkmcnt(0)
	s_nop 1
	v_permlane16_swap_b32_e32 v81, v80
	v_add_f32_e32 v80, v80, v81
	ds_bpermute_b32 v81, v175, v80
	v_cvt_pk_bf16_f32 v83, v86, v87
	v_cvt_pk_bf16_f32 v84, v92, v93
	v_cvt_pk_bf16_f32 v85, v94, v95
	global_store_dwordx4 v[166:167], v[82:85], off offset:256
	s_and_saveexec_b64 s[30:31], s[2:3]
	s_cbranch_execz .LBB0_1169
	v_lshlrev_b64 v[82:83], 6, v[164:165]
	v_lshl_add_u64 v[82:83], s[8:9], 0, v[82:83]
	v_lshl_add_u64 v[82:83], s[28:29], 2, v[82:83]
	s_lshl_b32 s10, s63, 2
	v_lshl_add_u64 v[82:83], v[82:83], 0, s[10:11]
	s_waitcnt lgkmcnt(0)
	v_add_f32_e32 v80, v80, v81
	global_store_dword v[82:83], v80, off
.LBB0_1169:
	s_or_b64 exec, exec, s[30:31]
	s_waitcnt lgkmcnt(0)
	v_lshl_add_u64 v[80:81], v[160:161], 1, v[162:163]
	v_lshl_add_u64 v[88:89], v[80:81], 0, s[18:19]
	v_add_co_u32_e32 v80, vcc, 0x48000, v80
	s_waitcnt vmcnt(7)
	v_lshlrev_b32_e32 v90, 16, v116
	v_addc_co_u32_e32 v81, vcc, 0, v81, vcc
	global_load_dwordx4 v[84:87], v[80:81], off
	s_nop 0
	global_load_dwordx4 v[80:83], v[88:89], off offset:256
	v_and_b32_e32 v91, 0xffff0000, v116
	v_lshlrev_b32_e32 v92, 16, v117
	v_and_b32_e32 v93, 0xffff0000, v117
	v_pk_add_f32 v[78:79], v[78:79], v[92:93]
	v_pk_add_f32 v[76:77], v[76:77], v[90:91]
	v_lshlrev_b32_e32 v90, 16, v118
	v_and_b32_e32 v91, 0xffff0000, v118
	v_lshlrev_b32_e32 v92, 16, v119
	v_and_b32_e32 v93, 0xffff0000, v119
	v_pk_add_f32 v[92:93], v[74:75], v[92:93]
	v_pk_add_f32 v[74:75], v[72:73], v[90:91]
	v_cvt_pk_bf16_f32 v72, v76, v77
	v_mul_f32_e32 v77, v77, v77
	v_fmac_f32_e32 v77, v76, v76
	v_mul_f32_e32 v76, v79, v79
	v_fmac_f32_e32 v76, v78, v78
	v_cvt_pk_bf16_f32 v73, v78, v79
	v_add_f32_e32 v76, v77, v76
	v_mul_f32_e32 v77, v75, v75
	v_mul_f32_e32 v78, v93, v93
	v_fmac_f32_e32 v77, v74, v74
	v_fmac_f32_e32 v78, v92, v92
	v_add_f32_e32 v77, v77, v78
	v_add_f32_e32 v90, v76, v77
	s_waitcnt vmcnt(8)
	v_lshlrev_b32_e32 v76, 16, v112
	v_and_b32_e32 v77, 0xffff0000, v112
	v_lshlrev_b32_e32 v78, 16, v113
	v_and_b32_e32 v79, 0xffff0000, v113
	v_pk_add_f32 v[70:71], v[70:71], v[78:79]
	v_pk_add_f32 v[68:69], v[68:69], v[76:77]
	v_lshlrev_b32_e32 v76, 16, v114
	v_and_b32_e32 v77, 0xffff0000, v114
	v_lshlrev_b32_e32 v78, 16, v115
	v_and_b32_e32 v79, 0xffff0000, v115
	v_pk_add_f32 v[76:77], v[64:65], v[76:77]
	v_mul_f32_e32 v64, v69, v69
	v_mul_f32_e32 v65, v71, v71
	v_pk_add_f32 v[78:79], v[66:67], v[78:79]
	v_fmac_f32_e32 v64, v68, v68
	v_fmac_f32_e32 v65, v70, v70
	v_add_f32_e32 v64, v64, v65
	v_mul_f32_e32 v65, v77, v77
	v_mul_f32_e32 v66, v79, v79
	v_fmac_f32_e32 v65, v76, v76
	v_fmac_f32_e32 v66, v78, v78
	v_add_f32_e32 v65, v65, v66
	v_add_f32_e32 v64, v64, v65
	v_add_f32_e32 v64, v90, v64
	v_mov_b32_e32 v65, v64
	v_cvt_pk_bf16_f32 v74, v74, v75
	v_cvt_pk_bf16_f32 v75, v92, v93
	global_store_dwordx4 v[122:123], v[72:75], off
	v_cvt_pk_bf16_f32 v66, v68, v69
	s_waitcnt lgkmcnt(0)
	s_nop 1
	v_permlane16_swap_b32_e32 v65, v64
	v_add_f32_e32 v64, v64, v65
	ds_bpermute_b32 v65, v175, v64
	v_cvt_pk_bf16_f32 v67, v70, v71
	v_cvt_pk_bf16_f32 v68, v76, v77
	v_cvt_pk_bf16_f32 v69, v78, v79
	global_store_dwordx4 v[122:123], v[66:69], off offset:256
	s_and_saveexec_b64 s[30:31], s[2:3]
	s_cbranch_execz .LBB0_1171
	v_lshlrev_b64 v[66:67], 6, v[120:121]
	v_lshl_add_u64 v[66:67], s[8:9], 0, v[66:67]
	v_lshl_add_u64 v[66:67], s[28:29], 2, v[66:67]
	s_lshl_b32 s10, s63, 2
	v_lshl_add_u64 v[66:67], v[66:67], 0, s[10:11]
	s_waitcnt lgkmcnt(0)
	v_add_f32_e32 v64, v64, v65
	global_store_dword v[66:67], v64, off
.LBB0_1171:
	s_or_b64 exec, exec, s[30:31]
	v_or_b32_e32 v72, 32, v104
	v_ashrrev_i32_e32 v73, 31, v72
	s_waitcnt lgkmcnt(0)
	v_lshlrev_b64 v[64:65], 11, v[72:73]
	v_lshl_add_u64 v[64:65], s[46:47], 0, v[64:65]
	v_lshl_add_u64 v[74:75], v[160:161], 1, v[64:65]
	global_load_dwordx4 v[68:71], v[74:75], off
	global_load_dwordx4 v[64:67], v[74:75], off offset:256
	s_waitcnt vmcnt(9)
	v_lshlrev_b32_e32 v76, 16, v100
	v_and_b32_e32 v77, 0xffff0000, v100
	v_lshlrev_b32_e32 v78, 16, v101
	v_and_b32_e32 v79, 0xffff0000, v101
	v_pk_add_f32 v[62:63], v[62:63], v[78:79]
	v_pk_add_f32 v[60:61], v[60:61], v[76:77]
	v_lshlrev_b32_e32 v76, 16, v102
	v_and_b32_e32 v77, 0xffff0000, v102
	v_lshlrev_b32_e32 v78, 16, v103
	v_and_b32_e32 v79, 0xffff0000, v103
	v_pk_add_f32 v[78:79], v[58:59], v[78:79]
	v_pk_add_f32 v[58:59], v[56:57], v[76:77]
	v_cvt_pk_bf16_f32 v56, v60, v61
	v_mul_f32_e32 v61, v61, v61
	v_fmac_f32_e32 v61, v60, v60
	v_mul_f32_e32 v60, v63, v63
	v_fmac_f32_e32 v60, v62, v62
	v_cvt_pk_bf16_f32 v57, v62, v63
	v_add_f32_e32 v60, v61, v60
	v_mul_f32_e32 v61, v59, v59
	v_mul_f32_e32 v62, v79, v79
	v_fmac_f32_e32 v61, v58, v58
	v_fmac_f32_e32 v62, v78, v78
	v_add_f32_e32 v61, v61, v62
	v_add_f32_e32 v76, v60, v61
	s_waitcnt vmcnt(8)
	v_lshlrev_b32_e32 v60, 16, v96
	v_and_b32_e32 v61, 0xffff0000, v96
	v_lshlrev_b32_e32 v62, 16, v97
	v_and_b32_e32 v63, 0xffff0000, v97
	v_pk_add_f32 v[54:55], v[54:55], v[62:63]
	v_pk_add_f32 v[52:53], v[52:53], v[60:61]
	v_lshlrev_b32_e32 v60, 16, v98
	v_and_b32_e32 v61, 0xffff0000, v98
	v_lshlrev_b32_e32 v62, 16, v99
	v_and_b32_e32 v63, 0xffff0000, v99
	v_pk_add_f32 v[60:61], v[48:49], v[60:61]
	v_mul_f32_e32 v48, v53, v53
	v_mul_f32_e32 v49, v55, v55
	v_pk_add_f32 v[62:63], v[50:51], v[62:63]
	v_fmac_f32_e32 v48, v52, v52
	v_fmac_f32_e32 v49, v54, v54
	v_add_f32_e32 v48, v48, v49
	v_mul_f32_e32 v49, v61, v61
	v_mul_f32_e32 v50, v63, v63
	v_fmac_f32_e32 v49, v60, v60
	v_fmac_f32_e32 v50, v62, v62
	v_add_f32_e32 v49, v49, v50
	v_add_f32_e32 v48, v48, v49
	v_add_f32_e32 v48, v76, v48
	v_mov_b32_e32 v49, v48
	v_cvt_pk_bf16_f32 v58, v58, v59
	v_cvt_pk_bf16_f32 v59, v78, v79
	global_store_dwordx4 v[106:107], v[56:59], off
	v_cvt_pk_bf16_f32 v50, v52, v53
	s_waitcnt lgkmcnt(0)
	s_nop 1
	v_permlane16_swap_b32_e32 v49, v48
	v_add_f32_e32 v48, v48, v49
	ds_bpermute_b32 v49, v175, v48
	v_cvt_pk_bf16_f32 v51, v54, v55
	v_cvt_pk_bf16_f32 v52, v60, v61
	v_cvt_pk_bf16_f32 v53, v62, v63
	global_store_dwordx4 v[106:107], v[50:53], off offset:256
	s_and_saveexec_b64 s[30:31], s[2:3]
	s_cbranch_execz .LBB0_1173
	v_lshlrev_b64 v[50:51], 6, v[104:105]
	v_lshl_add_u64 v[50:51], s[8:9], 0, v[50:51]
	v_lshl_add_u64 v[50:51], s[28:29], 2, v[50:51]
	s_lshl_b32 s10, s63, 2
	v_lshl_add_u64 v[50:51], v[50:51], 0, s[10:11]
	s_waitcnt lgkmcnt(0)
	v_add_f32_e32 v48, v48, v49
	global_store_dword v[50:51], v48, off
.LBB0_1173:
	s_or_b64 exec, exec, s[30:31]
	v_or_b32_e32 v56, 48, v104
	v_ashrrev_i32_e32 v57, 31, v56
	s_waitcnt lgkmcnt(0)
	v_lshlrev_b64 v[48:49], 11, v[56:57]
	v_lshl_add_u64 v[48:49], s[46:47], 0, v[48:49]
	v_lshl_add_u64 v[58:59], v[160:161], 1, v[48:49]
	global_load_dwordx4 v[52:55], v[58:59], off
	global_load_dwordx4 v[48:51], v[58:59], off offset:256
	s_waitcnt vmcnt(9)
	v_lshlrev_b32_e32 v60, 16, v84
	v_and_b32_e32 v61, 0xffff0000, v84
	v_lshlrev_b32_e32 v62, 16, v85
	v_and_b32_e32 v63, 0xffff0000, v85
	v_pk_add_f32 v[46:47], v[46:47], v[62:63]
	v_pk_add_f32 v[44:45], v[44:45], v[60:61]
	v_lshlrev_b32_e32 v60, 16, v86
	v_and_b32_e32 v61, 0xffff0000, v86
	v_lshlrev_b32_e32 v62, 16, v87
	v_and_b32_e32 v63, 0xffff0000, v87
	v_pk_add_f32 v[62:63], v[42:43], v[62:63]
	v_pk_add_f32 v[42:43], v[40:41], v[60:61]
	v_cvt_pk_bf16_f32 v40, v44, v45
	v_mul_f32_e32 v45, v45, v45
	v_fmac_f32_e32 v45, v44, v44
	v_mul_f32_e32 v44, v47, v47
	v_fmac_f32_e32 v44, v46, v46
	v_cvt_pk_bf16_f32 v41, v46, v47
	v_add_f32_e32 v44, v45, v44
	v_mul_f32_e32 v45, v43, v43
	v_mul_f32_e32 v46, v63, v63
	v_fmac_f32_e32 v45, v42, v42
	v_fmac_f32_e32 v46, v62, v62
	v_add_f32_e32 v45, v45, v46
	v_add_f32_e32 v60, v44, v45
	s_waitcnt vmcnt(8)
	v_lshlrev_b32_e32 v44, 16, v80
	v_and_b32_e32 v45, 0xffff0000, v80
	v_lshlrev_b32_e32 v46, 16, v81
	v_and_b32_e32 v47, 0xffff0000, v81
	v_pk_add_f32 v[38:39], v[38:39], v[46:47]
	v_pk_add_f32 v[36:37], v[36:37], v[44:45]
	v_lshlrev_b32_e32 v44, 16, v82
	v_and_b32_e32 v45, 0xffff0000, v82
	v_lshlrev_b32_e32 v46, 16, v83
	v_and_b32_e32 v47, 0xffff0000, v83
	v_pk_add_f32 v[44:45], v[32:33], v[44:45]
	v_mul_f32_e32 v32, v37, v37
	v_mul_f32_e32 v33, v39, v39
	v_pk_add_f32 v[46:47], v[34:35], v[46:47]
	v_fmac_f32_e32 v32, v36, v36
	v_fmac_f32_e32 v33, v38, v38
	v_add_f32_e32 v32, v32, v33
	v_mul_f32_e32 v33, v45, v45
	v_mul_f32_e32 v34, v47, v47
	v_fmac_f32_e32 v33, v44, v44
	v_fmac_f32_e32 v34, v46, v46
	v_add_f32_e32 v33, v33, v34
	v_add_f32_e32 v32, v32, v33
	v_add_f32_e32 v32, v60, v32
	v_mov_b32_e32 v33, v32
	v_cvt_pk_bf16_f32 v42, v42, v43
	v_cvt_pk_bf16_f32 v43, v62, v63
	global_store_dwordx4 v[88:89], v[40:43], off
	v_cvt_pk_bf16_f32 v34, v36, v37
	s_waitcnt lgkmcnt(0)
	s_nop 1
	v_permlane16_swap_b32_e32 v33, v32
	v_add_f32_e32 v32, v32, v33
	ds_bpermute_b32 v33, v175, v32
	v_cvt_pk_bf16_f32 v35, v38, v39
	v_cvt_pk_bf16_f32 v36, v44, v45
	v_cvt_pk_bf16_f32 v37, v46, v47
	global_store_dwordx4 v[88:89], v[34:37], off offset:256
	s_and_saveexec_b64 s[30:31], s[2:3]
	s_cbranch_execz .LBB0_1175
	v_or_b32_e32 v34, 16, v104
	v_ashrrev_i32_e32 v35, 31, v34
	v_lshlrev_b64 v[34:35], 6, v[34:35]
	v_lshl_add_u64 v[34:35], s[8:9], 0, v[34:35]
	v_lshl_add_u64 v[34:35], s[28:29], 2, v[34:35]
	s_lshl_b32 s10, s63, 2
	v_lshl_add_u64 v[34:35], v[34:35], 0, s[10:11]
	s_waitcnt lgkmcnt(0)
	v_add_f32_e32 v32, v32, v33
	global_store_dword v[34:35], v32, off
.LBB0_1175:
	s_or_b64 exec, exec, s[30:31]
	s_waitcnt vmcnt(7)
	v_lshlrev_b32_e32 v32, 16, v68
	s_waitcnt lgkmcnt(0)
	v_and_b32_e32 v33, 0xffff0000, v68
	v_lshlrev_b32_e32 v34, 16, v69
	v_and_b32_e32 v35, 0xffff0000, v69
	v_pk_add_f32 v[30:31], v[30:31], v[34:35]
	v_pk_add_f32 v[28:29], v[28:29], v[32:33]
	v_lshlrev_b32_e32 v32, 16, v70
	v_and_b32_e32 v33, 0xffff0000, v70
	v_lshlrev_b32_e32 v34, 16, v71
	v_and_b32_e32 v35, 0xffff0000, v71
	v_pk_add_f32 v[34:35], v[26:27], v[34:35]
	v_pk_add_f32 v[26:27], v[24:25], v[32:33]
	v_cvt_pk_bf16_f32 v24, v28, v29
	v_mul_f32_e32 v29, v29, v29
	v_fmac_f32_e32 v29, v28, v28
	v_mul_f32_e32 v28, v31, v31
	v_fmac_f32_e32 v28, v30, v30
	v_cvt_pk_bf16_f32 v25, v30, v31
	v_add_f32_e32 v28, v29, v28
	v_mul_f32_e32 v29, v27, v27
	v_mul_f32_e32 v30, v35, v35
	v_fmac_f32_e32 v29, v26, v26
	v_fmac_f32_e32 v30, v34, v34
	v_add_f32_e32 v29, v29, v30
	v_add_f32_e32 v32, v28, v29
	s_waitcnt vmcnt(6)
	v_lshlrev_b32_e32 v28, 16, v64
	v_and_b32_e32 v29, 0xffff0000, v64
	v_lshlrev_b32_e32 v30, 16, v65
	v_and_b32_e32 v31, 0xffff0000, v65
	v_pk_add_f32 v[22:23], v[22:23], v[30:31]
	v_pk_add_f32 v[20:21], v[20:21], v[28:29]
	v_lshlrev_b32_e32 v28, 16, v66
	v_and_b32_e32 v29, 0xffff0000, v66
	v_lshlrev_b32_e32 v30, 16, v67
	v_and_b32_e32 v31, 0xffff0000, v67
	v_pk_add_f32 v[28:29], v[16:17], v[28:29]
	v_mul_f32_e32 v16, v21, v21
	v_mul_f32_e32 v17, v23, v23
	v_pk_add_f32 v[30:31], v[18:19], v[30:31]
	v_fmac_f32_e32 v16, v20, v20
	v_fmac_f32_e32 v17, v22, v22
	v_add_f32_e32 v16, v16, v17
	v_mul_f32_e32 v17, v29, v29
	v_mul_f32_e32 v18, v31, v31
	v_fmac_f32_e32 v17, v28, v28
	v_fmac_f32_e32 v18, v30, v30
	v_add_f32_e32 v17, v17, v18
	v_add_f32_e32 v16, v16, v17
	v_add_f32_e32 v16, v32, v16
	v_mov_b32_e32 v17, v16
	v_cvt_pk_bf16_f32 v26, v26, v27
	v_cvt_pk_bf16_f32 v27, v34, v35
	global_store_dwordx4 v[74:75], v[24:27], off
	v_cvt_pk_bf16_f32 v18, v20, v21
	s_waitcnt lgkmcnt(0)
	s_nop 1
	v_permlane16_swap_b32_e32 v17, v16
	v_add_f32_e32 v16, v16, v17
	ds_bpermute_b32 v17, v175, v16
	v_cvt_pk_bf16_f32 v19, v22, v23
	v_cvt_pk_bf16_f32 v20, v28, v29
	v_cvt_pk_bf16_f32 v21, v30, v31
	global_store_dwordx4 v[74:75], v[18:21], off offset:256
	s_and_saveexec_b64 s[30:31], s[2:3]
	s_cbranch_execz .LBB0_1177
	v_lshlrev_b64 v[18:19], 6, v[72:73]
	v_lshl_add_u64 v[18:19], s[8:9], 0, v[18:19]
	v_lshl_add_u64 v[18:19], s[28:29], 2, v[18:19]
	s_lshl_b32 s10, s63, 2
	v_lshl_add_u64 v[18:19], v[18:19], 0, s[10:11]
	s_waitcnt lgkmcnt(0)
	v_add_f32_e32 v16, v16, v17
	global_store_dword v[18:19], v16, off
.LBB0_1177:
	s_or_b64 exec, exec, s[30:31]
	s_waitcnt vmcnt(5)
	v_lshlrev_b32_e32 v16, 16, v52
	s_waitcnt lgkmcnt(0)
	v_and_b32_e32 v17, 0xffff0000, v52
	v_lshlrev_b32_e32 v18, 16, v53
	v_and_b32_e32 v19, 0xffff0000, v53
	v_pk_add_f32 v[14:15], v[14:15], v[18:19]
	v_pk_add_f32 v[12:13], v[12:13], v[16:17]
	v_lshlrev_b32_e32 v16, 16, v54
	v_and_b32_e32 v17, 0xffff0000, v54
	v_lshlrev_b32_e32 v18, 16, v55
	v_and_b32_e32 v19, 0xffff0000, v55
	v_pk_add_f32 v[18:19], v[10:11], v[18:19]
	v_pk_add_f32 v[10:11], v[8:9], v[16:17]
	v_cvt_pk_bf16_f32 v8, v12, v13
	v_mul_f32_e32 v13, v13, v13
	v_fmac_f32_e32 v13, v12, v12
	v_mul_f32_e32 v12, v15, v15
	v_fmac_f32_e32 v12, v14, v14
	v_cvt_pk_bf16_f32 v9, v14, v15
	v_add_f32_e32 v12, v13, v12
	v_mul_f32_e32 v13, v11, v11
	v_mul_f32_e32 v14, v19, v19
	v_fmac_f32_e32 v13, v10, v10
	v_fmac_f32_e32 v14, v18, v18
	v_add_f32_e32 v13, v13, v14
	v_add_f32_e32 v16, v12, v13
	s_waitcnt vmcnt(4)
	v_lshlrev_b32_e32 v12, 16, v48
	v_and_b32_e32 v13, 0xffff0000, v48
	v_lshlrev_b32_e32 v14, 16, v49
	v_and_b32_e32 v15, 0xffff0000, v49
	v_pk_add_f32 v[6:7], v[6:7], v[14:15]
	v_pk_add_f32 v[4:5], v[4:5], v[12:13]
	v_lshlrev_b32_e32 v12, 16, v50
	v_and_b32_e32 v13, 0xffff0000, v50
	v_lshlrev_b32_e32 v14, 16, v51
	v_and_b32_e32 v15, 0xffff0000, v51
	v_pk_add_f32 v[12:13], v[0:1], v[12:13]
	v_mul_f32_e32 v0, v5, v5
	v_mul_f32_e32 v1, v7, v7
	v_pk_add_f32 v[14:15], v[2:3], v[14:15]
	v_fmac_f32_e32 v0, v4, v4
	v_fmac_f32_e32 v1, v6, v6
	v_add_f32_e32 v0, v0, v1
	v_mul_f32_e32 v1, v13, v13
	v_mul_f32_e32 v2, v15, v15
	v_fmac_f32_e32 v1, v12, v12
	v_fmac_f32_e32 v2, v14, v14
	v_add_f32_e32 v1, v1, v2
	v_add_f32_e32 v0, v0, v1
	v_add_f32_e32 v0, v16, v0
	v_mov_b32_e32 v1, v0
	v_cvt_pk_bf16_f32 v10, v10, v11
	v_cvt_pk_bf16_f32 v11, v18, v19
	global_store_dwordx4 v[58:59], v[8:11], off
	v_cvt_pk_bf16_f32 v2, v4, v5
	s_waitcnt lgkmcnt(0)
	s_nop 1
	v_permlane16_swap_b32_e32 v1, v0
	v_add_f32_e32 v0, v0, v1
	ds_bpermute_b32 v1, v175, v0
	v_cvt_pk_bf16_f32 v3, v6, v7
	v_cvt_pk_bf16_f32 v4, v12, v13
	v_cvt_pk_bf16_f32 v5, v14, v15
	global_store_dwordx4 v[58:59], v[2:5], off offset:256
	s_and_saveexec_b64 s[30:31], s[2:3]
	s_cbranch_execz .LBB0_1179
	v_lshlrev_b64 v[2:3], 6, v[56:57]
	v_lshl_add_u64 v[2:3], s[8:9], 0, v[2:3]
	v_lshl_add_u64 v[2:3], s[28:29], 2, v[2:3]
	s_lshl_b32 s10, s63, 2
	v_lshl_add_u64 v[2:3], v[2:3], 0, s[10:11]
	s_waitcnt lgkmcnt(0)
	v_add_f32_e32 v0, v0, v1
	global_store_dword v[2:3], v0, off

.LBB0_1212:
	s_lshl_b32 s51, s58, 8
	s_add_i32 s51, s51, s78
	v_or_b32_e32 v156, s51, v210
	v_ashrrev_i32_e32 v157, 31, v156
	v_or_b32_e32 v170, 16, v156
	v_or_b32_e32 v168, 32, v156
	v_or_b32_e32 v166, 48, v156
	v_lshlrev_b64 v[146:147], 6, v[156:157]
	v_ashrrev_i32_e32 v171, 31, v170
	v_ashrrev_i32_e32 v169, 31, v168
	v_ashrrev_i32_e32 v167, 31, v166
	v_lshl_add_u64 v[154:155], v[136:137], 0, v[146:147]
	v_lshlrev_b64 v[146:147], 6, v[170:171]
	v_lshlrev_b64 v[158:159], 6, v[168:169]
	v_lshlrev_b64 v[162:163], 6, v[166:167]
	v_lshl_add_u64 v[150:151], v[136:137], 0, v[146:147]
	v_lshl_add_u64 v[158:159], v[136:137], 0, v[158:159]
	v_lshl_add_u64 v[162:163], v[136:137], 0, v[162:163]
	global_load_dwordx4 v[146:149], v[154:155], off
	s_nop 0
	global_load_dwordx4 v[150:153], v[150:151], off
	s_waitcnt vmcnt(0)
	v_mov_b32_e32 v172, v147
	global_load_dwordx4 v[158:161], v[158:159], off
	v_mov_b32_e32 v173, v148
	global_load_dwordx4 v[162:165], v[162:163], off
	v_mov_b32_e32 v147, v149
	v_pk_add_f32 v[146:147], v[172:173], v[146:147]
	v_mov_b32_e32 v148, v151
	v_mov_b32_e32 v149, v152
	v_mov_b32_e32 v151, v153
	v_add_f32_e32 v157, v146, v147
	v_pk_add_f32 v[146:147], v[148:149], v[150:151]
	s_waitcnt vmcnt(1)
	v_mov_b32_e32 v152, v159
	v_mov_b32_e32 v153, v160
	v_mov_b32_e32 v159, v161
	s_waitcnt vmcnt(0)
	v_mov_b32_e32 v160, v163
	v_mov_b32_e32 v161, v164
	v_mov_b32_e32 v163, v165
	v_pk_add_f32 v[148:149], v[152:153], v[158:159]
	v_pk_add_f32 v[150:151], v[160:161], v[162:163]
	v_add_f32_e32 v146, v146, v147
	v_add_f32_e32 v147, v148, v149
	v_add_f32_e32 v148, v150, v151
	v_mov_b32_e32 v152, v157
	v_mov_b32_e32 v149, v146
	v_mov_b32_e32 v150, v147
	v_mov_b32_e32 v151, v148
	s_waitcnt lgkmcnt(3)
	s_nop 1
	v_permlane16_swap_b32_e32 v152, v157
	v_add_f32_e32 v152, v157, v152
	s_waitcnt lgkmcnt(2)
	s_nop 1
	v_permlane16_swap_b32_e32 v149, v146
	v_add_f32_e32 v146, v146, v149
	s_waitcnt lgkmcnt(1)
	s_nop 1
	v_permlane16_swap_b32_e32 v150, v147
	v_add_f32_e32 v147, v147, v150
	s_waitcnt lgkmcnt(0)
	s_nop 1
	v_permlane16_swap_b32_e32 v151, v148
	v_add_f32_e32 v148, v148, v151
	v_mov_b32_e32 v153, v152
	v_mov_b32_e32 v149, v146
	v_mov_b32_e32 v150, v147
	v_mov_b32_e32 v151, v148
	s_waitcnt lgkmcnt(3)
	s_nop 1
	v_permlane32_swap_b32_e32 v153, v152
	v_add_f32_e32 v152, v152, v153
	s_waitcnt lgkmcnt(2)
	s_nop 1
	v_permlane32_swap_b32_e32 v149, v146
	v_add_f32_e32 v146, v146, v149
	s_waitcnt lgkmcnt(1)
	s_nop 1
	v_permlane32_swap_b32_e32 v150, v147
	v_add_f32_e32 v147, v147, v150
	s_waitcnt lgkmcnt(0)
	s_nop 1
	v_permlane32_swap_b32_e32 v151, v148
	v_add_f32_e32 v148, v148, v151
	v_fmamk_f32 v152, v152, 0x3a800000, v219
	v_fmamk_f32 v146, v146, 0x3a800000, v219
	v_fmamk_f32 v147, v147, 0x3a800000, v219
	v_fmamk_f32 v148, v148, 0x3a800000, v219
	v_rsq_f32_e32 v164, v152
	v_rsq_f32_e32 v162, v146
	v_rsq_f32_e32 v160, v147
	v_rsq_f32_e32 v158, v148
	v_add_co_u32_e32 v154, vcc, s73, v154
	s_nop 1
	v_addc_co_u32_e32 v155, vcc, 0, v155, vcc
	global_load_dwordx4 v[146:149], v[154:155], off
	global_load_dwordx4 v[150:153], v[154:155], off offset:1024
	global_load_dwordx4 v[172:175], v[154:155], off offset:2048
	global_load_dwordx4 v[176:179], v[154:155], off offset:3072
	s_waitcnt vmcnt(3)
	v_mov_b32_e32 v154, v147
	v_mov_b32_e32 v155, v148
	v_mov_b32_e32 v147, v149
	s_waitcnt vmcnt(2)
	v_mov_b32_e32 v148, v151
	v_mov_b32_e32 v149, v152
	v_mov_b32_e32 v151, v153
	s_waitcnt vmcnt(1)
	v_mov_b32_e32 v152, v173
	v_mov_b32_e32 v153, v174
	v_mov_b32_e32 v173, v175
	s_waitcnt vmcnt(0)
	v_mov_b32_e32 v174, v177
	v_mov_b32_e32 v175, v178
	v_mov_b32_e32 v177, v179
	v_pk_add_f32 v[146:147], v[154:155], v[146:147]
	v_pk_add_f32 v[148:149], v[148:149], v[150:151]
	v_pk_add_f32 v[150:151], v[152:153], v[172:173]
	v_pk_add_f32 v[152:153], v[174:175], v[176:177]
	v_add_f32_e32 v146, v146, v147
	v_add_f32_e32 v147, v148, v149
	v_add_f32_e32 v148, v150, v151
	v_add_f32_e32 v149, v152, v153
	v_mov_b32_e32 v150, v146
	v_mov_b32_e32 v151, v147
	v_mov_b32_e32 v152, v148
	v_mov_b32_e32 v153, v149
	s_waitcnt lgkmcnt(3)
	s_nop 1
	v_permlane16_swap_b32_e32 v150, v146
	v_add_f32_e32 v146, v146, v150
	s_waitcnt lgkmcnt(2)
	s_nop 1
	v_permlane16_swap_b32_e32 v151, v147
	v_add_f32_e32 v147, v147, v151
	s_waitcnt lgkmcnt(1)
	s_nop 1
	v_permlane16_swap_b32_e32 v152, v148
	v_add_f32_e32 v148, v148, v152
	s_waitcnt lgkmcnt(0)
	s_nop 1
	v_permlane16_swap_b32_e32 v153, v149
	v_add_f32_e32 v149, v149, v153
	v_mov_b32_e32 v150, v146
	ds_bpermute_b32 v151, v213, v147
	v_mov_b32_e32 v152, v148
	ds_bpermute_b32 v153, v213, v149
	s_waitcnt lgkmcnt(3)
	s_nop 1
	v_permlane32_swap_b32_e32 v150, v146
	v_add_f32_e32 v146, v146, v150
	s_waitcnt lgkmcnt(2)
	v_add_f32_e32 v147, v147, v151
	s_waitcnt lgkmcnt(1)
	s_nop 1
	v_permlane32_swap_b32_e32 v152, v148
	v_add_f32_e32 v148, v148, v152
	s_waitcnt lgkmcnt(0)
	v_add_f32_e32 v149, v149, v153
	v_fmamk_f32 v146, v146, 0x3a800000, v219
	v_fmamk_f32 v147, v147, 0x3a800000, v219
	v_fmamk_f32 v148, v148, 0x3a800000, v219
	v_fmamk_f32 v149, v149, 0x3a800000, v219
	v_rsq_f32_e32 v154, v146
	v_rsq_f32_e32 v152, v147
	v_rsq_f32_e32 v150, v148
	v_rsq_f32_e32 v148, v149
	v_lshl_or_b32 v146, s56, 7, v215
	v_ashrrev_i32_e32 v147, 31, v146
	v_lshlrev_b64 v[172:173], 2, v[146:147]
	v_lshl_add_u64 v[174:175], s[16:17], 0, v[172:173]
	v_lshl_add_u64 v[176:177], s[8:9], 0, v[172:173]
	v_lshl_add_u64 v[178:179], s[24:25], 0, v[172:173]
	global_load_dwordx2 v[202:203], v[174:175], off
	global_load_dwordx2 v[208:209], v[176:177], off
	global_load_dwordx2 v[206:207], v[178:179], off
	v_lshl_add_u64 v[174:175], s[18:19], 0, v[172:173]
	global_load_dwordx2 v[204:205], v[174:175], off
	v_lshl_add_u64 v[174:175], s[26:27], 0, v[172:173]
	v_lshl_add_u64 v[178:179], s[28:29], 0, v[172:173]
	v_lshl_add_u64 v[180:181], s[30:31], 0, v[172:173]
	global_load_dwordx2 v[176:177], v[174:175], off
	global_load_dwordx2 v[200:201], v[178:179], off
	global_load_dwordx2 v[196:197], v[180:181], off
	v_lshl_add_u64 v[172:173], s[42:43], 0, v[172:173]
	global_load_dwordx2 v[198:199], v[172:173], off
	v_pk_mul_f32 v[126:127], v[126:127], v[164:165] op_sel_hi:[1,0]
	v_pk_mul_f32 v[124:125], v[124:125], v[164:165] op_sel_hi:[1,0]
	v_pk_mul_f32 v[122:123], v[122:123], v[164:165] op_sel_hi:[1,0]
	v_pk_mul_f32 v[120:121], v[120:121], v[164:165] op_sel_hi:[1,0]
	v_pk_mul_f32 v[180:181], v[116:117], v[162:163] op_sel_hi:[1,0]
	v_pk_mul_f32 v[182:183], v[104:105], v[162:163] op_sel_hi:[1,0]
	v_pk_mul_f32 v[178:179], v[112:113], v[160:161] op_sel_hi:[1,0]
	v_pk_mul_f32 v[172:173], v[100:101], v[160:161] op_sel_hi:[1,0]
	v_pk_mul_f32 v[100:101], v[108:109], v[158:159] op_sel_hi:[1,0]
	v_pk_mul_f32 v[96:97], v[96:97], v[158:159] op_sel_hi:[1,0]
	v_pk_mul_f32 v[92:93], v[92:93], v[154:155] op_sel_hi:[1,0]
	v_pk_mul_f32 v[88:89], v[88:89], v[154:155] op_sel_hi:[1,0]
	v_pk_mul_f32 v[116:117], v[84:85], v[152:153] op_sel_hi:[1,0]
	v_pk_mul_f32 v[84:85], v[68:69], v[150:151] op_sel_hi:[1,0]
	v_pk_mul_f32 v[68:69], v[76:77], v[148:149] op_sel_hi:[1,0]
	v_pk_mul_f32 v[64:65], v[64:65], v[148:149] op_sel_hi:[1,0]
	v_pk_mul_f32 v[112:113], v[72:73], v[152:153] op_sel_hi:[1,0]
	v_pk_mul_f32 v[104:105], v[80:81], v[150:151] op_sel_hi:[1,0]
	s_waitcnt vmcnt(6)
	v_mul_f32_dpp v73, v124, v208 row_shr:1 row_mask:0xf bank_mask:0xf bound_ctrl:1
	v_mov_b32_dpp v72, v124 row_shr:2 row_mask:0xf bank_mask:0xf bound_ctrl:1
	s_waitcnt vmcnt(5)
	v_fmac_f32_e32 v73, v124, v206
	v_fmac_f32_e32 v73, v202, v72
	s_waitcnt vmcnt(4)
	v_add_f32_e32 v72, v204, v73
	v_mul_f32_e32 v73, 0xbfb8aa3b, v72
	v_exp_f32_e32 v73, v73
	s_waitcnt vmcnt(2)
	v_mul_f32_dpp v77, v120, v200 row_shr:1 row_mask:0xf bank_mask:0xf bound_ctrl:1
	v_mov_b32_dpp v76, v120 row_shr:2 row_mask:0xf bank_mask:0xf bound_ctrl:1
	s_waitcnt vmcnt(1)
	v_fmac_f32_e32 v77, v120, v196
	v_add_f32_e32 v73, 1.0, v73
	v_rcp_f32_e32 v73, v73
	v_fmac_f32_e32 v77, v176, v76
	s_waitcnt vmcnt(0)
	v_add_f32_e32 v76, v198, v77
	v_mul_f32_dpp v80, v121, v201 row_shr:1 row_mask:0xf bank_mask:0xf bound_ctrl:1
	v_mul_f32_dpp v77, v125, v209 row_shr:1 row_mask:0xf bank_mask:0xf bound_ctrl:1
	v_mul_f32_e32 v72, v72, v73
	v_mov_b32_dpp v73, v125 row_shr:2 row_mask:0xf bank_mask:0xf bound_ctrl:1
	v_fmac_f32_e32 v77, v125, v207
	v_fmac_f32_e32 v77, v203, v73
	v_add_f32_e32 v73, v205, v77
	v_mul_f32_e32 v77, 0xbfb8aa3b, v73
	v_exp_f32_e32 v77, v77
	v_mul_f32_e32 v72, v76, v72
	v_mov_b32_dpp v76, v121 row_shr:2 row_mask:0xf bank_mask:0xf bound_ctrl:1
	v_fmac_f32_e32 v80, v121, v197
	v_add_f32_e32 v77, 1.0, v77
	v_rcp_f32_e32 v77, v77
	v_fmac_f32_e32 v80, v177, v76
	v_add_f32_e32 v76, v199, v80
	v_or_b32_e32 v174, 2, v146
	v_mul_f32_e32 v73, v73, v77
	v_mul_f32_e32 v73, v76, v73
	v_cvt_pk_bf16_f32 v80, v72, v73
	v_ashrrev_i32_e32 v175, 31, v174
	v_mov_b32_dpp v72, v124 row_ror:1 row_mask:0xf bank_mask:0xf bound_ctrl:1
	v_mov_b32_dpp v73, v124 row_ror:2 row_mask:0xf bank_mask:0xf bound_ctrl:1
	v_mov_b32_dpp v76, v120 row_ror:1 row_mask:0xf bank_mask:0xf bound_ctrl:1
	v_mov_b32_dpp v72, v180 row_shr:1 row_mask:0xf bank_mask:0xf
	v_mul_f32_e32 v72, v208, v72
	v_mov_b32_dpp v73, v180 row_shr:2 row_mask:0xf bank_mask:0xf
	v_fmac_f32_e32 v72, v180, v206
	v_fmac_f32_e32 v72, v202, v73
	v_add_f32_e32 v72, v204, v72
	v_mul_f32_e32 v73, 0xbfb8aa3b, v72
	v_exp_f32_e32 v73, v73
	v_mov_b32_dpp v76, v182 row_shr:1 row_mask:0xf bank_mask:0xf
	v_mov_b32_dpp v77, v120 row_ror:2 row_mask:0xf bank_mask:0xf bound_ctrl:1
	v_mul_f32_e32 v76, v200, v76
	v_add_f32_e32 v73, 1.0, v73
	v_rcp_f32_e32 v73, v73
	v_mov_b32_dpp v77, v182 row_shr:2 row_mask:0xf bank_mask:0xf
	v_fmac_f32_e32 v76, v182, v196
	v_fmac_f32_e32 v76, v176, v77
	v_mul_f32_e32 v72, v72, v73
	v_mov_b32_dpp v73, v125 row_ror:1 row_mask:0xf bank_mask:0xf bound_ctrl:1
	v_add_f32_e32 v76, v198, v76
	v_mul_f32_e32 v72, v76, v72
	v_mov_b32_dpp v73, v181 row_shr:1 row_mask:0xf bank_mask:0xf
	v_mov_b32_dpp v76, v125 row_ror:2 row_mask:0xf bank_mask:0xf bound_ctrl:1
	v_mul_f32_e32 v73, v209, v73
	v_fmac_f32_e32 v73, v181, v207
	v_mov_b32_dpp v76, v181 row_shr:2 row_mask:0xf bank_mask:0xf
	v_fmac_f32_e32 v73, v203, v76
	v_add_f32_e32 v73, v205, v73
	v_mul_f32_e32 v76, 0xbfb8aa3b, v73
	v_exp_f32_e32 v76, v76
	v_mov_b32_dpp v77, v121 row_ror:1 row_mask:0xf bank_mask:0xf bound_ctrl:1
	v_mov_b32_dpp v81, v121 row_ror:2 row_mask:0xf bank_mask:0xf bound_ctrl:1
	v_add_f32_e32 v76, 1.0, v76
	v_mov_b32_dpp v77, v183 row_shr:1 row_mask:0xf bank_mask:0xf
	v_rcp_f32_e32 v76, v76
	v_mul_f32_e32 v77, v201, v77
	v_mov_b32_dpp v81, v183 row_shr:2 row_mask:0xf bank_mask:0xf
	v_fmac_f32_e32 v77, v183, v197
	v_fmac_f32_e32 v77, v177, v81
	v_add_f32_e32 v77, v199, v77
	v_mul_f32_e32 v73, v73, v76
	v_mul_f32_e32 v73, v77, v73
	v_cvt_pk_bf16_f32 v72, v72, v73
	s_nop 1
	v_mov_b32_dpp v73, v180 row_ror:1 row_mask:0xf bank_mask:0xf bound_ctrl:1
	v_mov_b32_dpp v76, v180 row_ror:2 row_mask:0xf bank_mask:0xf bound_ctrl:1
	v_mov_b32_dpp v77, v182 row_ror:1 row_mask:0xf bank_mask:0xf bound_ctrl:1
	v_mov_b32_dpp v73, v178 row_shr:1 row_mask:0xf bank_mask:0xf
	v_mul_f32_e32 v73, v208, v73
	v_mov_b32_dpp v76, v178 row_shr:2 row_mask:0xf bank_mask:0xf
	v_fmac_f32_e32 v73, v178, v206
	v_fmac_f32_e32 v73, v202, v76
	v_add_f32_e32 v73, v204, v73
	v_mul_f32_e32 v76, 0xbfb8aa3b, v73
	v_exp_f32_e32 v76, v76
	v_mov_b32_dpp v77, v172 row_shr:1 row_mask:0xf bank_mask:0xf
	v_mov_b32_dpp v81, v182 row_ror:2 row_mask:0xf bank_mask:0xf bound_ctrl:1
	v_mul_f32_e32 v77, v200, v77
	v_add_f32_e32 v76, 1.0, v76
	v_rcp_f32_e32 v76, v76
	v_mov_b32_dpp v81, v172 row_shr:2 row_mask:0xf bank_mask:0xf
	v_fmac_f32_e32 v77, v172, v196
	v_fmac_f32_e32 v77, v176, v81
	v_mul_f32_e32 v73, v73, v76
	v_mov_b32_dpp v76, v181 row_ror:1 row_mask:0xf bank_mask:0xf bound_ctrl:1
	v_add_f32_e32 v77, v198, v77
	v_mul_f32_e32 v73, v77, v73
	v_mov_b32_dpp v76, v179 row_shr:1 row_mask:0xf bank_mask:0xf
	v_mov_b32_dpp v77, v181 row_ror:2 row_mask:0xf bank_mask:0xf bound_ctrl:1
	v_mul_f32_e32 v76, v209, v76
	v_fmac_f32_e32 v76, v179, v207
	v_mov_b32_dpp v77, v179 row_shr:2 row_mask:0xf bank_mask:0xf
	v_fmac_f32_e32 v76, v203, v77
	v_add_f32_e32 v76, v205, v76
	v_mul_f32_e32 v77, 0xbfb8aa3b, v76
	v_exp_f32_e32 v77, v77
	v_mov_b32_dpp v81, v183 row_ror:1 row_mask:0xf bank_mask:0xf bound_ctrl:1
	v_mov_b32_dpp v108, v183 row_ror:2 row_mask:0xf bank_mask:0xf bound_ctrl:1
	v_add_f32_e32 v77, 1.0, v77
	v_mov_b32_dpp v81, v173 row_shr:1 row_mask:0xf bank_mask:0xf
	v_rcp_f32_e32 v77, v77
	v_mul_f32_e32 v81, v201, v81
	v_mov_b32_dpp v108, v173 row_shr:2 row_mask:0xf bank_mask:0xf
	v_fmac_f32_e32 v81, v173, v197
	v_fmac_f32_e32 v81, v177, v108
	v_add_f32_e32 v81, v199, v81
	v_mul_f32_e32 v76, v76, v77
	v_mul_f32_e32 v76, v81, v76
	v_cvt_pk_bf16_f32 v76, v73, v76
	v_mov_b32_dpp v73, v178 row_ror:1 row_mask:0xf bank_mask:0xf bound_ctrl:1
	v_mov_b32_dpp v77, v178 row_ror:2 row_mask:0xf bank_mask:0xf bound_ctrl:1
	v_mov_b32_dpp v81, v172 row_ror:1 row_mask:0xf bank_mask:0xf bound_ctrl:1
	v_mov_b32_dpp v73, v100 row_shr:1 row_mask:0xf bank_mask:0xf
	v_mul_f32_e32 v73, v208, v73
	v_mov_b32_dpp v77, v100 row_shr:2 row_mask:0xf bank_mask:0xf
	v_fmac_f32_e32 v73, v100, v206
	v_fmac_f32_e32 v73, v202, v77
	v_add_f32_e32 v73, v204, v73
	v_mul_f32_e32 v77, 0xbfb8aa3b, v73
	v_exp_f32_e32 v77, v77
	v_mov_b32_dpp v81, v96 row_shr:1 row_mask:0xf bank_mask:0xf
	v_mov_b32_dpp v108, v172 row_ror:2 row_mask:0xf bank_mask:0xf bound_ctrl:1
	v_mul_f32_e32 v81, v200, v81
	v_add_f32_e32 v77, 1.0, v77
	v_rcp_f32_e32 v77, v77
	v_mov_b32_dpp v108, v96 row_shr:2 row_mask:0xf bank_mask:0xf
	v_fmac_f32_e32 v81, v96, v196
	v_fmac_f32_e32 v81, v176, v108
	v_mul_f32_e32 v73, v73, v77
	v_mov_b32_dpp v77, v179 row_ror:1 row_mask:0xf bank_mask:0xf bound_ctrl:1
	v_add_f32_e32 v81, v198, v81
	v_mul_f32_e32 v73, v81, v73
	v_mov_b32_dpp v77, v101 row_shr:1 row_mask:0xf bank_mask:0xf
	v_mov_b32_dpp v81, v179 row_ror:2 row_mask:0xf bank_mask:0xf bound_ctrl:1
	v_mul_f32_e32 v77, v209, v77
	v_fmac_f32_e32 v77, v101, v207
	v_mov_b32_dpp v81, v101 row_shr:2 row_mask:0xf bank_mask:0xf
	v_fmac_f32_e32 v77, v203, v81
	v_add_f32_e32 v77, v205, v77
	v_mul_f32_e32 v81, 0xbfb8aa3b, v77
	v_exp_f32_e32 v81, v81
	v_mov_b32_dpp v108, v173 row_ror:1 row_mask:0xf bank_mask:0xf bound_ctrl:1
	v_mov_b32_dpp v109, v173 row_ror:2 row_mask:0xf bank_mask:0xf bound_ctrl:1
	v_add_f32_e32 v81, 1.0, v81
	v_mov_b32_dpp v108, v97 row_shr:1 row_mask:0xf bank_mask:0xf
	v_rcp_f32_e32 v81, v81
	v_mul_f32_e32 v108, v201, v108
	v_mov_b32_dpp v109, v97 row_shr:2 row_mask:0xf bank_mask:0xf
	v_fmac_f32_e32 v108, v97, v197
	v_fmac_f32_e32 v108, v177, v109
	v_add_f32_e32 v108, v199, v108
	v_mul_f32_e32 v77, v77, v81
	v_mul_f32_e32 v77, v108, v77
	v_cvt_pk_bf16_f32 v108, v73, v77
	v_lshlrev_b64 v[172:173], 2, v[174:175]
	v_lshl_add_u64 v[174:175], s[16:17], 0, v[172:173]
	v_lshl_add_u64 v[178:179], s[8:9], 0, v[172:173]
	v_lshl_add_u64 v[180:181], s[24:25], 0, v[172:173]
	global_load_dwordx2 v[186:187], v[174:175], off
	global_load_dwordx2 v[192:193], v[178:179], off
	global_load_dwordx2 v[190:191], v[180:181], off
	v_lshl_add_u64 v[174:175], s[18:19], 0, v[172:173]
	global_load_dwordx2 v[188:189], v[174:175], off
	v_lshl_add_u64 v[174:175], s[26:27], 0, v[172:173]
	v_lshl_add_u64 v[180:181], s[28:29], 0, v[172:173]
	v_lshl_add_u64 v[182:183], s[30:31], 0, v[172:173]
	global_load_dwordx2 v[178:179], v[174:175], off
	global_load_dwordx2 v[184:185], v[180:181], off
	s_nop 0
	global_load_dwordx2 v[180:181], v[182:183], off
	v_lshl_add_u64 v[172:173], s[42:43], 0, v[172:173]
	global_load_dwordx2 v[182:183], v[172:173], off
	v_mul_f32_dpp v77, v92, v208 row_shr:1 row_mask:0xf bank_mask:0xf bound_ctrl:1
	v_mov_b32_dpp v73, v92 row_shr:2 row_mask:0xf bank_mask:0xf bound_ctrl:1
	v_fmac_f32_e32 v77, v92, v206
	v_fmac_f32_e32 v77, v202, v73
	v_add_f32_e32 v73, v204, v77
	v_mul_f32_e32 v77, 0xbfb8aa3b, v73
	v_exp_f32_e32 v77, v77
	v_mul_f32_dpp v109, v88, v200 row_shr:1 row_mask:0xf bank_mask:0xf bound_ctrl:1
	v_mov_b32_dpp v81, v88 row_shr:2 row_mask:0xf bank_mask:0xf bound_ctrl:1
	v_fmac_f32_e32 v109, v88, v196
	v_add_f32_e32 v77, 1.0, v77
	v_rcp_f32_e32 v77, v77
	v_fmac_f32_e32 v109, v176, v81
	v_add_f32_e32 v81, v198, v109
	v_mul_f32_dpp v149, v89, v201 row_shr:1 row_mask:0xf bank_mask:0xf bound_ctrl:1
	v_mul_f32_dpp v109, v93, v209 row_shr:1 row_mask:0xf bank_mask:0xf bound_ctrl:1
	v_mul_f32_e32 v73, v73, v77
	v_mov_b32_dpp v77, v93 row_shr:2 row_mask:0xf bank_mask:0xf bound_ctrl:1
	v_fmac_f32_e32 v109, v93, v207
	v_fmac_f32_e32 v109, v203, v77
	v_add_f32_e32 v77, v205, v109
	v_mul_f32_e32 v109, 0xbfb8aa3b, v77
	v_exp_f32_e32 v109, v109
	v_mul_f32_e32 v73, v81, v73
	v_mov_b32_dpp v81, v89 row_shr:2 row_mask:0xf bank_mask:0xf bound_ctrl:1
	v_fmac_f32_e32 v149, v89, v197
	v_add_f32_e32 v109, 1.0, v109
	v_rcp_f32_e32 v109, v109
	v_fmac_f32_e32 v149, v177, v81
	v_add_f32_e32 v81, v199, v149
	v_mul_f32_e32 v77, v77, v109
	v_mul_f32_e32 v77, v81, v77
	v_cvt_pk_bf16_f32 v194, v73, v77
	v_mov_b32_dpp v73, v92 row_ror:1 row_mask:0xf bank_mask:0xf bound_ctrl:1
	s_nop 0
	v_mov_b32_dpp v77, v92 row_ror:2 row_mask:0xf bank_mask:0xf bound_ctrl:1
	v_mov_b32_dpp v81, v88 row_ror:1 row_mask:0xf bank_mask:0xf bound_ctrl:1
	v_mov_b32_dpp v73, v116 row_shr:1 row_mask:0xf bank_mask:0xf
	v_mul_f32_e32 v73, v208, v73
	v_mov_b32_dpp v77, v116 row_shr:2 row_mask:0xf bank_mask:0xf
	v_fmac_f32_e32 v73, v206, v116
	v_fmac_f32_e32 v73, v202, v77
	v_add_f32_e32 v73, v204, v73
	v_mul_f32_e32 v77, 0xbfb8aa3b, v73
	v_exp_f32_e32 v77, v77
	v_mov_b32_dpp v81, v112 row_shr:1 row_mask:0xf bank_mask:0xf
	v_mov_b32_dpp v109, v88 row_ror:2 row_mask:0xf bank_mask:0xf bound_ctrl:1
	v_mul_f32_e32 v81, v200, v81
	v_add_f32_e32 v77, 1.0, v77
	v_rcp_f32_e32 v77, v77
	v_mov_b32_dpp v109, v112 row_shr:2 row_mask:0xf bank_mask:0xf
	v_fmac_f32_e32 v81, v112, v196
	v_fmac_f32_e32 v81, v176, v109
	v_mul_f32_e32 v73, v73, v77
	v_mov_b32_dpp v77, v93 row_ror:1 row_mask:0xf bank_mask:0xf bound_ctrl:1
	v_add_f32_e32 v81, v198, v81
	v_mul_f32_e32 v73, v81, v73
	v_mov_b32_dpp v77, v117 row_shr:1 row_mask:0xf bank_mask:0xf
	v_mov_b32_dpp v81, v93 row_ror:2 row_mask:0xf bank_mask:0xf bound_ctrl:1
	v_mul_f32_e32 v77, v209, v77
	v_fmac_f32_e32 v77, v207, v117
	v_mov_b32_dpp v81, v117 row_shr:2 row_mask:0xf bank_mask:0xf
	v_fmac_f32_e32 v77, v203, v81
	v_add_f32_e32 v77, v205, v77
	v_mul_f32_e32 v81, 0xbfb8aa3b, v77
	v_exp_f32_e32 v81, v81
	v_mov_b32_dpp v109, v89 row_ror:1 row_mask:0xf bank_mask:0xf bound_ctrl:1
	v_mov_b32_dpp v149, v89 row_ror:2 row_mask:0xf bank_mask:0xf bound_ctrl:1
	v_add_f32_e32 v81, 1.0, v81
	v_mov_b32_dpp v109, v113 row_shr:1 row_mask:0xf bank_mask:0xf
	v_rcp_f32_e32 v81, v81
	v_mul_f32_e32 v109, v201, v109
	v_mov_b32_dpp v149, v113 row_shr:2 row_mask:0xf bank_mask:0xf
	v_fmac_f32_e32 v109, v113, v197
	v_fmac_f32_e32 v109, v177, v149
	v_add_f32_e32 v109, v199, v109
	v_mul_f32_e32 v77, v77, v81
	v_mul_f32_e32 v77, v109, v77
	v_cvt_pk_bf16_f32 v172, v73, v77
	v_mov_b32_dpp v73, v116 row_ror:1 row_mask:0xf bank_mask:0xf bound_ctrl:1
	s_nop 0
	v_mov_b32_dpp v77, v116 row_ror:2 row_mask:0xf bank_mask:0xf bound_ctrl:1
	v_mov_b32_dpp v81, v112 row_ror:1 row_mask:0xf bank_mask:0xf bound_ctrl:1
	v_mov_b32_dpp v73, v104 row_shr:1 row_mask:0xf bank_mask:0xf
	v_mul_f32_e32 v73, v208, v73
	v_mov_b32_dpp v77, v104 row_shr:2 row_mask:0xf bank_mask:0xf
	v_fmac_f32_e32 v73, v206, v104
	v_fmac_f32_e32 v73, v202, v77
	v_add_f32_e32 v73, v204, v73
	v_mul_f32_e32 v77, 0xbfb8aa3b, v73
	v_exp_f32_e32 v77, v77
	v_mov_b32_dpp v81, v84 row_shr:1 row_mask:0xf bank_mask:0xf
	v_mov_b32_dpp v109, v112 row_ror:2 row_mask:0xf bank_mask:0xf bound_ctrl:1
	v_mul_f32_e32 v81, v200, v81
	v_add_f32_e32 v77, 1.0, v77
	v_rcp_f32_e32 v77, v77
	v_mov_b32_dpp v109, v84 row_shr:2 row_mask:0xf bank_mask:0xf
	v_fmac_f32_e32 v81, v84, v196
	v_fmac_f32_e32 v81, v176, v109
	v_mul_f32_e32 v73, v73, v77
	v_mov_b32_dpp v77, v117 row_ror:1 row_mask:0xf bank_mask:0xf bound_ctrl:1
	v_add_f32_e32 v81, v198, v81
	v_mul_f32_e32 v73, v81, v73
	v_mov_b32_dpp v77, v105 row_shr:1 row_mask:0xf bank_mask:0xf
	v_mov_b32_dpp v81, v117 row_ror:2 row_mask:0xf bank_mask:0xf bound_ctrl:1
	v_mul_f32_e32 v77, v209, v77
	v_fmac_f32_e32 v77, v207, v105
	v_mov_b32_dpp v81, v105 row_shr:2 row_mask:0xf bank_mask:0xf
	v_fmac_f32_e32 v77, v203, v81
	v_add_f32_e32 v77, v205, v77
	v_mul_f32_e32 v81, 0xbfb8aa3b, v77
	v_exp_f32_e32 v81, v81
	v_mov_b32_dpp v109, v113 row_ror:1 row_mask:0xf bank_mask:0xf bound_ctrl:1
	v_mov_b32_dpp v112, v113 row_ror:2 row_mask:0xf bank_mask:0xf bound_ctrl:1
	v_add_f32_e32 v81, 1.0, v81
	v_mov_b32_dpp v109, v85 row_shr:1 row_mask:0xf bank_mask:0xf
	v_rcp_f32_e32 v81, v81
	v_mul_f32_e32 v109, v201, v109
	v_mov_b32_dpp v112, v85 row_shr:2 row_mask:0xf bank_mask:0xf
	v_fmac_f32_e32 v109, v85, v197
	v_fmac_f32_e32 v109, v177, v112
	v_add_f32_e32 v109, v199, v109
	v_mul_f32_e32 v77, v77, v81
	v_mul_f32_e32 v77, v109, v77
	v_cvt_pk_bf16_f32 v174, v73, v77
	v_mov_b32_dpp v73, v104 row_ror:1 row_mask:0xf bank_mask:0xf bound_ctrl:1
	s_nop 0
	v_mov_b32_dpp v77, v104 row_ror:2 row_mask:0xf bank_mask:0xf bound_ctrl:1
	v_mov_b32_dpp v81, v84 row_ror:1 row_mask:0xf bank_mask:0xf bound_ctrl:1
	v_mov_b32_dpp v73, v68 row_shr:1 row_mask:0xf bank_mask:0xf
	v_mul_f32_e32 v73, v208, v73
	v_mov_b32_dpp v77, v68 row_shr:2 row_mask:0xf bank_mask:0xf
	v_fmac_f32_e32 v73, v206, v68
	v_fmac_f32_e32 v73, v202, v77
	v_add_f32_e32 v73, v204, v73
	v_mul_f32_e32 v77, 0xbfb8aa3b, v73
	v_exp_f32_e32 v77, v77
	v_mov_b32_dpp v81, v64 row_shr:1 row_mask:0xf bank_mask:0xf
	v_mov_b32_dpp v84, v84 row_ror:2 row_mask:0xf bank_mask:0xf bound_ctrl:1
	v_mul_f32_e32 v81, v200, v81
	v_add_f32_e32 v77, 1.0, v77
	v_rcp_f32_e32 v77, v77
	v_mov_b32_dpp v84, v64 row_shr:2 row_mask:0xf bank_mask:0xf
	v_fmac_f32_e32 v81, v196, v64
	v_fmac_f32_e32 v81, v176, v84
	v_mul_f32_e32 v73, v73, v77
	v_mov_b32_dpp v77, v105 row_ror:1 row_mask:0xf bank_mask:0xf bound_ctrl:1
	v_add_f32_e32 v81, v198, v81
	v_mul_f32_e32 v73, v81, v73
	v_mov_b32_dpp v77, v69 row_shr:1 row_mask:0xf bank_mask:0xf
	v_mov_b32_dpp v81, v105 row_ror:2 row_mask:0xf bank_mask:0xf bound_ctrl:1
	v_mul_f32_e32 v77, v209, v77
	v_fmac_f32_e32 v77, v207, v69
	v_mov_b32_dpp v81, v69 row_shr:2 row_mask:0xf bank_mask:0xf
	v_fmac_f32_e32 v77, v203, v81
	v_add_f32_e32 v77, v205, v77
	v_mul_f32_e32 v81, 0xbfb8aa3b, v77
	v_exp_f32_e32 v81, v81
	v_mov_b32_dpp v84, v85 row_ror:1 row_mask:0xf bank_mask:0xf bound_ctrl:1
	v_mov_b32_dpp v85, v85 row_ror:2 row_mask:0xf bank_mask:0xf bound_ctrl:1
	v_add_f32_e32 v81, 1.0, v81
	v_mov_b32_dpp v84, v65 row_shr:1 row_mask:0xf bank_mask:0xf
	v_rcp_f32_e32 v81, v81
	v_mul_f32_e32 v84, v201, v84
	v_mov_b32_dpp v85, v65 row_shr:2 row_mask:0xf bank_mask:0xf
	v_fmac_f32_e32 v84, v197, v65
	v_fmac_f32_e32 v84, v177, v85
	v_add_f32_e32 v84, v199, v84
	v_mul_f32_e32 v77, v77, v81
	v_mul_f32_e32 v77, v84, v77
	v_cvt_pk_bf16_f32 v176, v73, v77
	s_waitcnt vmcnt(6)
	s_nop 0
	v_mul_f32_dpp v77, v126, v192 row_shr:1 row_mask:0xf bank_mask:0xf bound_ctrl:1
	v_mov_b32_dpp v73, v126 row_shr:2 row_mask:0xf bank_mask:0xf bound_ctrl:1
	s_waitcnt vmcnt(5)
	v_fmac_f32_e32 v77, v126, v190
	v_fmac_f32_e32 v77, v186, v73
	s_waitcnt vmcnt(4)
	v_add_f32_e32 v73, v188, v77
	v_mul_f32_e32 v77, 0xbfb8aa3b, v73
	v_exp_f32_e32 v77, v77
	s_waitcnt vmcnt(2)
	v_mul_f32_dpp v84, v122, v184 row_shr:1 row_mask:0xf bank_mask:0xf bound_ctrl:1
	v_mov_b32_dpp v81, v122 row_shr:2 row_mask:0xf bank_mask:0xf bound_ctrl:1
	s_waitcnt vmcnt(1)
	v_fmac_f32_e32 v84, v122, v180
	v_add_f32_e32 v77, 1.0, v77
	v_rcp_f32_e32 v77, v77
	v_fmac_f32_e32 v84, v178, v81
	s_waitcnt vmcnt(0)
	v_add_f32_e32 v81, v182, v84
	v_mul_f32_dpp v85, v123, v185 row_shr:1 row_mask:0xf bank_mask:0xf bound_ctrl:1
	v_mul_f32_dpp v84, v127, v193 row_shr:1 row_mask:0xf bank_mask:0xf bound_ctrl:1
	v_mul_f32_e32 v73, v73, v77
	v_mov_b32_dpp v77, v127 row_shr:2 row_mask:0xf bank_mask:0xf bound_ctrl:1
	v_fmac_f32_e32 v84, v127, v191
	v_fmac_f32_e32 v84, v187, v77
	v_add_f32_e32 v77, v189, v84
	v_mul_f32_e32 v84, 0xbfb8aa3b, v77
	v_exp_f32_e32 v84, v84
	v_mul_f32_e32 v73, v81, v73
	v_mov_b32_dpp v81, v123 row_shr:2 row_mask:0xf bank_mask:0xf bound_ctrl:1
	v_fmac_f32_e32 v85, v123, v181
	v_add_f32_e32 v84, 1.0, v84
	v_rcp_f32_e32 v84, v84
	v_fmac_f32_e32 v85, v179, v81
	v_add_f32_e32 v81, v183, v85
	v_mul_f32_e32 v77, v77, v84
	v_mul_f32_e32 v77, v81, v77
	v_cvt_pk_bf16_f32 v81, v73, v77
	s_and_saveexec_b64 s[56:57], s[2:3]
	s_xor_b64 s[56:57], exec, s[56:57]
	s_cbranch_execz .LBB0_1214
	v_mov_b64_e32 v[84:85], s[48:49]
	v_mad_i64_i32 v[84:85], s[58:59], v156, s85, v[84:85]
	v_lshl_add_u64 v[84:85], v[146:147], 1, v[84:85]
	v_mov_b32_e32 v251, v80
	v_mov_b32_e32 v252, v81
